# stack1 + nt on the one-time epilogue loads of the GEMM phases
# baseline (speedup 1.0000x reference)
.LBB0_696:
	s_lshl_b32 s4, s78, 3
	s_and_b32 s4, s4, -16
	s_ashr_i32 s5, s4, 31
	s_lshl_b64 s[4:5], s[4:5], 2
	s_add_u32 s4, s60, s4
	s_addc_u32 s5, s61, s5
	v_ashrrev_i32_e32 v149, 31, v148
	v_lshl_add_u64 v[150:151], v[150:151], 1, s[0:1]
	v_lshlrev_b64 v[130:131], 12, v[146:147]
	v_lshl_add_u64 v[154:155], v[150:151], 0, v[130:131]
	v_lshl_add_u64 v[152:153], v[148:149], 4, s[4:5]
	v_lshlrev_b64 v[130:131], 8, v[146:147]
	v_lshl_add_u64 v[130:131], v[152:153], 0, v[130:131]
	global_load_dwordx4 v[164:167], v[154:155], off nt
	global_load_dwordx4 v[168:171], v[130:131], off nt
	v_add_u32_e32 v130, 16, v146
	v_ashrrev_i32_e32 v131, 31, v130
	v_lshlrev_b64 v[132:133], 8, v[130:131]
	v_lshl_add_u64 v[132:133], v[152:153], 0, v[132:133]
	global_load_dwordx4 v[172:175], v[132:133], off nt
	global_load_dwordx4 v[176:179], v[154:155], off offset:256 nt
	v_mul_f32_e32 v132, 0xbfb8aa3b, v126
	v_mul_f32_e32 v135, 0xbfb8aa3b, v127
	v_mul_f32_e32 v133, 0xbfb8aa3b, v122
	v_mul_f32_e32 v156, 0xbfb8aa3b, v129
	v_mul_f32_e32 v157, 0xbfb8aa3b, v125
	v_exp_f32_e32 v163, v132
	v_exp_f32_e32 v135, v135
	v_lshlrev_b64 v[130:131], 12, v[130:131]
	v_exp_f32_e32 v184, v133
	v_exp_f32_e32 v185, v156
	v_exp_f32_e32 v186, v157
	v_lshl_add_u64 v[156:157], v[150:151], 0, v[130:131]
	global_load_dwordx4 v[180:183], v[156:157], off nt
	global_load_dwordx4 v[130:133], v[156:157], off offset:256 nt
	v_add_f32_e32 v163, 1.0, v163
	v_add_f32_e32 v135, 1.0, v135
	v_add_f32_e32 v187, 1.0, v184
	v_add_f32_e32 v189, 1.0, v185
	v_rcp_f32_e32 v184, v163
	v_rcp_f32_e32 v185, v135
	v_mul_f32_e32 v137, 0xbfb8aa3b, v123
	v_mul_f32_e32 v147, 0xbfb8aa3b, v124
	v_exp_f32_e32 v137, v137
	v_pk_mul_f32 v[184:185], v[126:127], v[184:185]
	v_exp_f32_e32 v147, v147
	v_mov_b64_e32 v[148:149], s[38:39]
	v_mul_f32_e32 v139, 0xbfb8aa3b, v128
	v_exp_f32_e32 v139, v139
	v_add_f32_e32 v137, 1.0, v137
	v_add_f32_e32 v147, 1.0, v147
	v_add_f32_e32 v191, 1.0, v186
	v_rcp_f32_e32 v186, v187
	v_rcp_f32_e32 v187, v137
	v_rcp_f32_e32 v190, v147
	v_rcp_f32_e32 v191, v191
	v_add_f32_e32 v139, 1.0, v139
	v_rcp_f32_e32 v188, v139
	v_rcp_f32_e32 v189, v189
	v_pk_mul_f32 v[124:125], v[124:125], v[190:191]
	v_pk_mul_f32 v[122:123], v[122:123], v[186:187]
	v_pk_mul_f32 v[128:129], v[128:129], v[188:189]
	s_waitcnt vmcnt(0)
	v_lshlrev_b32_e32 v192, 16, v166
	v_mov_b32_e32 v126, v169
	v_mov_b32_e32 v127, v170
	v_mov_b32_e32 v169, v171
	v_pk_add_f32 v[126:127], v[126:127], v[168:169]
	v_and_b32_e32 v193, 0xffff0000, v166
	v_mov_b32_e32 v170, v173
	v_mov_b32_e32 v171, v174
	v_mov_b32_e32 v173, v175
	v_pk_add_f32 v[168:169], v[170:171], v[172:173]
	v_pk_add_f32 v[126:127], v[126:127], v[126:127] op_sel:[0,1] op_sel_hi:[1,0]
	v_pk_add_f32 v[168:169], v[168:169], v[168:169] op_sel:[0,1] op_sel_hi:[1,0]
	v_mov_b32_e32 v127, v126
	v_mov_b32_e32 v135, v168
	s_nop 0
	v_permlane16_swap_b32_e32 v126, v127
	v_permlane16_swap_b32_e32 v168, v135
	v_add_f32_e32 v127, v126, v127
	v_add_f32_e32 v126, v168, v135
	v_mov_b32_e32 v169, v127
	v_mov_b32_e32 v168, v126
	s_nop 0
	v_permlane32_swap_b32_e32 v127, v169
	v_permlane32_swap_b32_e32 v126, v168
	v_pk_add_f32 v[126:127], v[126:127], v[168:169]
	v_lshlrev_b32_e32 v166, 16, v167
	v_pk_fma_f32 v[126:127], v[126:127], s[36:37], v[148:149] op_sel_hi:[1,0,0]
	v_and_b32_e32 v167, 0xffff0000, v167
	v_mul_f32_e32 v135, 0x4b800000, v127
	v_cmp_gt_f32_e32 vcc, s76, v127
	v_pk_mul_f32 v[122:123], v[122:123], v[192:193]
	v_pk_mul_f32 v[124:125], v[124:125], v[166:167]
	v_cndmask_b32_e32 v127, v127, v135, vcc
	v_rsq_f32_e32 v127, v127
	v_lshlrev_b32_e32 v188, 16, v164
	v_and_b32_e32 v189, 0xffff0000, v164
	v_lshlrev_b32_e32 v164, 16, v165
	v_mul_f32_e32 v135, 0x45800000, v127
	v_cndmask_b32_e32 v168, v127, v135, vcc
	v_and_b32_e32 v165, 0xffff0000, v165
	v_pk_mul_f32 v[166:167], v[124:125], v[168:169] op_sel_hi:[1,0]
	v_pk_mul_f32 v[124:125], v[122:123], v[168:169] op_sel_hi:[1,0]
	v_pk_mul_f32 v[128:129], v[128:129], v[164:165]
	v_cvt_pk_bf16_f32 v124, v124, v125
	v_mul_f32_e32 v125, 0xbfb8aa3b, v118
	v_pk_mul_f32 v[128:129], v[128:129], v[168:169] op_sel_hi:[1,0]
	v_exp_f32_e32 v127, v125
	v_mul_f32_e32 v125, 0xbfb8aa3b, v114
	v_cvt_pk_bf16_f32 v123, v128, v129
	v_exp_f32_e32 v129, v125
	v_add_f32_e32 v127, 1.0, v127
	v_mul_f32_e32 v137, 0x4b800000, v126
	v_cmp_gt_f32_e64 s[4:5], s76, v126
	v_rcp_f32_e32 v128, v127
	v_add_f32_e32 v127, 1.0, v129
	v_mul_f32_e32 v129, 0xbfb8aa3b, v119
	v_cndmask_b32_e64 v126, v126, v137, s[4:5]
	v_exp_f32_e32 v129, v129
	v_mul_f32_e32 v135, 0xbfb8aa3b, v115
	v_rsq_f32_e32 v126, v126
	v_exp_f32_e32 v135, v135
	v_pk_mul_f32 v[170:171], v[184:185], v[188:189]
	v_cvt_pk_bf16_f32 v125, v166, v167
	v_pk_mul_f32 v[164:165], v[170:171], v[168:169] op_sel_hi:[1,0]
	v_mul_f32_e32 v137, 0x45800000, v126
	v_cvt_pk_bf16_f32 v122, v164, v165
	v_rcp_f32_e32 v164, v127
	v_add_f32_e32 v127, 1.0, v129
	v_rcp_f32_e32 v129, v127
	v_add_f32_e32 v127, 1.0, v135
	v_mul_f32_e32 v135, 0xbfb8aa3b, v120
	v_cndmask_b32_e64 v126, v126, v137, s[4:5]
	v_exp_f32_e32 v135, v135
	v_mul_f32_e32 v137, 0xbfb8aa3b, v116
	v_exp_f32_e32 v137, v137
	v_rcp_f32_e32 v165, v127
	v_add_f32_e32 v127, 1.0, v135
	v_mul_f32_e32 v135, 0xbfb8aa3b, v121
	v_rcp_f32_e32 v166, v127
	v_add_f32_e32 v127, 1.0, v137
	v_exp_f32_e32 v135, v135
	v_mul_f32_e32 v137, 0xbfb8aa3b, v117
	v_exp_f32_e32 v137, v137
	v_rcp_f32_e32 v170, v127
	v_add_f32_e32 v127, 1.0, v135
	v_rcp_f32_e32 v167, v127
	v_add_f32_e32 v127, 1.0, v137
	v_rcp_f32_e32 v171, v127
	v_lshlrev_b32_e32 v172, 16, v176
	v_and_b32_e32 v173, 0xffff0000, v176
	v_lshlrev_b32_e32 v174, 16, v177
	v_and_b32_e32 v175, 0xffff0000, v177
	v_lshlrev_b32_e32 v176, 16, v178
	v_and_b32_e32 v177, 0xffff0000, v178
	v_lshlrev_b32_e32 v178, 16, v179
	v_and_b32_e32 v179, 0xffff0000, v179
	v_pk_mul_f32 v[116:117], v[116:117], v[170:171]
	v_pk_mul_f32 v[114:115], v[114:115], v[164:165]
	v_pk_mul_f32 v[118:119], v[118:119], v[128:129]
	v_pk_mul_f32 v[114:115], v[114:115], v[176:177]
	v_pk_mul_f32 v[116:117], v[116:117], v[178:179]
	v_pk_mul_f32 v[120:121], v[120:121], v[166:167]
	v_pk_mul_f32 v[118:119], v[118:119], v[172:173]
	v_pk_mul_f32 v[128:129], v[116:117], v[168:169] op_sel_hi:[1,0]
	v_pk_mul_f32 v[116:117], v[114:115], v[168:169] op_sel_hi:[1,0]
	v_pk_mul_f32 v[120:121], v[120:121], v[174:175]
	v_pk_mul_f32 v[118:119], v[118:119], v[168:169] op_sel_hi:[1,0]
	v_cvt_pk_bf16_f32 v116, v116, v117
	v_mul_f32_e32 v117, 0xbfb8aa3b, v110
	v_pk_mul_f32 v[120:121], v[120:121], v[168:169] op_sel_hi:[1,0]
	v_cvt_pk_bf16_f32 v114, v118, v119
	v_exp_f32_e32 v118, v117
	v_mul_f32_e32 v117, 0xbfb8aa3b, v106
	v_cvt_pk_bf16_f32 v115, v120, v121
	v_exp_f32_e32 v119, v117
	v_mul_f32_e32 v120, 0xbfb8aa3b, v111
	v_mul_f32_e32 v121, 0xbfb8aa3b, v107
	v_exp_f32_e32 v120, v120
	v_exp_f32_e32 v121, v121
	v_add_f32_e32 v119, 1.0, v119
	v_cvt_pk_bf16_f32 v117, v128, v129
	v_rcp_f32_e32 v128, v119
	v_add_f32_e32 v119, 1.0, v120
	v_add_f32_e32 v120, 1.0, v121
	v_mul_f32_e32 v121, 0xbfb8aa3b, v112
	v_mul_f32_e32 v127, 0xbfb8aa3b, v108
	v_exp_f32_e32 v121, v121
	v_exp_f32_e32 v127, v127
	v_rcp_f32_e32 v129, v120
	v_add_f32_e32 v118, 1.0, v118
	v_add_f32_e32 v120, 1.0, v121
	v_add_f32_e32 v121, 1.0, v127
	v_mul_f32_e32 v127, 0xbfb8aa3b, v113
	v_exp_f32_e32 v127, v127
	v_rcp_f32_e32 v164, v121
	v_rcp_f32_e32 v118, v118
	v_rcp_f32_e32 v119, v119
	v_add_f32_e32 v121, 1.0, v127
	v_rcp_f32_e32 v120, v120
	v_rcp_f32_e32 v121, v121
	v_add_u32_e32 v174, 48, v146
	v_add_u32_e32 v176, 32, v146
	v_lshlrev_b32_e32 v166, 16, v180
	v_and_b32_e32 v167, 0xffff0000, v180
	v_lshlrev_b32_e32 v168, 16, v181
	v_and_b32_e32 v169, 0xffff0000, v181
	v_pk_mul_f32 v[112:113], v[112:113], v[120:121]
	v_pk_mul_f32 v[110:111], v[110:111], v[118:119]
	v_ashrrev_i32_e32 v175, 31, v174
	v_ashrrev_i32_e32 v177, 31, v176
	v_pk_mul_f32 v[166:167], v[110:111], v[166:167]
	v_pk_mul_f32 v[168:169], v[112:113], v[168:169]
	v_lshlrev_b64 v[110:111], 8, v[174:175]
	v_lshlrev_b64 v[112:113], 8, v[176:177]
	v_lshl_add_u64 v[110:111], v[152:153], 0, v[110:111]
	v_lshl_add_u64 v[118:119], v[152:153], 0, v[112:113]
	global_load_dwordx4 v[110:113], v[110:111], off nt
	s_nop 0
	global_load_dwordx4 v[118:121], v[118:119], off nt
	v_mul_f32_e32 v135, 0xbfb8aa3b, v109
	v_exp_f32_e32 v135, v135
	v_lshlrev_b32_e32 v170, 16, v182
	v_and_b32_e32 v171, 0xffff0000, v182
	v_lshlrev_b32_e32 v172, 16, v183
	v_add_f32_e32 v127, 1.0, v135
	v_rcp_f32_e32 v165, v127
	v_and_b32_e32 v173, 0xffff0000, v183
	v_pk_mul_f32 v[106:107], v[106:107], v[128:129]
	v_pk_mul_f32 v[166:167], v[166:167], v[126:127] op_sel_hi:[1,0]
	v_pk_mul_f32 v[108:109], v[108:109], v[164:165]
	v_pk_mul_f32 v[106:107], v[106:107], v[170:171]
	v_pk_mul_f32 v[108:109], v[108:109], v[172:173]
	v_pk_mul_f32 v[106:107], v[106:107], v[126:127] op_sel_hi:[1,0]
	v_pk_mul_f32 v[108:109], v[108:109], v[126:127] op_sel_hi:[1,0]
	v_cvt_pk_bf16_f32 v164, v166, v167
	v_cvt_pk_bf16_f32 v166, v106, v107
	v_mul_f32_e32 v107, 0xbfb8aa3b, v98
	v_cvt_pk_bf16_f32 v167, v108, v109
	v_mul_f32_e32 v108, 0xbfb8aa3b, v103
	v_exp_f32_e32 v107, v107
	v_exp_f32_e32 v109, v108
	v_mul_f32_e32 v108, 0xbfb8aa3b, v99
	v_pk_mul_f32 v[168:169], v[168:169], v[126:127] op_sel_hi:[1,0]
	v_exp_f32_e32 v127, v108
	v_add_f32_e32 v107, 1.0, v107
	v_rcp_f32_e32 v108, v107
	v_add_f32_e32 v107, 1.0, v109
	v_add_f32_e32 v109, 1.0, v127
	v_mul_f32_e32 v127, 0xbfb8aa3b, v104
	v_exp_f32_e32 v127, v127
	v_mul_f32_e32 v128, 0xbfb8aa3b, v100
	v_exp_f32_e32 v129, v128
	v_mul_f32_e32 v106, 0xbfb8aa3b, v102
	v_add_f32_e32 v127, 1.0, v127
	v_rcp_f32_e32 v128, v127
	v_add_f32_e32 v127, 1.0, v129
	v_mul_f32_e32 v129, 0xbfb8aa3b, v105
	v_exp_f32_e32 v129, v129
	v_mul_f32_e32 v135, 0xbfb8aa3b, v101
	v_exp_f32_e32 v106, v106
	v_exp_f32_e32 v135, v135
	v_rcp_f32_e32 v109, v109
	v_cvt_pk_bf16_f32 v165, v168, v169
	v_rcp_f32_e32 v168, v127
	v_add_f32_e32 v127, 1.0, v129
	v_add_f32_e32 v106, 1.0, v106
	v_rcp_f32_e32 v129, v127
	v_add_f32_e32 v127, 1.0, v135
	v_rcp_f32_e32 v106, v106
	v_rcp_f32_e32 v107, v107
	v_rcp_f32_e32 v169, v127
	v_lshlrev_b32_e32 v172, 16, v132
	v_and_b32_e32 v173, 0xffff0000, v132
	v_pk_mul_f32 v[98:99], v[98:99], v[108:109]
	v_pk_mul_f32 v[104:105], v[104:105], v[128:129]
	v_pk_mul_f32 v[98:99], v[98:99], v[172:173]
	v_lshlrev_b32_e32 v170, 16, v130
	v_pk_mul_f32 v[98:99], v[98:99], v[126:127] op_sel_hi:[1,0]
	v_and_b32_e32 v171, 0xffff0000, v130
	v_cvt_pk_bf16_f32 v128, v98, v99
	v_lshlrev_b64 v[98:99], 12, v[176:177]
	v_lshlrev_b32_e32 v130, 16, v131
	v_and_b32_e32 v131, 0xffff0000, v131
	v_lshlrev_b32_e32 v132, 16, v133
	v_and_b32_e32 v133, 0xffff0000, v133
	v_pk_mul_f32 v[102:103], v[102:103], v[106:107]
	v_pk_mul_f32 v[100:101], v[100:101], v[168:169]
	v_lshl_add_u64 v[108:109], v[150:151], 0, v[98:99]
	v_pk_mul_f32 v[102:103], v[102:103], v[170:171]
	v_pk_mul_f32 v[104:105], v[104:105], v[130:131]
	v_pk_mul_f32 v[100:101], v[100:101], v[132:133]
	global_load_dwordx4 v[130:133], v[108:109], off offset:256 nt
	global_load_dwordx4 v[168:171], v[108:109], off nt
	v_lshlrev_b64 v[98:99], 12, v[174:175]
	v_pk_mul_f32 v[104:105], v[104:105], v[126:127] op_sel_hi:[1,0]
	v_pk_mul_f32 v[102:103], v[102:103], v[126:127] op_sel_hi:[1,0]
	v_pk_mul_f32 v[100:101], v[100:101], v[126:127] op_sel_hi:[1,0]
	v_lshl_add_u64 v[106:107], v[150:151], 0, v[98:99]
	v_cvt_pk_bf16_f32 v126, v102, v103
	v_cvt_pk_bf16_f32 v127, v104, v105
	v_cvt_pk_bf16_f32 v129, v100, v101
	global_load_dwordx4 v[98:101], v[106:107], off offset:256 nt
	global_load_dwordx4 v[102:105], v[106:107], off nt
	s_nop 0
	global_store_dwordx4 v[154:155], v[122:125], off nt
	global_store_dwordx4 v[154:155], v[114:117], off offset:256 nt
	global_store_dwordx4 v[156:157], v[164:167], off nt
	global_store_dwordx4 v[156:157], v[126:129], off offset:256 nt
	s_waitcnt vmcnt(0)
	v_mov_b32_e32 v114, v119
	v_mov_b32_e32 v115, v120
	v_mov_b32_e32 v119, v121
	v_pk_add_f32 v[114:115], v[114:115], v[118:119]
	v_mov_b32_e32 v118, v111
	v_mov_b32_e32 v119, v112
	v_mov_b32_e32 v111, v113
	v_pk_add_f32 v[110:111], v[118:119], v[110:111]
	v_pk_add_f32 v[114:115], v[114:115], v[114:115] op_sel:[0,1] op_sel_hi:[1,0]
	v_pk_add_f32 v[110:111], v[110:111], v[110:111] op_sel:[0,1] op_sel_hi:[1,0]
	v_mov_b32_e32 v115, v114
	v_mov_b32_e32 v111, v110
	s_nop 0
	v_permlane16_swap_b32_e32 v114, v115
	v_permlane16_swap_b32_e32 v110, v111
	v_add_f32_e32 v115, v114, v115
	v_add_f32_e32 v114, v110, v111
	v_mov_b32_e32 v117, v115
	v_mov_b32_e32 v116, v114
	s_nop 0
	v_permlane32_swap_b32_e32 v115, v117
	v_permlane32_swap_b32_e32 v114, v116
	v_pk_add_f32 v[110:111], v[114:115], v[116:117]
	v_mul_f32_e32 v113, 0xbfb8aa3b, v94
	v_pk_fma_f32 v[110:111], v[110:111], s[36:37], v[148:149] op_sel_hi:[1,0,0]
	v_exp_f32_e32 v113, v113
	v_mul_f32_e32 v112, 0x4b800000, v111
	v_cmp_gt_f32_e32 vcc, s76, v111
	v_cmp_gt_f32_e64 s[4:5], s76, v110
	v_mul_f32_e32 v114, 0xbfb8aa3b, v90
	v_cndmask_b32_e32 v111, v111, v112, vcc
	v_mul_f32_e32 v112, 0x4b800000, v110
	v_rsq_f32_e32 v111, v111
	v_cndmask_b32_e64 v110, v110, v112, s[4:5]
	v_rsq_f32_e32 v110, v110
	v_exp_f32_e32 v115, v114
	v_mul_f32_e32 v112, 0x45800000, v111
	v_cndmask_b32_e32 v112, v111, v112, vcc
	v_mul_f32_e32 v111, 0x45800000, v110
	v_cndmask_b32_e64 v110, v110, v111, s[4:5]
	v_add_f32_e32 v111, 1.0, v113
	v_mul_f32_e32 v113, 0xbfb8aa3b, v95
	v_rcp_f32_e32 v114, v111
	v_add_f32_e32 v111, 1.0, v115
	v_exp_f32_e32 v113, v113
	v_mul_f32_e32 v115, 0xbfb8aa3b, v91
	v_exp_f32_e32 v117, v115
	v_rcp_f32_e32 v116, v111
	v_add_f32_e32 v111, 1.0, v113
	v_mul_f32_e32 v113, 0xbfb8aa3b, v96
	v_rcp_f32_e32 v115, v111
	v_add_f32_e32 v111, 1.0, v117
	v_exp_f32_e32 v113, v113
	v_mul_f32_e32 v117, 0xbfb8aa3b, v92
	v_exp_f32_e32 v119, v117
	v_rcp_f32_e32 v117, v111
	v_add_f32_e32 v111, 1.0, v113
	v_mul_f32_e32 v113, 0xbfb8aa3b, v97
	v_rcp_f32_e32 v118, v111
	v_add_f32_e32 v111, 1.0, v119
	v_exp_f32_e32 v113, v113
	v_mul_f32_e32 v119, 0xbfb8aa3b, v93
	v_exp_f32_e32 v121, v119
	v_rcp_f32_e32 v120, v111
	v_add_f32_e32 v111, 1.0, v113
	v_rcp_f32_e32 v119, v111
	v_add_f32_e32 v111, 1.0, v121
	v_rcp_f32_e32 v121, v111
	v_lshlrev_b32_e32 v126, 16, v170
	v_and_b32_e32 v127, 0xffff0000, v170
	v_lshlrev_b32_e32 v128, 16, v171
	v_and_b32_e32 v129, 0xffff0000, v171
	v_pk_mul_f32 v[92:93], v[92:93], v[120:121]
	v_pk_mul_f32 v[90:91], v[90:91], v[116:117]
	v_lshlrev_b32_e32 v122, 16, v168
	v_and_b32_e32 v123, 0xffff0000, v168
	v_lshlrev_b32_e32 v124, 16, v169
	v_and_b32_e32 v125, 0xffff0000, v169
	v_pk_mul_f32 v[96:97], v[96:97], v[118:119]
	v_pk_mul_f32 v[94:95], v[94:95], v[114:115]
	v_pk_mul_f32 v[90:91], v[90:91], v[126:127]
	v_pk_mul_f32 v[92:93], v[92:93], v[128:129]
	v_pk_mul_f32 v[94:95], v[94:95], v[122:123]
	v_pk_mul_f32 v[96:97], v[96:97], v[124:125]
	v_pk_mul_f32 v[114:115], v[92:93], v[112:113] op_sel_hi:[1,0]
	v_pk_mul_f32 v[92:93], v[90:91], v[112:113] op_sel_hi:[1,0]
	v_pk_mul_f32 v[96:97], v[96:97], v[112:113] op_sel_hi:[1,0]
	v_pk_mul_f32 v[94:95], v[94:95], v[112:113] op_sel_hi:[1,0]
	v_cvt_pk_bf16_f32 v92, v92, v93
	v_mul_f32_e32 v93, 0xbfb8aa3b, v86
	v_cvt_pk_bf16_f32 v90, v94, v95
	v_cvt_pk_bf16_f32 v91, v96, v97
	v_exp_f32_e32 v94, v93
	v_mul_f32_e32 v93, 0xbfb8aa3b, v82
	v_mul_f32_e32 v96, 0xbfb8aa3b, v87
	v_exp_f32_e32 v95, v93
	v_exp_f32_e32 v97, v96
	v_mul_f32_e32 v96, 0xbfb8aa3b, v83
	v_exp_f32_e32 v111, v96
	v_add_f32_e32 v95, 1.0, v95
	v_rcp_f32_e32 v96, v95
	v_add_f32_e32 v95, 1.0, v97
	v_add_f32_e32 v97, 1.0, v111
	v_mul_f32_e32 v111, 0xbfb8aa3b, v88
	v_exp_f32_e32 v111, v111
	v_mul_f32_e32 v113, 0xbfb8aa3b, v84
	v_exp_f32_e32 v113, v113
	v_cvt_pk_bf16_f32 v93, v114, v115
	v_add_f32_e32 v111, 1.0, v111
	v_rcp_f32_e32 v114, v111
	v_add_f32_e32 v111, 1.0, v113
	v_mul_f32_e32 v113, 0xbfb8aa3b, v89
	v_exp_f32_e32 v113, v113
	v_mul_f32_e32 v115, 0xbfb8aa3b, v85
	v_exp_f32_e32 v117, v115
	v_rcp_f32_e32 v116, v111
	v_add_f32_e32 v111, 1.0, v113
	v_rcp_f32_e32 v115, v111
	v_add_f32_e32 v111, 1.0, v117
	v_add_f32_e32 v94, 1.0, v94
	v_rcp_f32_e32 v97, v97
	v_rcp_f32_e32 v117, v111
	v_rcp_f32_e32 v94, v94
	v_rcp_f32_e32 v95, v95
	v_lshlrev_b32_e32 v122, 16, v132
	v_and_b32_e32 v123, 0xffff0000, v132
	v_lshlrev_b32_e32 v124, 16, v133
	v_and_b32_e32 v125, 0xffff0000, v133
	v_pk_mul_f32 v[84:85], v[84:85], v[116:117]
	v_pk_mul_f32 v[82:83], v[82:83], v[96:97]
	v_lshlrev_b32_e32 v118, 16, v130
	v_and_b32_e32 v119, 0xffff0000, v130
	v_pk_mul_f32 v[86:87], v[86:87], v[94:95]
	v_pk_mul_f32 v[82:83], v[82:83], v[122:123]
	v_pk_mul_f32 v[84:85], v[84:85], v[124:125]
	v_lshlrev_b32_e32 v120, 16, v131
	v_and_b32_e32 v121, 0xffff0000, v131
	v_pk_mul_f32 v[88:89], v[88:89], v[114:115]
	v_pk_mul_f32 v[86:87], v[86:87], v[118:119]
	v_pk_mul_f32 v[94:95], v[84:85], v[112:113] op_sel_hi:[1,0]
	v_pk_mul_f32 v[84:85], v[82:83], v[112:113] op_sel_hi:[1,0]
	v_pk_mul_f32 v[88:89], v[88:89], v[120:121]
	v_pk_mul_f32 v[86:87], v[86:87], v[112:113] op_sel_hi:[1,0]
	v_cvt_pk_bf16_f32 v84, v84, v85
	v_mul_f32_e32 v85, 0xbfb8aa3b, v78
	v_pk_mul_f32 v[88:89], v[88:89], v[112:113] op_sel_hi:[1,0]
	v_cvt_pk_bf16_f32 v82, v86, v87
	v_exp_f32_e32 v86, v85
	v_mul_f32_e32 v85, 0xbfb8aa3b, v74
	v_cvt_pk_bf16_f32 v83, v88, v89
	v_exp_f32_e32 v87, v85
	v_mul_f32_e32 v88, 0xbfb8aa3b, v79
	v_mul_f32_e32 v89, 0xbfb8aa3b, v75
	v_exp_f32_e32 v88, v88
	v_exp_f32_e32 v89, v89
	v_add_f32_e32 v87, 1.0, v87
	v_cvt_pk_bf16_f32 v85, v94, v95
	v_rcp_f32_e32 v94, v87
	v_add_f32_e32 v87, 1.0, v88
	v_add_f32_e32 v88, 1.0, v89
	v_mul_f32_e32 v89, 0xbfb8aa3b, v80
	v_mul_f32_e32 v95, 0xbfb8aa3b, v76
	v_exp_f32_e32 v89, v89
	v_exp_f32_e32 v96, v95
	v_rcp_f32_e32 v95, v88
	v_add_f32_e32 v86, 1.0, v86
	v_add_f32_e32 v88, 1.0, v89
	v_add_f32_e32 v89, 1.0, v96
	v_mul_f32_e32 v96, 0xbfb8aa3b, v81
	v_exp_f32_e32 v97, v96
	v_mul_f32_e32 v96, 0xbfb8aa3b, v77
	v_exp_f32_e32 v111, v96
	v_rcp_f32_e32 v96, v89
	v_add_f32_e32 v89, 1.0, v97
	v_rcp_f32_e32 v86, v86
	v_rcp_f32_e32 v87, v87
	v_rcp_f32_e32 v88, v88
	v_rcp_f32_e32 v89, v89
	v_add_u32_e32 v116, 0x90, v146
	v_add_u32_e32 v118, 0x80, v146
	v_lshlrev_b32_e32 v112, 16, v102
	v_and_b32_e32 v113, 0xffff0000, v102
	v_lshlrev_b32_e32 v102, 16, v103
	v_and_b32_e32 v103, 0xffff0000, v103
	v_pk_mul_f32 v[80:81], v[80:81], v[88:89]
	v_pk_mul_f32 v[78:79], v[78:79], v[86:87]
	v_ashrrev_i32_e32 v117, 31, v116
	v_ashrrev_i32_e32 v119, 31, v118
	v_pk_mul_f32 v[112:113], v[78:79], v[112:113]
	v_pk_mul_f32 v[102:103], v[80:81], v[102:103]
	v_lshlrev_b64 v[78:79], 8, v[116:117]
	v_lshlrev_b64 v[80:81], 8, v[118:119]
	v_lshl_add_u64 v[78:79], v[152:153], 0, v[78:79]
	v_lshl_add_u64 v[86:87], v[152:153], 0, v[80:81]
	global_load_dwordx4 v[78:81], v[78:79], off nt
	s_nop 0
	global_load_dwordx4 v[86:89], v[86:87], off nt
	v_add_f32_e32 v97, 1.0, v111
	v_rcp_f32_e32 v97, v97
	v_lshlrev_b32_e32 v114, 16, v104
	v_and_b32_e32 v115, 0xffff0000, v104
	v_lshlrev_b32_e32 v104, 16, v105
	v_and_b32_e32 v105, 0xffff0000, v105
	v_pk_mul_f32 v[76:77], v[76:77], v[96:97]
	v_pk_mul_f32 v[74:75], v[74:75], v[94:95]
	v_pk_mul_f32 v[76:77], v[76:77], v[104:105]
	v_pk_mul_f32 v[74:75], v[74:75], v[114:115]
	v_pk_mul_f32 v[76:77], v[76:77], v[110:111] op_sel_hi:[1,0]
	v_pk_mul_f32 v[74:75], v[74:75], v[110:111] op_sel_hi:[1,0]
	v_cvt_pk_bf16_f32 v97, v76, v77
	v_cvt_pk_bf16_f32 v96, v74, v75
	v_mul_f32_e32 v75, 0xbfb8aa3b, v66
	v_mul_f32_e32 v76, 0xbfb8aa3b, v71
	v_pk_mul_f32 v[102:103], v[102:103], v[110:111] op_sel_hi:[1,0]
	v_exp_f32_e32 v75, v75
	v_exp_f32_e32 v77, v76
	v_mul_f32_e32 v76, 0xbfb8aa3b, v67
	v_cvt_pk_bf16_f32 v95, v102, v103
	v_exp_f32_e32 v102, v76
	v_mul_f32_e32 v103, 0xbfb8aa3b, v68
	v_mul_f32_e32 v104, 0xbfb8aa3b, v73
	v_add_f32_e32 v75, 1.0, v75
	v_exp_f32_e32 v103, v103
	v_exp_f32_e32 v105, v104
	v_mul_f32_e32 v104, 0xbfb8aa3b, v69
	v_pk_mul_f32 v[112:113], v[112:113], v[110:111] op_sel_hi:[1,0]
	v_mul_f32_e32 v74, 0xbfb8aa3b, v70
	v_rcp_f32_e32 v76, v75
	v_add_f32_e32 v75, 1.0, v77
	v_add_f32_e32 v77, 1.0, v102
	v_mul_f32_e32 v102, 0xbfb8aa3b, v72
	v_exp_f32_e32 v111, v104
	v_exp_f32_e32 v74, v74
	v_exp_f32_e32 v102, v102
	v_rcp_f32_e32 v77, v77
	v_add_f32_e32 v103, 1.0, v103
	v_rcp_f32_e32 v104, v103
	v_add_f32_e32 v103, 1.0, v105
	v_add_f32_e32 v105, 1.0, v111
	v_add_f32_e32 v74, 1.0, v74
	v_add_f32_e32 v102, 1.0, v102
	v_rcp_f32_e32 v105, v105
	v_rcp_f32_e32 v74, v74
	v_rcp_f32_e32 v75, v75
	v_rcp_f32_e32 v102, v102
	v_rcp_f32_e32 v103, v103
	v_lshlrev_b32_e32 v114, 16, v100
	v_and_b32_e32 v115, 0xffff0000, v100
	v_pk_mul_f32 v[66:67], v[66:67], v[76:77]
	v_lshlrev_b32_e32 v100, 16, v101
	v_pk_mul_f32 v[66:67], v[66:67], v[114:115]
	v_and_b32_e32 v101, 0xffff0000, v101
	v_pk_mul_f32 v[68:69], v[68:69], v[104:105]
	v_pk_mul_f32 v[66:67], v[66:67], v[110:111] op_sel_hi:[1,0]
	v_cvt_pk_bf16_f32 v94, v112, v113
	v_lshlrev_b32_e32 v112, 16, v98
	v_and_b32_e32 v113, 0xffff0000, v98
	v_lshlrev_b32_e32 v98, 16, v99
	v_and_b32_e32 v99, 0xffff0000, v99
	v_pk_mul_f32 v[72:73], v[72:73], v[102:103]
	v_pk_mul_f32 v[70:71], v[70:71], v[74:75]
	v_pk_mul_f32 v[68:69], v[68:69], v[100:101]
	v_cvt_pk_bf16_f32 v100, v66, v67
	v_lshlrev_b64 v[66:67], 12, v[118:119]
	v_pk_mul_f32 v[70:71], v[70:71], v[112:113]
	v_pk_mul_f32 v[72:73], v[72:73], v[98:99]
	v_lshl_add_u64 v[74:75], v[150:151], 0, v[66:67]
	v_pk_mul_f32 v[72:73], v[72:73], v[110:111] op_sel_hi:[1,0]
	v_pk_mul_f32 v[70:71], v[70:71], v[110:111] op_sel_hi:[1,0]
	v_pk_mul_f32 v[68:69], v[68:69], v[110:111] op_sel_hi:[1,0]
	global_load_dwordx4 v[102:105], v[74:75], off offset:256 nt
	global_load_dwordx4 v[110:113], v[74:75], off nt
	v_lshlrev_b64 v[66:67], 12, v[116:117]
	v_lshl_add_u64 v[76:77], v[150:151], 0, v[66:67]
	v_cvt_pk_bf16_f32 v98, v70, v71
	v_cvt_pk_bf16_f32 v99, v72, v73
	v_cvt_pk_bf16_f32 v101, v68, v69
	global_load_dwordx4 v[66:69], v[76:77], off offset:256 nt
	global_load_dwordx4 v[70:73], v[76:77], off nt
	s_nop 0
	global_store_dwordx4 v[108:109], v[90:93], off nt
	global_store_dwordx4 v[108:109], v[82:85], off offset:256 nt
	global_store_dwordx4 v[106:107], v[94:97], off nt
	global_store_dwordx4 v[106:107], v[98:101], off offset:256 nt
	s_waitcnt vmcnt(0)
	v_mov_b32_e32 v82, v87
	v_mov_b32_e32 v83, v88
	v_mov_b32_e32 v87, v89
	v_pk_add_f32 v[82:83], v[82:83], v[86:87]
	v_mov_b32_e32 v86, v79
	v_mov_b32_e32 v87, v80
	v_mov_b32_e32 v79, v81
	v_pk_add_f32 v[78:79], v[86:87], v[78:79]
	v_pk_add_f32 v[82:83], v[82:83], v[82:83] op_sel:[0,1] op_sel_hi:[1,0]
	v_pk_add_f32 v[78:79], v[78:79], v[78:79] op_sel:[0,1] op_sel_hi:[1,0]
	v_mov_b32_e32 v83, v82
	v_mov_b32_e32 v79, v78
	s_nop 0
	v_permlane16_swap_b32_e32 v82, v83
	v_permlane16_swap_b32_e32 v78, v79
	v_add_f32_e32 v83, v82, v83
	v_add_f32_e32 v82, v78, v79
	v_mov_b32_e32 v85, v83
	v_mov_b32_e32 v84, v82
	s_nop 0
	v_permlane32_swap_b32_e32 v83, v85
	v_permlane32_swap_b32_e32 v82, v84
	v_pk_add_f32 v[78:79], v[82:83], v[84:85]
	v_mul_f32_e32 v81, 0xbfb8aa3b, v62
	v_pk_fma_f32 v[78:79], v[78:79], s[36:37], v[148:149] op_sel_hi:[1,0,0]
	v_exp_f32_e32 v81, v81
	v_mul_f32_e32 v80, 0x4b800000, v79
	v_cmp_gt_f32_e32 vcc, s76, v79
	v_cmp_gt_f32_e64 s[4:5], s76, v78
	v_mul_f32_e32 v82, 0xbfb8aa3b, v58
	v_cndmask_b32_e32 v79, v79, v80, vcc
	v_mul_f32_e32 v80, 0x4b800000, v78
	v_rsq_f32_e32 v79, v79
	v_cndmask_b32_e64 v78, v78, v80, s[4:5]
	v_rsq_f32_e32 v78, v78
	v_exp_f32_e32 v83, v82
	v_mul_f32_e32 v80, 0x45800000, v79
	v_cndmask_b32_e32 v80, v79, v80, vcc
	v_mul_f32_e32 v79, 0x45800000, v78
	v_cndmask_b32_e64 v78, v78, v79, s[4:5]
	v_add_f32_e32 v79, 1.0, v81
	v_mul_f32_e32 v81, 0xbfb8aa3b, v63
	v_rcp_f32_e32 v82, v79
	v_add_f32_e32 v79, 1.0, v83
	v_exp_f32_e32 v81, v81
	v_mul_f32_e32 v83, 0xbfb8aa3b, v59
	v_exp_f32_e32 v85, v83
	v_rcp_f32_e32 v84, v79
	v_add_f32_e32 v79, 1.0, v81
	v_mul_f32_e32 v81, 0xbfb8aa3b, v64
	v_rcp_f32_e32 v83, v79
	v_add_f32_e32 v79, 1.0, v85
	v_exp_f32_e32 v81, v81
	v_mul_f32_e32 v85, 0xbfb8aa3b, v60
	v_exp_f32_e32 v87, v85
	v_rcp_f32_e32 v85, v79
	v_add_f32_e32 v79, 1.0, v81
	v_mul_f32_e32 v81, 0xbfb8aa3b, v65
	v_rcp_f32_e32 v86, v79
	v_add_f32_e32 v79, 1.0, v87
	v_exp_f32_e32 v81, v81
	v_mul_f32_e32 v87, 0xbfb8aa3b, v61
	v_exp_f32_e32 v89, v87
	v_rcp_f32_e32 v88, v79
	v_add_f32_e32 v79, 1.0, v81
	v_rcp_f32_e32 v87, v79
	v_add_f32_e32 v79, 1.0, v89
	v_rcp_f32_e32 v89, v79
	v_pk_mul_f32 v[58:59], v[58:59], v[84:85]
	v_lshlrev_b32_e32 v94, 16, v112
	v_and_b32_e32 v95, 0xffff0000, v112
	v_lshlrev_b32_e32 v96, 16, v113
	v_and_b32_e32 v97, 0xffff0000, v113
	v_pk_mul_f32 v[60:61], v[60:61], v[88:89]
	v_lshlrev_b32_e32 v90, 16, v110
	v_and_b32_e32 v91, 0xffff0000, v110
	v_lshlrev_b32_e32 v92, 16, v111
	v_and_b32_e32 v93, 0xffff0000, v111
	v_pk_mul_f32 v[64:65], v[64:65], v[86:87]
	v_pk_mul_f32 v[62:63], v[62:63], v[82:83]
	v_pk_mul_f32 v[58:59], v[58:59], v[94:95]
	v_pk_mul_f32 v[60:61], v[60:61], v[96:97]
	v_pk_mul_f32 v[62:63], v[62:63], v[90:91]
	v_pk_mul_f32 v[64:65], v[64:65], v[92:93]
	v_pk_mul_f32 v[82:83], v[60:61], v[80:81] op_sel_hi:[1,0]
	v_pk_mul_f32 v[60:61], v[58:59], v[80:81] op_sel_hi:[1,0]
	v_pk_mul_f32 v[64:65], v[64:65], v[80:81] op_sel_hi:[1,0]
	v_pk_mul_f32 v[62:63], v[62:63], v[80:81] op_sel_hi:[1,0]
	v_cvt_pk_bf16_f32 v60, v60, v61
	v_mul_f32_e32 v61, 0xbfb8aa3b, v54
	v_cvt_pk_bf16_f32 v58, v62, v63
	v_cvt_pk_bf16_f32 v59, v64, v65
	v_exp_f32_e32 v62, v61
	v_mul_f32_e32 v61, 0xbfb8aa3b, v50
	v_mul_f32_e32 v64, 0xbfb8aa3b, v55
	v_exp_f32_e32 v63, v61
	v_exp_f32_e32 v65, v64
	v_mul_f32_e32 v64, 0xbfb8aa3b, v51
	v_exp_f32_e32 v79, v64
	v_add_f32_e32 v63, 1.0, v63
	v_rcp_f32_e32 v64, v63
	v_add_f32_e32 v63, 1.0, v65
	v_add_f32_e32 v65, 1.0, v79
	v_mul_f32_e32 v79, 0xbfb8aa3b, v56
	v_exp_f32_e32 v79, v79
	v_mul_f32_e32 v81, 0xbfb8aa3b, v52
	v_exp_f32_e32 v81, v81
	v_cvt_pk_bf16_f32 v61, v82, v83
	v_add_f32_e32 v79, 1.0, v79
	v_rcp_f32_e32 v82, v79
	v_add_f32_e32 v79, 1.0, v81
	v_mul_f32_e32 v81, 0xbfb8aa3b, v57
	v_exp_f32_e32 v81, v81
	v_mul_f32_e32 v83, 0xbfb8aa3b, v53
	v_exp_f32_e32 v85, v83
	v_rcp_f32_e32 v84, v79
	v_add_f32_e32 v79, 1.0, v81
	v_rcp_f32_e32 v83, v79
	v_add_f32_e32 v79, 1.0, v85
	v_add_f32_e32 v62, 1.0, v62
	v_rcp_f32_e32 v65, v65
	v_rcp_f32_e32 v85, v79
	v_rcp_f32_e32 v62, v62
	v_rcp_f32_e32 v63, v63
	v_lshlrev_b32_e32 v90, 16, v104
	v_and_b32_e32 v91, 0xffff0000, v104
	v_lshlrev_b32_e32 v92, 16, v105
	v_and_b32_e32 v93, 0xffff0000, v105
	v_pk_mul_f32 v[52:53], v[52:53], v[84:85]
	v_pk_mul_f32 v[50:51], v[50:51], v[64:65]
	v_lshlrev_b32_e32 v86, 16, v102
	v_and_b32_e32 v87, 0xffff0000, v102
	v_pk_mul_f32 v[54:55], v[54:55], v[62:63]
	v_pk_mul_f32 v[50:51], v[50:51], v[90:91]
	v_pk_mul_f32 v[52:53], v[52:53], v[92:93]
	v_lshlrev_b32_e32 v88, 16, v103
	v_and_b32_e32 v89, 0xffff0000, v103
	v_pk_mul_f32 v[56:57], v[56:57], v[82:83]
	v_pk_mul_f32 v[54:55], v[54:55], v[86:87]
	v_pk_mul_f32 v[62:63], v[52:53], v[80:81] op_sel_hi:[1,0]
	v_pk_mul_f32 v[52:53], v[50:51], v[80:81] op_sel_hi:[1,0]
	v_pk_mul_f32 v[56:57], v[56:57], v[88:89]
	v_pk_mul_f32 v[54:55], v[54:55], v[80:81] op_sel_hi:[1,0]
	v_cvt_pk_bf16_f32 v52, v52, v53
	v_mul_f32_e32 v53, 0xbfb8aa3b, v46
	v_pk_mul_f32 v[56:57], v[56:57], v[80:81] op_sel_hi:[1,0]
	v_cvt_pk_bf16_f32 v50, v54, v55
	v_exp_f32_e32 v54, v53
	v_mul_f32_e32 v53, 0xbfb8aa3b, v42
	v_cvt_pk_bf16_f32 v51, v56, v57
	v_exp_f32_e32 v55, v53
	v_mul_f32_e32 v56, 0xbfb8aa3b, v47
	v_mul_f32_e32 v57, 0xbfb8aa3b, v43
	v_exp_f32_e32 v56, v56
	v_exp_f32_e32 v57, v57
	v_add_f32_e32 v55, 1.0, v55
	v_cvt_pk_bf16_f32 v53, v62, v63
	v_rcp_f32_e32 v62, v55
	v_add_f32_e32 v55, 1.0, v56
	v_add_f32_e32 v56, 1.0, v57
	v_mul_f32_e32 v57, 0xbfb8aa3b, v48
	v_mul_f32_e32 v63, 0xbfb8aa3b, v44
	v_exp_f32_e32 v57, v57
	v_exp_f32_e32 v64, v63
	v_rcp_f32_e32 v63, v56
	v_add_f32_e32 v54, 1.0, v54
	v_add_f32_e32 v56, 1.0, v57
	v_add_f32_e32 v57, 1.0, v64
	v_mul_f32_e32 v64, 0xbfb8aa3b, v49
	v_exp_f32_e32 v65, v64
	v_mul_f32_e32 v64, 0xbfb8aa3b, v45
	v_exp_f32_e32 v79, v64
	v_rcp_f32_e32 v64, v57
	v_add_f32_e32 v57, 1.0, v65
	v_rcp_f32_e32 v54, v54
	v_rcp_f32_e32 v55, v55
	v_rcp_f32_e32 v56, v56
	v_rcp_f32_e32 v57, v57
	v_lshlrev_b32_e32 v80, 16, v70
	v_and_b32_e32 v81, 0xffff0000, v70
	v_lshlrev_b32_e32 v70, 16, v71
	v_and_b32_e32 v71, 0xffff0000, v71
	v_pk_mul_f32 v[48:49], v[48:49], v[56:57]
	v_pk_mul_f32 v[46:47], v[46:47], v[54:55]
	v_add_u32_e32 v84, 0xb0, v146
	v_add_u32_e32 v86, 0xa0, v146
	v_pk_mul_f32 v[80:81], v[46:47], v[80:81]
	v_pk_mul_f32 v[46:47], v[48:49], v[70:71]
	v_ashrrev_i32_e32 v85, 31, v84
	v_ashrrev_i32_e32 v87, 31, v86
	v_pk_mul_f32 v[70:71], v[46:47], v[78:79] op_sel_hi:[1,0]
	v_lshlrev_b64 v[46:47], 8, v[84:85]
	v_lshlrev_b64 v[48:49], 8, v[86:87]
	v_lshl_add_u64 v[46:47], v[152:153], 0, v[46:47]
	v_lshl_add_u64 v[54:55], v[152:153], 0, v[48:49]
	global_load_dwordx4 v[46:49], v[46:47], off nt
	s_nop 0
	global_load_dwordx4 v[54:57], v[54:55], off nt
	v_add_f32_e32 v65, 1.0, v79
	v_rcp_f32_e32 v65, v65
	v_lshlrev_b32_e32 v82, 16, v72
	v_and_b32_e32 v83, 0xffff0000, v72
	v_lshlrev_b32_e32 v72, 16, v73
	v_and_b32_e32 v73, 0xffff0000, v73
	v_pk_mul_f32 v[44:45], v[44:45], v[64:65]
	v_pk_mul_f32 v[42:43], v[42:43], v[62:63]
	v_pk_mul_f32 v[44:45], v[44:45], v[72:73]
	v_pk_mul_f32 v[42:43], v[42:43], v[82:83]
	v_pk_mul_f32 v[44:45], v[44:45], v[78:79] op_sel_hi:[1,0]
	v_pk_mul_f32 v[42:43], v[42:43], v[78:79] op_sel_hi:[1,0]
	v_cvt_pk_bf16_f32 v65, v44, v45
	v_cvt_pk_bf16_f32 v64, v42, v43
	v_mul_f32_e32 v43, 0xbfb8aa3b, v34
	v_mul_f32_e32 v44, 0xbfb8aa3b, v39
	v_exp_f32_e32 v43, v43
	v_exp_f32_e32 v45, v44
	v_mul_f32_e32 v44, 0xbfb8aa3b, v35
	v_cvt_pk_bf16_f32 v63, v70, v71
	v_exp_f32_e32 v70, v44
	v_add_f32_e32 v43, 1.0, v43
	v_rcp_f32_e32 v44, v43
	v_add_f32_e32 v43, 1.0, v45
	v_add_f32_e32 v45, 1.0, v70
	v_mul_f32_e32 v70, 0xbfb8aa3b, v40
	v_exp_f32_e32 v70, v70
	v_mul_f32_e32 v71, 0xbfb8aa3b, v36
	v_exp_f32_e32 v71, v71
	v_pk_mul_f32 v[80:81], v[80:81], v[78:79] op_sel_hi:[1,0]
	v_add_f32_e32 v70, 1.0, v70
	v_cvt_pk_bf16_f32 v62, v80, v81
	v_rcp_f32_e32 v80, v70
	v_add_f32_e32 v70, 1.0, v71
	v_rcp_f32_e32 v82, v70
	v_mul_f32_e32 v70, 0xbfb8aa3b, v41
	v_exp_f32_e32 v79, v70
	v_mul_f32_e32 v70, 0xbfb8aa3b, v37
	v_exp_f32_e32 v83, v70
	v_lshlrev_b64 v[70:71], 12, v[84:85]
	v_lshl_add_u64 v[152:153], v[150:151], 0, v[70:71]
	global_load_dwordx4 v[70:73], v[152:153], off offset:256 nt
	v_mul_f32_e32 v42, 0xbfb8aa3b, v38
	v_exp_f32_e32 v42, v42
	v_add_f32_e32 v79, 1.0, v79
	v_rcp_f32_e32 v81, v79
	v_add_f32_e32 v79, 1.0, v83
	v_add_f32_e32 v42, 1.0, v42
	v_rcp_f32_e32 v42, v42
	v_rcp_f32_e32 v43, v43
	v_rcp_f32_e32 v45, v45
	v_rcp_f32_e32 v83, v79
	v_lshlrev_b32_e32 v84, 16, v66
	v_and_b32_e32 v85, 0xffff0000, v66
	v_lshlrev_b32_e32 v66, 16, v67
	v_and_b32_e32 v67, 0xffff0000, v67
	v_lshlrev_b32_e32 v88, 16, v68
	v_and_b32_e32 v89, 0xffff0000, v68
	v_lshlrev_b32_e32 v68, 16, v69
	v_and_b32_e32 v69, 0xffff0000, v69
	v_pk_mul_f32 v[40:41], v[40:41], v[80:81]
	v_pk_mul_f32 v[38:39], v[38:39], v[42:43]
	v_pk_mul_f32 v[36:37], v[36:37], v[82:83]
	v_pk_mul_f32 v[34:35], v[34:35], v[44:45]
	v_pk_mul_f32 v[38:39], v[38:39], v[84:85]
	v_pk_mul_f32 v[40:41], v[40:41], v[66:67]
	v_pk_mul_f32 v[34:35], v[34:35], v[88:89]
	v_pk_mul_f32 v[36:37], v[36:37], v[68:69]
	v_pk_mul_f32 v[40:41], v[40:41], v[78:79] op_sel_hi:[1,0]
	v_pk_mul_f32 v[38:39], v[38:39], v[78:79] op_sel_hi:[1,0]
	v_pk_mul_f32 v[36:37], v[36:37], v[78:79] op_sel_hi:[1,0]
	v_pk_mul_f32 v[34:35], v[34:35], v[78:79] op_sel_hi:[1,0]
	global_load_dwordx4 v[78:81], v[152:153], off nt
	v_cvt_pk_bf16_f32 v68, v34, v35
	v_lshlrev_b64 v[34:35], 12, v[86:87]
	v_lshl_add_u64 v[42:43], v[150:151], 0, v[34:35]
	v_cvt_pk_bf16_f32 v66, v38, v39
	v_cvt_pk_bf16_f32 v67, v40, v41
	v_cvt_pk_bf16_f32 v69, v36, v37
	global_load_dwordx4 v[38:41], v[42:43], off offset:256 nt
	global_load_dwordx4 v[34:37], v[42:43], off nt
	s_nop 0
	global_store_dwordx4 v[74:75], v[58:61], off nt
	global_store_dwordx4 v[74:75], v[50:53], off offset:256 nt
	global_store_dwordx4 v[76:77], v[62:65], off nt
	global_store_dwordx4 v[76:77], v[66:69], off offset:256 nt
	s_waitcnt vmcnt(0)
	v_mov_b32_e32 v52, v47
	v_mov_b32_e32 v53, v48
	v_mov_b32_e32 v47, v49
	v_mov_b32_e32 v44, v55
	v_mov_b32_e32 v45, v56
	v_mov_b32_e32 v55, v57
	v_pk_add_f32 v[46:47], v[52:53], v[46:47]
	v_pk_add_f32 v[44:45], v[44:45], v[54:55]
	v_pk_add_f32 v[46:47], v[46:47], v[46:47] op_sel:[0,1] op_sel_hi:[1,0]
	v_pk_add_f32 v[44:45], v[44:45], v[44:45] op_sel:[0,1] op_sel_hi:[1,0]
	v_mul_f32_e32 v47, 0xbfb8aa3b, v30
	v_mov_b32_e32 v45, v44
	v_exp_f32_e32 v47, v47
	s_nop 0
	v_permlane16_swap_b32_e32 v44, v45
	v_add_f32_e32 v44, v44, v45
	v_mov_b32_e32 v45, v46
	s_nop 1
	v_permlane16_swap_b32_e32 v46, v45
	v_add_f32_e32 v45, v46, v45
	v_add_f32_e32 v46, 1.0, v47
	v_mul_f32_e32 v47, 0xbfb8aa3b, v31
	v_exp_f32_e32 v47, v47
	v_rcp_f32_e32 v46, v46
	v_mul_f32_e32 v53, 0xbfb8aa3b, v27
	v_exp_f32_e32 v53, v53
	v_add_f32_e32 v47, 1.0, v47
	v_rcp_f32_e32 v47, v47
	v_mul_f32_e32 v54, 0xbfb8aa3b, v28
	v_mul_f32_e32 v55, 0xbfb8aa3b, v29
	v_exp_f32_e32 v54, v54
	v_pk_mul_f32 v[30:31], v[30:31], v[46:47]
	v_mul_f32_e32 v47, 0xbfb8aa3b, v26
	v_exp_f32_e32 v52, v47
	v_exp_f32_e32 v55, v55
	v_add_f32_e32 v53, 1.0, v53
	v_add_f32_e32 v54, 1.0, v54
	v_add_f32_e32 v52, 1.0, v52
	v_rcp_f32_e32 v52, v52
	v_add_f32_e32 v55, 1.0, v55
	v_rcp_f32_e32 v53, v53
	v_rcp_f32_e32 v54, v54
	v_rcp_f32_e32 v55, v55
	v_lshlrev_b32_e32 v46, 16, v70
	v_and_b32_e32 v47, 0xffff0000, v70
	v_pk_mul_f32 v[30:31], v[30:31], v[46:47]
	v_pk_mul_f32 v[26:27], v[26:27], v[52:53]
	v_mul_f32_e32 v47, 0xbfb8aa3b, v22
	v_mul_f32_e32 v53, 0xbfb8aa3b, v23
	v_pk_mul_f32 v[28:29], v[28:29], v[54:55]
	v_exp_f32_e32 v52, v47
	v_exp_f32_e32 v53, v53
	v_mul_f32_e32 v54, 0xbfb8aa3b, v24
	v_mul_f32_e32 v55, 0xbfb8aa3b, v25
	v_mul_f32_e32 v48, 0xbfb8aa3b, v32
	v_mul_f32_e32 v49, 0xbfb8aa3b, v33
	v_exp_f32_e32 v54, v54
	v_exp_f32_e32 v55, v55
	v_exp_f32_e32 v48, v48
	v_exp_f32_e32 v49, v49
	v_add_f32_e32 v52, 1.0, v52
	v_add_f32_e32 v53, 1.0, v53
	v_rcp_f32_e32 v52, v52
	v_add_f32_e32 v54, 1.0, v54
	v_add_f32_e32 v55, 1.0, v55
	v_rcp_f32_e32 v53, v53
	v_add_f32_e32 v48, 1.0, v48
	v_add_f32_e32 v49, 1.0, v49
	v_rcp_f32_e32 v54, v54
	v_rcp_f32_e32 v55, v55
	v_rcp_f32_e32 v48, v48
	v_rcp_f32_e32 v49, v49
	v_lshlrev_b32_e32 v46, 16, v72
	v_and_b32_e32 v47, 0xffff0000, v72
	v_pk_mul_f32 v[26:27], v[26:27], v[46:47]
	v_pk_mul_f32 v[22:23], v[22:23], v[52:53]
	v_mul_f32_e32 v47, 0xbfb8aa3b, v18
	v_mul_f32_e32 v53, 0xbfb8aa3b, v19
	v_mov_b32_e32 v50, v44
	v_mov_b32_e32 v51, v45
	v_pk_mul_f32 v[24:25], v[24:25], v[54:55]
	v_exp_f32_e32 v52, v47
	v_exp_f32_e32 v53, v53
	v_mul_f32_e32 v54, 0xbfb8aa3b, v20
	v_mul_f32_e32 v55, 0xbfb8aa3b, v21
	v_permlane32_swap_b32_e32 v44, v50
	v_permlane32_swap_b32_e32 v45, v51
	v_pk_mul_f32 v[32:33], v[32:33], v[48:49]
	v_lshlrev_b32_e32 v48, 16, v71
	v_and_b32_e32 v49, 0xffff0000, v71
	v_exp_f32_e32 v54, v54
	v_exp_f32_e32 v55, v55
	v_pk_mul_f32 v[32:33], v[32:33], v[48:49]
	v_lshlrev_b32_e32 v48, 16, v73
	v_and_b32_e32 v49, 0xffff0000, v73
	v_pk_add_f32 v[44:45], v[44:45], v[50:51]
	v_pk_mul_f32 v[28:29], v[28:29], v[48:49]
	v_lshlrev_b32_e32 v48, 16, v79
	v_and_b32_e32 v49, 0xffff0000, v79
	v_pk_fma_f32 v[44:45], v[44:45], s[36:37], v[148:149] op_sel_hi:[1,0,0]
	v_add_f32_e32 v52, 1.0, v52
	v_add_f32_e32 v53, 1.0, v53
	v_pk_mul_f32 v[24:25], v[24:25], v[48:49]
	v_mul_f32_e32 v49, 0x4b800000, v45
	v_cmp_gt_f32_e32 vcc, s76, v45
	v_rcp_f32_e32 v52, v52
	v_add_f32_e32 v54, 1.0, v54
	v_add_f32_e32 v55, 1.0, v55
	v_rcp_f32_e32 v53, v53
	v_cndmask_b32_e32 v45, v45, v49, vcc
	v_rcp_f32_e32 v54, v54
	v_rcp_f32_e32 v55, v55
	v_rsq_f32_e32 v45, v45
	v_lshlrev_b32_e32 v46, 16, v78
	v_and_b32_e32 v47, 0xffff0000, v78
	v_pk_mul_f32 v[22:23], v[22:23], v[46:47]
	v_pk_mul_f32 v[18:19], v[18:19], v[52:53]
	v_lshlrev_b32_e32 v46, 16, v80
	v_and_b32_e32 v47, 0xffff0000, v80
	v_pk_mul_f32 v[20:21], v[20:21], v[54:55]
	v_lshlrev_b32_e32 v48, 16, v81
	v_and_b32_e32 v49, 0xffff0000, v81
	v_pk_mul_f32 v[46:47], v[18:19], v[46:47]
	v_mul_f32_e32 v18, 0x45800000, v45
	v_pk_mul_f32 v[20:21], v[20:21], v[48:49]
	v_cndmask_b32_e32 v48, v45, v18, vcc
	v_pk_mul_f32 v[18:19], v[32:33], v[48:49] op_sel_hi:[1,0]
	v_cmp_gt_f32_e32 vcc, s76, v44
	v_cvt_pk_bf16_f32 v131, v18, v19
	v_pk_mul_f32 v[18:19], v[28:29], v[48:49] op_sel_hi:[1,0]
	v_pk_mul_f32 v[26:27], v[26:27], v[48:49] op_sel_hi:[1,0]
	v_cvt_pk_bf16_f32 v133, v18, v19
	v_pk_mul_f32 v[18:19], v[22:23], v[48:49] op_sel_hi:[1,0]
	v_pk_mul_f32 v[22:23], v[20:21], v[48:49] op_sel_hi:[1,0]
	v_pk_mul_f32 v[20:21], v[46:47], v[48:49] op_sel_hi:[1,0]
	v_cvt_pk_bf16_f32 v132, v26, v27
	v_cvt_pk_bf16_f32 v20, v20, v21
	v_cvt_pk_bf16_f32 v21, v22, v23
	v_mul_f32_e32 v23, 0xbfb8aa3b, v14
	v_exp_f32_e32 v23, v23
	v_mul_f32_e32 v22, 0x4b800000, v44
	v_cndmask_b32_e32 v22, v44, v22, vcc
	v_rsq_f32_e32 v26, v22
	v_add_f32_e32 v22, 1.0, v23
	v_mul_f32_e32 v23, 0xbfb8aa3b, v15
	v_exp_f32_e32 v23, v23
	v_pk_mul_f32 v[24:25], v[24:25], v[48:49] op_sel_hi:[1,0]
	v_cvt_pk_bf16_f32 v18, v18, v19
	v_cvt_pk_bf16_f32 v19, v24, v25
	v_add_f32_e32 v23, 1.0, v23
	v_rcp_f32_e32 v22, v22
	v_mul_f32_e32 v24, 0xbfb8aa3b, v16
	v_mul_f32_e32 v25, 0xbfb8aa3b, v17
	v_rcp_f32_e32 v23, v23
	v_exp_f32_e32 v24, v24
	v_exp_f32_e32 v25, v25
	v_mul_f32_e32 v27, 0x45800000, v26
	v_pk_mul_f32 v[14:15], v[14:15], v[22:23]
	v_lshlrev_b32_e32 v22, 16, v38
	v_and_b32_e32 v23, 0xffff0000, v38
	v_add_f32_e32 v24, 1.0, v24
	v_add_f32_e32 v25, 1.0, v25
	v_pk_mul_f32 v[14:15], v[14:15], v[22:23]
	v_mul_f32_e32 v22, 0xbfb8aa3b, v10
	v_mul_f32_e32 v23, 0xbfb8aa3b, v11
	v_rcp_f32_e32 v24, v24
	v_rcp_f32_e32 v25, v25
	v_exp_f32_e32 v22, v22
	v_exp_f32_e32 v23, v23
	v_cndmask_b32_e32 v26, v26, v27, vcc
	v_pk_mul_f32 v[16:17], v[16:17], v[24:25]
	v_lshlrev_b32_e32 v24, 16, v39
	v_and_b32_e32 v25, 0xffff0000, v39
	v_add_f32_e32 v22, 1.0, v22
	v_add_f32_e32 v23, 1.0, v23
	v_pk_mul_f32 v[16:17], v[16:17], v[24:25]
	v_rcp_f32_e32 v22, v22
	v_mul_f32_e32 v24, 0xbfb8aa3b, v12
	v_mul_f32_e32 v25, 0xbfb8aa3b, v13
	v_rcp_f32_e32 v23, v23
	v_exp_f32_e32 v24, v24
	v_exp_f32_e32 v25, v25
	v_pk_mul_f32 v[16:17], v[16:17], v[26:27] op_sel_hi:[1,0]
	v_pk_mul_f32 v[14:15], v[14:15], v[26:27] op_sel_hi:[1,0]
	v_pk_mul_f32 v[10:11], v[10:11], v[22:23]
	v_cvt_pk_bf16_f32 v14, v14, v15
	v_cvt_pk_bf16_f32 v15, v16, v17
	v_lshlrev_b32_e32 v16, 16, v40
	v_and_b32_e32 v17, 0xffff0000, v40
	v_add_f32_e32 v24, 1.0, v24
	v_add_f32_e32 v25, 1.0, v25
	v_pk_mul_f32 v[10:11], v[10:11], v[16:17]
	v_mul_f32_e32 v16, 0xbfb8aa3b, v6
	v_rcp_f32_e32 v24, v24
	v_rcp_f32_e32 v25, v25
	v_exp_f32_e32 v16, v16
	v_lshlrev_b32_e32 v22, 16, v41
	v_and_b32_e32 v23, 0xffff0000, v41
	v_pk_mul_f32 v[12:13], v[12:13], v[24:25]
	v_add_f32_e32 v16, 1.0, v16
	v_mul_f32_e32 v17, 0xbfb8aa3b, v8
	v_pk_mul_f32 v[12:13], v[12:13], v[22:23]
	v_rcp_f32_e32 v22, v16
	v_mul_f32_e32 v16, 0xbfb8aa3b, v7
	v_exp_f32_e32 v17, v17
	v_mul_f32_e32 v23, 0xbfb8aa3b, v9
	v_exp_f32_e32 v16, v16
	v_exp_f32_e32 v23, v23
	v_add_f32_e32 v17, 1.0, v17
	v_rcp_f32_e32 v24, v17
	v_add_f32_e32 v16, 1.0, v16
	v_add_f32_e32 v17, 1.0, v23
	v_rcp_f32_e32 v25, v17
	v_rcp_f32_e32 v23, v16
	v_pk_mul_f32 v[12:13], v[12:13], v[26:27] op_sel_hi:[1,0]
	v_pk_mul_f32 v[10:11], v[10:11], v[26:27] op_sel_hi:[1,0]
	v_cvt_pk_bf16_f32 v17, v12, v13
	v_cvt_pk_bf16_f32 v16, v10, v11
	v_pk_mul_f32 v[8:9], v[8:9], v[24:25]
	v_pk_mul_f32 v[6:7], v[6:7], v[22:23]
	v_lshlrev_b32_e32 v10, 16, v34
	v_and_b32_e32 v11, 0xffff0000, v34
	v_lshlrev_b32_e32 v12, 16, v35
	v_and_b32_e32 v13, 0xffff0000, v35
	v_pk_mul_f32 v[6:7], v[6:7], v[10:11]
	v_mul_f32_e32 v10, 0xbfb8aa3b, v2
	v_pk_mul_f32 v[8:9], v[8:9], v[12:13]
	v_mul_f32_e32 v11, 0xbfb8aa3b, v3
	v_mul_f32_e32 v12, 0xbfb8aa3b, v4
	v_mul_f32_e32 v13, 0xbfb8aa3b, v5
	v_exp_f32_e32 v10, v10
	v_exp_f32_e32 v11, v11
	v_exp_f32_e32 v12, v12
	v_exp_f32_e32 v13, v13
	v_add_f32_e32 v10, 1.0, v10
	v_add_f32_e32 v11, 1.0, v11
	v_add_f32_e32 v12, 1.0, v12
	v_add_f32_e32 v13, 1.0, v13
	v_rcp_f32_e32 v10, v10
	v_rcp_f32_e32 v12, v12
	v_rcp_f32_e32 v13, v13
	v_rcp_f32_e32 v11, v11
	v_pk_mul_f32 v[8:9], v[8:9], v[26:27] op_sel_hi:[1,0]
	v_pk_mul_f32 v[6:7], v[6:7], v[26:27] op_sel_hi:[1,0]
	v_pk_mul_f32 v[4:5], v[4:5], v[12:13]
	v_cvt_pk_bf16_f32 v6, v6, v7
	v_cvt_pk_bf16_f32 v7, v8, v9
	v_pk_mul_f32 v[2:3], v[2:3], v[10:11]
	v_lshlrev_b32_e32 v8, 16, v36
	v_and_b32_e32 v9, 0xffff0000, v36
	v_lshlrev_b32_e32 v10, 16, v37
	v_and_b32_e32 v11, 0xffff0000, v37
	v_pk_mul_f32 v[2:3], v[2:3], v[8:9]
	v_pk_mul_f32 v[4:5], v[4:5], v[10:11]
	v_pk_mul_f32 v[30:31], v[30:31], v[48:49] op_sel_hi:[1,0]
	v_pk_mul_f32 v[4:5], v[4:5], v[26:27] op_sel_hi:[1,0]
	v_pk_mul_f32 v[2:3], v[2:3], v[26:27] op_sel_hi:[1,0]
	v_cvt_pk_bf16_f32 v130, v30, v31
	v_cvt_pk_bf16_f32 v8, v2, v3
	v_cvt_pk_bf16_f32 v9, v4, v5
	global_store_dwordx4 v[42:43], v[6:9], off nt
	global_store_dwordx4 v[42:43], v[14:17], off offset:256 nt
	global_store_dwordx4 v[152:153], v[18:21], off nt
	s_andn2_b64 vcc, exec, s[2:3]
	s_mov_b64 s[0:1], -1
	global_store_dwordx4 v[152:153], v[130:133], off offset:256 nt
	s_cbranch_vccnz .LBB0_678

.LBB0_771:
	ds_read_b128 v[130:133], v180
	ds_read_b128 v[134:137], v180 offset:1024
	ds_read_b128 v[138:141], v180 offset:2048
	ds_read_b128 v[142:145], v180 offset:3072
	ds_read_b128 v[146:149], v181
	ds_read_b128 v[166:169], v181 offset:1024
	ds_read_b128 v[170:173], v181 offset:2048
	ds_read_b128 v[174:177], v181 offset:3072
	s_add_u32 s36, s0, 0xfffc0080
	s_addc_u32 s37, s1, -1
	s_cmp_eq_u32 s58, 12
	s_cselect_b32 s39, s27, s37
	s_cselect_b32 s38, s54, s36
	s_cselect_b32 s37, s25, s57
	s_cselect_b32 s36, s55, s56
	v_lshl_add_u64 v[216:217], s[0:1], 0, v[158:159]
	s_add_i32 m0, s35, 0xc000
	ds_read_b128 v[184:187], v182
	ds_read_b128 v[188:191], v182 offset:1024
	ds_read_b128 v[192:195], v182 offset:2048
	ds_read_b128 v[196:199], v182 offset:3072
	ds_read_b128 v[200:203], v182 offset:4096
	ds_read_b128 v[204:207], v182 offset:5120
	ds_read_b128 v[208:211], v182 offset:6144
	ds_read_b128 v[212:215], v182 offset:7168
	global_load_lds_dwordx4 v[216:217], off
	v_lshl_add_u64 v[216:217], s[0:1], 0, v[160:161]
	s_add_i32 m0, s35, 0xe000
	s_nop 0
	global_load_lds_dwordx4 v[216:217], off
	s_waitcnt vmcnt(8)
	s_waitcnt lgkmcnt(0)
	s_barrier
	s_setprio 1
	s_waitcnt lgkmcnt(0)
	v_mfma_f32_16x16x32_bf16 v[126:129], v[130:133], v[184:187], v[126:129]
	v_mfma_f32_16x16x32_bf16 v[122:125], v[138:141], v[184:187], v[122:125]
	v_mfma_f32_16x16x32_bf16 v[110:113], v[130:133], v[192:195], v[110:113]
	v_mfma_f32_16x16x32_bf16 v[106:109], v[138:141], v[192:195], v[106:109]
	v_mfma_f32_16x16x32_bf16 v[94:97], v[130:133], v[200:203], v[94:97]
	v_mfma_f32_16x16x32_bf16 v[90:93], v[138:141], v[200:203], v[90:93]
	v_mfma_f32_16x16x32_bf16 v[78:81], v[130:133], v[208:211], v[78:81]
	v_mfma_f32_16x16x32_bf16 v[74:77], v[138:141], v[208:211], v[74:77]
	v_mfma_f32_16x16x32_bf16 v[126:129], v[134:137], v[188:191], v[126:129]
	v_mfma_f32_16x16x32_bf16 v[122:125], v[142:145], v[188:191], v[122:125]
	v_mfma_f32_16x16x32_bf16 v[110:113], v[134:137], v[196:199], v[110:113]
	v_mfma_f32_16x16x32_bf16 v[106:109], v[142:145], v[196:199], v[106:109]
	v_mfma_f32_16x16x32_bf16 v[94:97], v[134:137], v[204:207], v[94:97]
	v_mfma_f32_16x16x32_bf16 v[90:93], v[142:145], v[204:207], v[90:93]
	v_mfma_f32_16x16x32_bf16 v[78:81], v[134:137], v[212:215], v[78:81]
	v_mfma_f32_16x16x32_bf16 v[74:77], v[142:145], v[212:215], v[74:77]
	s_setprio 0
	s_setprio 1
	v_mfma_f32_16x16x32_bf16 v[118:121], v[146:149], v[184:187], v[118:121]
	v_mfma_f32_16x16x32_bf16 v[114:117], v[170:173], v[184:187], v[114:117]
	v_mfma_f32_16x16x32_bf16 v[102:105], v[146:149], v[192:195], v[102:105]
	v_mfma_f32_16x16x32_bf16 v[98:101], v[170:173], v[192:195], v[98:101]
	v_mfma_f32_16x16x32_bf16 v[86:89], v[146:149], v[200:203], v[86:89]
	v_mfma_f32_16x16x32_bf16 v[82:85], v[170:173], v[200:203], v[82:85]
	v_mfma_f32_16x16x32_bf16 v[70:73], v[146:149], v[208:211], v[70:73]
	v_mfma_f32_16x16x32_bf16 v[66:69], v[170:173], v[208:211], v[66:69]
	v_mfma_f32_16x16x32_bf16 v[118:121], v[166:169], v[188:191], v[118:121]
	v_mfma_f32_16x16x32_bf16 v[114:117], v[174:177], v[188:191], v[114:117]
	v_mfma_f32_16x16x32_bf16 v[102:105], v[166:169], v[196:199], v[102:105]
	v_mfma_f32_16x16x32_bf16 v[98:101], v[174:177], v[196:199], v[98:101]
	v_mfma_f32_16x16x32_bf16 v[86:89], v[166:169], v[204:207], v[86:89]
	v_mfma_f32_16x16x32_bf16 v[82:85], v[174:177], v[204:207], v[82:85]
	v_mfma_f32_16x16x32_bf16 v[70:73], v[166:169], v[212:215], v[70:73]
	v_mfma_f32_16x16x32_bf16 v[66:69], v[174:177], v[212:215], v[66:69]
	s_setprio 0
	s_barrier
	s_add_i32 s59, s51, s43
	v_lshl_add_u64 v[216:217], s[36:37], 0, v[152:153]
	s_mov_b32 m0, s59
	ds_read_b128 v[184:187], v182 offset:16384
	ds_read_b128 v[188:191], v182 offset:17408
	ds_read_b128 v[192:195], v182 offset:18432
	ds_read_b128 v[196:199], v182 offset:19456
	ds_read_b128 v[200:203], v182 offset:20480
	ds_read_b128 v[204:207], v182 offset:21504
	ds_read_b128 v[208:211], v182 offset:22528
	ds_read_b128 v[212:215], v182 offset:23552
	global_load_lds_dwordx4 v[216:217], off
	s_add_i32 m0, s59, 0x2000
	s_add_u32 s60, s36, 0x40000
	v_lshl_add_u64 v[218:219], s[36:37], 0, v[156:157]
	s_addc_u32 s61, s37, 0
	s_add_i32 s59, s52, s43
	global_load_lds_dwordx4 v[218:219], off
	v_lshl_add_u64 v[220:221], s[60:61], 0, v[152:153]
	s_mov_b32 m0, s59
	v_lshl_add_u64 v[222:223], s[38:39], 0, v[154:155]
	global_load_lds_dwordx4 v[220:221], off
	v_lshl_add_u64 v[220:221], s[60:61], 0, v[156:157]
	s_add_i32 m0, s59, 0x2000
	s_nop 0
	global_load_lds_dwordx4 v[220:221], off
	v_lshl_add_u64 v[220:221], s[38:39], 0, v[150:151]
	s_mov_b32 m0, s35
	s_nop 0
	global_load_lds_dwordx4 v[220:221], off
	s_mov_b32 m0, s44
	s_nop 0
	global_load_lds_dwordx4 v[222:223], off
	s_waitcnt vmcnt(8)
	s_waitcnt lgkmcnt(0)
	s_barrier
	s_setprio 1
	s_waitcnt lgkmcnt(0)
	v_mfma_f32_16x16x32_bf16 v[6:9], v[130:133], v[184:187], v[6:9]
	v_mfma_f32_16x16x32_bf16 v[2:5], v[138:141], v[184:187], v[2:5]
	v_mfma_f32_16x16x32_bf16 v[22:25], v[130:133], v[192:195], v[22:25]
	v_mfma_f32_16x16x32_bf16 v[18:21], v[138:141], v[192:195], v[18:21]
	v_mfma_f32_16x16x32_bf16 v[38:41], v[130:133], v[200:203], v[38:41]
	v_mfma_f32_16x16x32_bf16 v[34:37], v[138:141], v[200:203], v[34:37]
	v_mfma_f32_16x16x32_bf16 v[54:57], v[130:133], v[208:211], v[54:57]
	v_mfma_f32_16x16x32_bf16 v[50:53], v[138:141], v[208:211], v[50:53]
	v_mfma_f32_16x16x32_bf16 v[6:9], v[134:137], v[188:191], v[6:9]
	v_mfma_f32_16x16x32_bf16 v[2:5], v[142:145], v[188:191], v[2:5]
	v_mfma_f32_16x16x32_bf16 v[22:25], v[134:137], v[196:199], v[22:25]
	v_mfma_f32_16x16x32_bf16 v[18:21], v[142:145], v[196:199], v[18:21]
	v_mfma_f32_16x16x32_bf16 v[38:41], v[134:137], v[204:207], v[38:41]
	v_mfma_f32_16x16x32_bf16 v[34:37], v[142:145], v[204:207], v[34:37]
	v_mfma_f32_16x16x32_bf16 v[54:57], v[134:137], v[212:215], v[54:57]
	v_mfma_f32_16x16x32_bf16 v[50:53], v[142:145], v[212:215], v[50:53]
	s_setprio 0
	s_setprio 1
	v_mfma_f32_16x16x32_bf16 v[14:17], v[146:149], v[184:187], v[14:17]
	v_mfma_f32_16x16x32_bf16 v[10:13], v[170:173], v[184:187], v[10:13]
	v_mfma_f32_16x16x32_bf16 v[30:33], v[146:149], v[192:195], v[30:33]
	v_mfma_f32_16x16x32_bf16 v[26:29], v[170:173], v[192:195], v[26:29]
	v_mfma_f32_16x16x32_bf16 v[46:49], v[146:149], v[200:203], v[46:49]
	v_mfma_f32_16x16x32_bf16 v[42:45], v[170:173], v[200:203], v[42:45]
	v_mfma_f32_16x16x32_bf16 v[62:65], v[146:149], v[208:211], v[62:65]
	v_mfma_f32_16x16x32_bf16 v[58:61], v[170:173], v[208:211], v[58:61]
	v_mfma_f32_16x16x32_bf16 v[14:17], v[166:169], v[188:191], v[14:17]
	v_mfma_f32_16x16x32_bf16 v[10:13], v[174:177], v[188:191], v[10:13]
	v_mfma_f32_16x16x32_bf16 v[30:33], v[166:169], v[196:199], v[30:33]
	v_mfma_f32_16x16x32_bf16 v[26:29], v[174:177], v[196:199], v[26:29]
	v_mfma_f32_16x16x32_bf16 v[46:49], v[166:169], v[204:207], v[46:49]
	v_mfma_f32_16x16x32_bf16 v[42:45], v[174:177], v[204:207], v[42:45]
	v_mfma_f32_16x16x32_bf16 v[62:65], v[166:169], v[212:215], v[62:65]
	v_mfma_f32_16x16x32_bf16 v[58:61], v[174:177], v[212:215], v[58:61]
	s_setprio 0
	s_barrier
	s_cmp_lg_u32 s58, 12
	s_cbranch_scc1 .Lmy_p5_nox
	v_lshl_or_b32 v183, s53, 8, v179
	v_lshl_add_u32 v226, s34, 8, v1
	v_lshlrev_b32_e32 v183, 1, v183
	v_lshl_add_u32 v183, v226, 11, v183
	global_load_dwordx4 v[226:229], v183, s[12:13] nt
	global_load_dwordx4 v[230:233], v183, s[12:13] offset:256 nt
	v_add_u32_e32 v183, 0x8000, v183
	global_load_dwordx4 v[234:237], v183, s[12:13] nt
	global_load_dwordx4 v[238:241], v183, s[12:13] offset:256 nt
	v_add_u32_e32 v183, 0x8000, v183
	global_load_dwordx4 v[242:245], v183, s[12:13] nt
	global_load_dwordx4 v[246:249], v183, s[12:13] offset:256 nt
	v_add_u32_e32 v183, 0x8000, v183
	global_load_dwordx4 v[250:253], v183, s[12:13] nt
	global_load_dwordx4 v[162:165], v183, s[12:13] offset:256 nt

.LBB0_774:
	v_lshl_or_b32 v132, s53, 8, v179
	v_lshl_add_u32 v130, s34, 8, v1
	v_ashrrev_i32_e32 v133, 31, v132
	v_lshlrev_b64 v[166:167], 1, v[132:133]
	v_ashrrev_i32_e32 v131, 31, v130
	v_lshl_add_u64 v[168:169], s[12:13], 0, v[166:167]
	v_lshlrev_b64 v[170:171], 11, v[130:131]
	v_lshl_add_u64 v[132:133], v[168:169], 0, v[170:171]
	s_waitcnt vmcnt(8)
	v_mov_b32_e32 v184, v226
	v_mov_b32_e32 v185, v227
	v_mov_b32_e32 v186, v228
	v_mov_b32_e32 v187, v229
	v_mov_b32_e32 v188, v230
	v_mov_b32_e32 v189, v231
	v_mov_b32_e32 v190, v232
	v_mov_b32_e32 v191, v233
	v_or_b32_e32 v132, 16, v130
	v_or_b32_e32 v134, 32, v130
	v_or_b32_e32 v130, 48, v130
	v_ashrrev_i32_e32 v133, 31, v132
	v_ashrrev_i32_e32 v135, 31, v134
	v_ashrrev_i32_e32 v131, 31, v130
	v_lshlrev_b64 v[176:177], 11, v[132:133]
	v_lshlrev_b64 v[174:175], 11, v[134:135]
	v_lshlrev_b64 v[172:173], 11, v[130:131]
	v_lshl_add_u64 v[130:131], v[168:169], 0, v[176:177]
	v_lshl_add_u64 v[132:133], v[168:169], 0, v[174:175]
	v_lshl_add_u64 v[196:197], v[168:169], 0, v[172:173]
	v_mov_b32_e32 v192, v234
	v_mov_b32_e32 v193, v235
	v_mov_b32_e32 v194, v236
	v_mov_b32_e32 v195, v237
	v_mov_b32_e32 v146, v238
	v_mov_b32_e32 v147, v239
	v_mov_b32_e32 v148, v240
	v_mov_b32_e32 v149, v241
	v_mov_b32_e32 v142, v242
	v_mov_b32_e32 v143, v243
	v_mov_b32_e32 v144, v244
	v_mov_b32_e32 v145, v245
	v_mov_b32_e32 v138, v246
	v_mov_b32_e32 v139, v247
	v_mov_b32_e32 v140, v248
	v_mov_b32_e32 v141, v249
	v_mov_b32_e32 v134, v250
	v_mov_b32_e32 v135, v251
	v_mov_b32_e32 v136, v252
	v_mov_b32_e32 v137, v253
	s_nop 0
	v_mov_b32_e32 v130, v162
	v_mov_b32_e32 v131, v163
	v_mov_b32_e32 v132, v164
	v_mov_b32_e32 v133, v165
	s_andn2_b64 vcc, exec, s[2:3]
	s_mov_b64 s[0:1], -1
	s_waitcnt vmcnt(8)
	v_lshlrev_b32_e32 v183, 16, v184
	v_and_b32_e32 v184, 0xffff0000, v184
	v_lshlrev_b32_e32 v197, 16, v186
	v_lshlrev_b32_e32 v196, 16, v185
	v_and_b32_e32 v185, 0xffff0000, v185
	v_and_b32_e32 v186, 0xffff0000, v186
	v_lshlrev_b32_e32 v198, 16, v187
	v_and_b32_e32 v187, 0xffff0000, v187
	v_lshlrev_b32_e32 v202, 16, v191
	v_and_b32_e32 v203, 0xffff0000, v191
	v_mul_f32_e32 v183, 0xbfb8aa3b, v183
	v_mul_f32_e32 v191, 0xbfb8aa3b, v197
	v_mul_f32_e32 v184, 0xbfb8aa3b, v184
	v_lshlrev_b32_e32 v199, 16, v188
	v_and_b32_e32 v188, 0xffff0000, v188
	v_lshlrev_b32_e32 v200, 16, v189
	v_and_b32_e32 v201, 0xffff0000, v189
	v_lshlrev_b32_e32 v189, 16, v190
	v_mul_f32_e32 v186, 0xbfb8aa3b, v186
	v_mul_f32_e32 v196, 0xbfb8aa3b, v196
	v_mul_f32_e32 v197, 0xbfb8aa3b, v198
	v_mul_f32_e32 v185, 0xbfb8aa3b, v185
	v_mul_f32_e32 v187, 0xbfb8aa3b, v187
	v_exp_f32_e32 v183, v183
	v_exp_f32_e32 v191, v191
	v_exp_f32_e32 v184, v184
	v_mul_f32_e32 v189, 0xbfb8aa3b, v189
	v_mul_f32_e32 v188, 0xbfb8aa3b, v188
	v_exp_f32_e32 v186, v186
	v_exp_f32_e32 v196, v196
	v_exp_f32_e32 v197, v197
	v_exp_f32_e32 v185, v185
	v_exp_f32_e32 v187, v187
	v_and_b32_e32 v190, 0xffff0000, v190
	v_exp_f32_e32 v189, v189
	v_exp_f32_e32 v188, v188
	v_mul_f32_e32 v190, 0xbfb8aa3b, v190
	v_mul_f32_e32 v198, 0xbfb8aa3b, v199
	v_exp_f32_e32 v199, v190
	v_add_f32_e32 v183, 1.0, v183
	v_add_f32_e32 v190, 1.0, v191
	v_add_f32_e32 v191, 1.0, v184
	v_add_f32_e32 v204, 1.0, v186
	v_add_f32_e32 v196, 1.0, v196
	v_add_f32_e32 v197, 1.0, v197
	v_add_f32_e32 v205, 1.0, v185
	v_add_f32_e32 v206, 1.0, v187
	v_rcp_f32_e32 v184, v183
	v_rcp_f32_e32 v185, v191
	v_add_f32_e32 v207, 1.0, v189
	v_add_f32_e32 v208, 1.0, v188
	v_rcp_f32_e32 v186, v190
	v_rcp_f32_e32 v187, v204
	v_rcp_f32_e32 v188, v196
	v_rcp_f32_e32 v190, v197
	v_rcp_f32_e32 v189, v205
	v_rcp_f32_e32 v191, v206
	v_pk_mul_f32 v[126:127], v[126:127], v[184:185]
	v_exp_f32_e32 v198, v198
	v_pk_mul_f32 v[128:129], v[128:129], v[188:189]
	v_pk_mul_f32 v[184:185], v[124:125], v[190:191]
	v_pk_mul_f32 v[124:125], v[122:123], v[186:187]
	v_cvt_pk_bf16_f32 v122, v126, v127
	v_mul_f32_e32 v127, 0xbfb8aa3b, v202
	v_cvt_pk_bf16_f32 v123, v128, v129
	v_mul_f32_e32 v126, 0xbfb8aa3b, v200
	v_exp_f32_e32 v127, v127
	v_mul_f32_e32 v128, 0xbfb8aa3b, v201
	v_exp_f32_e32 v126, v126
	v_exp_f32_e32 v129, v128
	v_mul_f32_e32 v128, 0xbfb8aa3b, v203
	v_cvt_pk_bf16_f32 v124, v124, v125
	v_cvt_pk_bf16_f32 v125, v184, v185
	v_exp_f32_e32 v184, v128
	v_add_f32_e32 v127, 1.0, v127
	v_add_f32_e32 v126, 1.0, v126
	v_rcp_f32_e32 v128, v127
	v_add_f32_e32 v127, 1.0, v129
	v_add_f32_e32 v198, 1.0, v198
	v_add_f32_e32 v183, 1.0, v199
	v_rcp_f32_e32 v126, v126
	v_rcp_f32_e32 v127, v127
	v_add_f32_e32 v129, 1.0, v184
	v_rcp_f32_e32 v196, v198
	v_rcp_f32_e32 v198, v207
	v_rcp_f32_e32 v129, v129
	v_rcp_f32_e32 v199, v183
	v_pk_mul_f32 v[120:121], v[120:121], v[126:127]
	v_rcp_f32_e32 v197, v208
	v_pk_mul_f32 v[126:127], v[116:117], v[128:129]
	v_pk_mul_f32 v[116:117], v[114:115], v[198:199]
	v_cvt_pk_bf16_f32 v115, v120, v121
	v_lshlrev_b32_e32 v121, 16, v193
	v_cvt_pk_bf16_f32 v116, v116, v117
	v_cvt_pk_bf16_f32 v117, v126, v127
	v_and_b32_e32 v126, 0xffff0000, v194
	v_lshlrev_b32_e32 v128, 16, v195
	v_mul_f32_e32 v121, 0xbfb8aa3b, v121
	v_mul_f32_e32 v126, 0xbfb8aa3b, v126
	v_exp_f32_e32 v121, v121
	v_mul_f32_e32 v128, 0xbfb8aa3b, v128
	v_exp_f32_e32 v126, v126
	v_exp_f32_e32 v128, v128
	v_pk_mul_f32 v[118:119], v[118:119], v[196:197]
	v_and_b32_e32 v127, 0xffff0000, v193
	v_cvt_pk_bf16_f32 v114, v118, v119
	v_lshlrev_b32_e32 v118, 16, v192
	v_and_b32_e32 v119, 0xffff0000, v192
	v_lshlrev_b32_e32 v120, 16, v194
	v_and_b32_e32 v129, 0xffff0000, v195
	v_add_f32_e32 v121, 1.0, v121
	v_mul_f32_e32 v127, 0xbfb8aa3b, v127
	v_mul_f32_e32 v118, 0xbfb8aa3b, v118
	v_mul_f32_e32 v120, 0xbfb8aa3b, v120
	v_mul_f32_e32 v119, 0xbfb8aa3b, v119
	v_add_f32_e32 v183, 1.0, v126
	v_rcp_f32_e32 v126, v121
	v_add_f32_e32 v121, 1.0, v128
	v_exp_f32_e32 v127, v127
	v_mul_f32_e32 v128, 0xbfb8aa3b, v129
	v_exp_f32_e32 v118, v118
	v_exp_f32_e32 v120, v120
	v_exp_f32_e32 v119, v119
	v_exp_f32_e32 v129, v128
	v_rcp_f32_e32 v128, v121
	v_add_f32_e32 v121, 1.0, v127
	v_add_f32_e32 v118, 1.0, v118
	v_add_f32_e32 v120, 1.0, v120
	v_add_f32_e32 v119, 1.0, v119
	v_rcp_f32_e32 v127, v121
	v_add_f32_e32 v121, 1.0, v129
	v_rcp_f32_e32 v118, v118
	v_rcp_f32_e32 v120, v120
	v_rcp_f32_e32 v119, v119
	v_rcp_f32_e32 v129, v121
	v_rcp_f32_e32 v121, v183
	v_pk_mul_f32 v[112:113], v[112:113], v[126:127]
	v_pk_mul_f32 v[110:111], v[110:111], v[118:119]
	v_pk_mul_f32 v[118:119], v[108:109], v[128:129]
	v_pk_mul_f32 v[108:109], v[106:107], v[120:121]
	v_cvt_pk_bf16_f32 v107, v112, v113
	v_lshlrev_b32_e32 v113, 16, v147
	v_cvt_pk_bf16_f32 v108, v108, v109
	v_cvt_pk_bf16_f32 v109, v118, v119
	v_and_b32_e32 v118, 0xffff0000, v148
	v_lshlrev_b32_e32 v120, 16, v149
	v_mul_f32_e32 v113, 0xbfb8aa3b, v113
	v_mul_f32_e32 v118, 0xbfb8aa3b, v118
	v_exp_f32_e32 v113, v113
	v_mul_f32_e32 v120, 0xbfb8aa3b, v120
	v_exp_f32_e32 v118, v118
	v_exp_f32_e32 v120, v120
	v_and_b32_e32 v119, 0xffff0000, v147
	v_cvt_pk_bf16_f32 v106, v110, v111
	v_lshlrev_b32_e32 v110, 16, v146
	v_and_b32_e32 v111, 0xffff0000, v146
	v_lshlrev_b32_e32 v112, 16, v148
	v_and_b32_e32 v121, 0xffff0000, v149
	v_add_f32_e32 v113, 1.0, v113
	v_mul_f32_e32 v119, 0xbfb8aa3b, v119
	v_mul_f32_e32 v110, 0xbfb8aa3b, v110
	v_mul_f32_e32 v112, 0xbfb8aa3b, v112
	v_mul_f32_e32 v111, 0xbfb8aa3b, v111
	v_add_f32_e32 v126, 1.0, v118
	v_rcp_f32_e32 v118, v113
	v_add_f32_e32 v113, 1.0, v120
	v_exp_f32_e32 v119, v119
	v_mul_f32_e32 v120, 0xbfb8aa3b, v121
	v_exp_f32_e32 v110, v110
	v_exp_f32_e32 v112, v112
	v_exp_f32_e32 v111, v111
	v_exp_f32_e32 v121, v120
	v_rcp_f32_e32 v120, v113
	v_add_f32_e32 v113, 1.0, v119
	v_add_f32_e32 v110, 1.0, v110
	v_add_f32_e32 v112, 1.0, v112
	v_add_f32_e32 v111, 1.0, v111
	v_rcp_f32_e32 v119, v113
	v_add_f32_e32 v113, 1.0, v121
	v_rcp_f32_e32 v110, v110
	v_rcp_f32_e32 v112, v112
	v_rcp_f32_e32 v111, v111
	v_rcp_f32_e32 v121, v113
	v_rcp_f32_e32 v113, v126
	v_pk_mul_f32 v[104:105], v[104:105], v[118:119]
	v_pk_mul_f32 v[102:103], v[102:103], v[110:111]
	v_pk_mul_f32 v[110:111], v[100:101], v[120:121]
	v_pk_mul_f32 v[100:101], v[98:99], v[112:113]
	v_cvt_pk_bf16_f32 v99, v104, v105
	v_lshlrev_b32_e32 v105, 16, v143
	v_cvt_pk_bf16_f32 v100, v100, v101
	v_cvt_pk_bf16_f32 v101, v110, v111
	v_and_b32_e32 v110, 0xffff0000, v144
	v_lshlrev_b32_e32 v112, 16, v145
	v_mul_f32_e32 v105, 0xbfb8aa3b, v105
	v_mul_f32_e32 v110, 0xbfb8aa3b, v110
	v_exp_f32_e32 v105, v105
	v_mul_f32_e32 v112, 0xbfb8aa3b, v112
	v_exp_f32_e32 v110, v110
	v_exp_f32_e32 v112, v112
	v_and_b32_e32 v111, 0xffff0000, v143
	v_cvt_pk_bf16_f32 v98, v102, v103
	v_lshlrev_b32_e32 v102, 16, v142
	v_and_b32_e32 v103, 0xffff0000, v142
	v_lshlrev_b32_e32 v104, 16, v144
	v_and_b32_e32 v113, 0xffff0000, v145
	v_add_f32_e32 v105, 1.0, v105
	v_mul_f32_e32 v111, 0xbfb8aa3b, v111
	v_mul_f32_e32 v102, 0xbfb8aa3b, v102
	v_mul_f32_e32 v104, 0xbfb8aa3b, v104
	v_mul_f32_e32 v103, 0xbfb8aa3b, v103
	v_add_f32_e32 v118, 1.0, v110
	v_rcp_f32_e32 v110, v105
	v_add_f32_e32 v105, 1.0, v112
	v_exp_f32_e32 v111, v111
	v_mul_f32_e32 v112, 0xbfb8aa3b, v113
	v_exp_f32_e32 v102, v102
	v_exp_f32_e32 v104, v104
	v_exp_f32_e32 v103, v103
	v_exp_f32_e32 v113, v112
	v_rcp_f32_e32 v112, v105
	v_add_f32_e32 v105, 1.0, v111
	v_add_f32_e32 v102, 1.0, v102
	v_add_f32_e32 v104, 1.0, v104
	v_add_f32_e32 v103, 1.0, v103
	v_rcp_f32_e32 v111, v105
	v_add_f32_e32 v105, 1.0, v113
	v_rcp_f32_e32 v102, v102
	v_rcp_f32_e32 v104, v104
	v_rcp_f32_e32 v103, v103
	v_rcp_f32_e32 v113, v105
	v_rcp_f32_e32 v105, v118
	v_pk_mul_f32 v[96:97], v[96:97], v[110:111]
	v_pk_mul_f32 v[94:95], v[94:95], v[102:103]
	v_pk_mul_f32 v[102:103], v[92:93], v[112:113]
	v_pk_mul_f32 v[92:93], v[90:91], v[104:105]
	v_cvt_pk_bf16_f32 v91, v96, v97
	v_lshlrev_b32_e32 v97, 16, v139
	v_cvt_pk_bf16_f32 v92, v92, v93
	v_cvt_pk_bf16_f32 v93, v102, v103
	v_and_b32_e32 v102, 0xffff0000, v140
	v_lshlrev_b32_e32 v104, 16, v141
	v_mul_f32_e32 v97, 0xbfb8aa3b, v97
	v_mul_f32_e32 v102, 0xbfb8aa3b, v102
	v_exp_f32_e32 v97, v97
	v_mul_f32_e32 v104, 0xbfb8aa3b, v104
	v_exp_f32_e32 v102, v102
	v_exp_f32_e32 v104, v104
	v_and_b32_e32 v103, 0xffff0000, v139
	v_and_b32_e32 v105, 0xffff0000, v141
	v_add_f32_e32 v97, 1.0, v97
	v_mul_f32_e32 v103, 0xbfb8aa3b, v103
	v_cvt_pk_bf16_f32 v90, v94, v95
	v_lshlrev_b32_e32 v94, 16, v138
	v_and_b32_e32 v95, 0xffff0000, v138
	v_add_f32_e32 v110, 1.0, v102
	v_rcp_f32_e32 v102, v97
	v_add_f32_e32 v97, 1.0, v104
	v_exp_f32_e32 v103, v103
	v_mul_f32_e32 v104, 0xbfb8aa3b, v105
	v_mul_f32_e32 v94, 0xbfb8aa3b, v94
	v_mul_f32_e32 v95, 0xbfb8aa3b, v95
	v_exp_f32_e32 v105, v104
	v_lshlrev_b32_e32 v96, 16, v140
	v_exp_f32_e32 v94, v94
	v_exp_f32_e32 v95, v95
	v_mul_f32_e32 v96, 0xbfb8aa3b, v96
	v_exp_f32_e32 v96, v96
	v_rcp_f32_e32 v104, v97
	v_add_f32_e32 v97, 1.0, v103
	v_rcp_f32_e32 v103, v97
	v_add_f32_e32 v97, 1.0, v105
	v_add_f32_e32 v94, 1.0, v94
	v_add_f32_e32 v95, 1.0, v95
	v_rcp_f32_e32 v105, v97
	v_rcp_f32_e32 v94, v94
	v_rcp_f32_e32 v95, v95
	v_add_f32_e32 v96, 1.0, v96
	v_rcp_f32_e32 v96, v96
	v_rcp_f32_e32 v97, v110
	v_pk_mul_f32 v[84:85], v[84:85], v[104:105]
	v_pk_mul_f32 v[88:89], v[88:89], v[102:103]
	v_pk_mul_f32 v[86:87], v[86:87], v[94:95]
	v_cvt_pk_bf16_f32 v105, v84, v85
	v_lshlrev_b32_e32 v85, 16, v135
	v_cvt_pk_bf16_f32 v102, v86, v87
	v_cvt_pk_bf16_f32 v103, v88, v89
	v_and_b32_e32 v86, 0xffff0000, v136
	v_lshlrev_b32_e32 v88, 16, v137
	v_mul_f32_e32 v85, 0xbfb8aa3b, v85
	v_pk_mul_f32 v[82:83], v[82:83], v[96:97]
	v_and_b32_e32 v87, 0xffff0000, v135
	v_mul_f32_e32 v86, 0xbfb8aa3b, v86
	v_exp_f32_e32 v85, v85
	v_mul_f32_e32 v88, 0xbfb8aa3b, v88
	v_cvt_pk_bf16_f32 v104, v82, v83
	v_lshlrev_b32_e32 v82, 16, v134
	v_and_b32_e32 v83, 0xffff0000, v134
	v_exp_f32_e32 v86, v86
	v_exp_f32_e32 v88, v88
	v_mul_f32_e32 v87, 0xbfb8aa3b, v87
	v_mul_f32_e32 v82, 0xbfb8aa3b, v82
	v_mul_f32_e32 v83, 0xbfb8aa3b, v83
	v_exp_f32_e32 v87, v87
	v_exp_f32_e32 v82, v82
	v_exp_f32_e32 v83, v83
	v_and_b32_e32 v89, 0xffff0000, v137
	v_add_f32_e32 v85, 1.0, v85
	v_add_f32_e32 v94, 1.0, v86
	v_rcp_f32_e32 v86, v85
	v_add_f32_e32 v85, 1.0, v88
	v_mul_f32_e32 v88, 0xbfb8aa3b, v89
	v_exp_f32_e32 v89, v88
	v_rcp_f32_e32 v88, v85
	v_add_f32_e32 v85, 1.0, v87
	v_add_f32_e32 v82, 1.0, v82
	v_add_f32_e32 v83, 1.0, v83
	v_rcp_f32_e32 v87, v85
	v_rcp_f32_e32 v82, v82
	v_rcp_f32_e32 v83, v83
	v_add_f32_e32 v85, 1.0, v89
	v_pk_mul_f32 v[80:81], v[80:81], v[86:87]
	v_lshl_add_u64 v[86:87], v[170:171], 0, s[18:19]
	v_pk_mul_f32 v[78:79], v[78:79], v[82:83]
	v_lshl_add_u64 v[82:83], v[168:169], 0, v[86:87]
	global_load_dwordx4 v[110:113], v[82:83], off offset:256 nt
	global_load_dwordx4 v[126:129], v[82:83], off nt
	v_rcp_f32_e32 v89, v85
	v_lshlrev_b32_e32 v84, 16, v136
	v_mul_f32_e32 v84, 0xbfb8aa3b, v84
	v_exp_f32_e32 v84, v84
	v_pk_mul_f32 v[76:77], v[76:77], v[88:89]
	v_cvt_pk_bf16_f32 v118, v78, v79
	v_cvt_pk_bf16_f32 v121, v76, v77
	v_lshlrev_b32_e32 v77, 16, v131
	v_cvt_pk_bf16_f32 v119, v80, v81
	v_and_b32_e32 v78, 0xffff0000, v132
	v_lshlrev_b32_e32 v80, 16, v133
	v_mul_f32_e32 v77, 0xbfb8aa3b, v77
	v_add_f32_e32 v84, 1.0, v84
	v_mul_f32_e32 v78, 0xbfb8aa3b, v78
	v_exp_f32_e32 v77, v77
	v_mul_f32_e32 v80, 0xbfb8aa3b, v80
	v_rcp_f32_e32 v84, v84
	v_rcp_f32_e32 v85, v94
	v_exp_f32_e32 v78, v78
	v_exp_f32_e32 v80, v80
	v_and_b32_e32 v79, 0xffff0000, v131
	v_lshlrev_b32_e32 v76, 16, v132
	v_and_b32_e32 v81, 0xffff0000, v133
	v_add_f32_e32 v77, 1.0, v77
	v_mul_f32_e32 v79, 0xbfb8aa3b, v79
	v_pk_mul_f32 v[74:75], v[74:75], v[84:85]
	v_mul_f32_e32 v76, 0xbfb8aa3b, v76
	v_add_f32_e32 v84, 1.0, v78
	v_rcp_f32_e32 v78, v77
	v_add_f32_e32 v77, 1.0, v80
	v_exp_f32_e32 v79, v79
	v_mul_f32_e32 v80, 0xbfb8aa3b, v81
	v_exp_f32_e32 v76, v76
	v_exp_f32_e32 v81, v80
	v_rcp_f32_e32 v80, v77
	v_add_f32_e32 v77, 1.0, v79
	v_add_f32_e32 v76, 1.0, v76
	v_rcp_f32_e32 v79, v77
	v_add_f32_e32 v77, 1.0, v81
	v_rcp_f32_e32 v76, v76
	v_rcp_f32_e32 v81, v77
	v_rcp_f32_e32 v77, v84
	v_lshl_add_u64 v[88:89], v[170:171], 0, s[20:21]
	v_cvt_pk_bf16_f32 v120, v74, v75
	v_lshlrev_b32_e32 v74, 16, v130
	v_pk_mul_f32 v[66:67], v[66:67], v[76:77]
	v_and_b32_e32 v75, 0xffff0000, v130
	v_cvt_pk_bf16_f32 v132, v66, v67
	v_lshl_add_u64 v[66:67], v[168:169], 0, v[88:89]
	global_load_dwordx4 v[134:137], v[66:67], off offset:256 nt
	global_load_dwordx4 v[82:85], v[66:67], off nt
	v_mul_f32_e32 v74, 0xbfb8aa3b, v74
	v_mul_f32_e32 v75, 0xbfb8aa3b, v75
	v_exp_f32_e32 v74, v74
	v_exp_f32_e32 v75, v75
	v_lshl_add_u64 v[94:95], v[170:171], 0, s[22:23]
	v_lshl_add_u64 v[66:67], v[168:169], 0, v[94:95]
	v_add_f32_e32 v74, 1.0, v74
	v_add_f32_e32 v75, 1.0, v75
	v_rcp_f32_e32 v74, v74
	v_rcp_f32_e32 v75, v75
	v_lshl_add_u64 v[96:97], v[170:171], 0, s[8:9]
	v_lshl_add_u64 v[138:139], s[6:7], 0, v[170:171]
	v_pk_mul_f32 v[72:73], v[72:73], v[78:79]
	v_pk_mul_f32 v[70:71], v[70:71], v[74:75]
	v_pk_mul_f32 v[68:69], v[68:69], v[80:81]
	global_load_dwordx4 v[78:81], v[66:67], off offset:256 nt
	global_load_dwordx4 v[74:77], v[66:67], off nt
	v_lshl_add_u64 v[66:67], v[168:169], 0, v[96:97]
	v_lshl_add_u64 v[138:139], v[138:139], 0, v[166:167]
	v_cvt_pk_bf16_f32 v130, v70, v71
	v_cvt_pk_bf16_f32 v131, v72, v73
	v_cvt_pk_bf16_f32 v133, v68, v69
	global_load_dwordx4 v[70:73], v[66:67], off offset:256 nt
	s_nop 0
	global_load_dwordx4 v[66:69], v[66:67], off nt
	s_nop 0
	global_store_dwordx4 v[138:139], v[122:125], off nt
	global_store_dwordx4 v[138:139], v[114:117], off offset:256 nt
	s_nop 1
	v_lshl_add_u64 v[114:115], s[6:7], 0, v[176:177]
	v_lshl_add_u64 v[114:115], v[114:115], 0, v[166:167]
	global_store_dwordx4 v[114:115], v[106:109], off nt
	global_store_dwordx4 v[114:115], v[98:101], off offset:256 nt
	s_nop 1
	v_lshl_add_u64 v[98:99], s[6:7], 0, v[174:175]
	v_lshl_add_u64 v[98:99], v[98:99], 0, v[166:167]
	global_store_dwordx4 v[98:99], v[90:93], off nt
	global_store_dwordx4 v[98:99], v[102:105], off offset:256 nt
	s_waitcnt vmcnt(13)
	v_lshlrev_b32_e32 v98, 16, v111
	v_lshlrev_b32_e32 v92, 16, v110
	v_and_b32_e32 v93, 0xffff0000, v110
	v_and_b32_e32 v99, 0xffff0000, v111
	v_mul_f32_e32 v92, 0xbfb8aa3b, v92
	v_mul_f32_e32 v93, 0xbfb8aa3b, v93
	v_mul_f32_e32 v98, 0xbfb8aa3b, v98
	v_mul_f32_e32 v99, 0xbfb8aa3b, v99
	v_exp_f32_e32 v92, v92
	v_exp_f32_e32 v93, v93
	v_exp_f32_e32 v98, v98
	v_exp_f32_e32 v99, v99
	v_lshl_add_u64 v[90:91], s[6:7], 0, v[172:173]
	v_lshl_add_u64 v[90:91], v[90:91], 0, v[166:167]
	global_store_dwordx4 v[90:91], v[118:121], off nt
	v_lshlrev_b32_e32 v100, 16, v112
	global_store_dwordx4 v[90:91], v[130:133], off offset:256 nt
	v_and_b32_e32 v91, 0xffff0000, v112
	v_add_f32_e32 v92, 1.0, v92
	v_add_f32_e32 v93, 1.0, v93
	v_add_f32_e32 v98, 1.0, v98
	v_add_f32_e32 v99, 1.0, v99
	v_mul_f32_e32 v100, 0xbfb8aa3b, v100
	v_mul_f32_e32 v91, 0xbfb8aa3b, v91
	v_rcp_f32_e32 v92, v92
	v_rcp_f32_e32 v93, v93
	v_rcp_f32_e32 v98, v98
	v_rcp_f32_e32 v99, v99
	v_exp_f32_e32 v100, v100
	v_exp_f32_e32 v91, v91
	v_pk_mul_f32 v[62:63], v[62:63], v[92:93]
	v_pk_mul_f32 v[64:65], v[64:65], v[98:99]
	v_add_f32_e32 v90, 1.0, v100
	v_add_f32_e32 v91, 1.0, v91
	v_rcp_f32_e32 v90, v90
	v_rcp_f32_e32 v91, v91
	v_cvt_pk_bf16_f32 v62, v62, v63
	v_cvt_pk_bf16_f32 v63, v64, v65
	s_waitcnt vmcnt(14)
	v_lshlrev_b32_e32 v64, 16, v126
	v_mul_f32_e32 v64, 0xbfb8aa3b, v64
	v_exp_f32_e32 v65, v64
	v_and_b32_e32 v64, 0xffff0000, v126
	v_mul_f32_e32 v64, 0xbfb8aa3b, v64
	v_pk_mul_f32 v[58:59], v[58:59], v[90:91]
	v_exp_f32_e32 v90, v64
	v_lshlrev_b32_e32 v92, 16, v113
	v_and_b32_e32 v93, 0xffff0000, v113
	v_mul_f32_e32 v92, 0xbfb8aa3b, v92
	v_mul_f32_e32 v93, 0xbfb8aa3b, v93
	v_cvt_pk_bf16_f32 v64, v58, v59
	v_add_f32_e32 v58, 1.0, v65
	v_lshlrev_b32_e32 v65, 16, v127
	v_exp_f32_e32 v92, v92
	v_exp_f32_e32 v93, v93
	v_add_f32_e32 v59, 1.0, v90
	v_mul_f32_e32 v65, 0xbfb8aa3b, v65
	v_and_b32_e32 v90, 0xffff0000, v127
	v_exp_f32_e32 v65, v65
	v_mul_f32_e32 v90, 0xbfb8aa3b, v90
	v_exp_f32_e32 v91, v90
	v_rcp_f32_e32 v58, v58
	v_rcp_f32_e32 v59, v59
	v_add_f32_e32 v92, 1.0, v92
	v_add_f32_e32 v93, 1.0, v93
	v_rcp_f32_e32 v92, v92
	v_rcp_f32_e32 v93, v93
	v_add_f32_e32 v65, 1.0, v65
	v_rcp_f32_e32 v90, v65
	v_add_f32_e32 v65, 1.0, v91
	v_rcp_f32_e32 v91, v65
	v_lshlrev_b32_e32 v65, 16, v128
	v_pk_mul_f32 v[54:55], v[54:55], v[58:59]
	v_and_b32_e32 v59, 0xffff0000, v128
	v_mul_f32_e32 v65, 0xbfb8aa3b, v65
	v_mul_f32_e32 v59, 0xbfb8aa3b, v59
	v_pk_mul_f32 v[60:61], v[60:61], v[92:93]
	v_exp_f32_e32 v92, v65
	v_exp_f32_e32 v59, v59
	v_pk_mul_f32 v[56:57], v[56:57], v[90:91]
	v_cvt_pk_bf16_f32 v54, v54, v55
	v_add_f32_e32 v58, 1.0, v92
	v_add_f32_e32 v59, 1.0, v59
	v_rcp_f32_e32 v58, v58
	v_rcp_f32_e32 v59, v59
	v_cvt_pk_bf16_f32 v55, v56, v57
	s_waitcnt vmcnt(13)
	v_lshlrev_b32_e32 v56, 16, v134
	v_mul_f32_e32 v56, 0xbfb8aa3b, v56
	v_exp_f32_e32 v57, v56
	v_and_b32_e32 v56, 0xffff0000, v134
	v_mul_f32_e32 v56, 0xbfb8aa3b, v56
	v_pk_mul_f32 v[50:51], v[50:51], v[58:59]
	v_exp_f32_e32 v58, v56
	v_cvt_pk_bf16_f32 v65, v60, v61
	v_lshlrev_b32_e32 v60, 16, v129
	v_and_b32_e32 v61, 0xffff0000, v129
	v_mul_f32_e32 v60, 0xbfb8aa3b, v60
	v_mul_f32_e32 v61, 0xbfb8aa3b, v61
	v_cvt_pk_bf16_f32 v56, v50, v51
	v_add_f32_e32 v50, 1.0, v57
	v_lshlrev_b32_e32 v57, 16, v135
	v_exp_f32_e32 v60, v60
	v_exp_f32_e32 v61, v61
	v_add_f32_e32 v51, 1.0, v58
	v_mul_f32_e32 v57, 0xbfb8aa3b, v57
	v_and_b32_e32 v58, 0xffff0000, v135
	v_exp_f32_e32 v57, v57
	v_mul_f32_e32 v58, 0xbfb8aa3b, v58
	v_exp_f32_e32 v59, v58
	v_rcp_f32_e32 v50, v50
	v_rcp_f32_e32 v51, v51
	v_add_f32_e32 v60, 1.0, v60
	v_add_f32_e32 v61, 1.0, v61
	v_rcp_f32_e32 v60, v60
	v_rcp_f32_e32 v61, v61
	v_add_f32_e32 v57, 1.0, v57
	v_rcp_f32_e32 v58, v57
	v_add_f32_e32 v57, 1.0, v59
	v_rcp_f32_e32 v59, v57
	v_lshlrev_b32_e32 v57, 16, v136
	v_pk_mul_f32 v[46:47], v[46:47], v[50:51]
	v_and_b32_e32 v51, 0xffff0000, v136
	v_mul_f32_e32 v57, 0xbfb8aa3b, v57
	v_mul_f32_e32 v51, 0xbfb8aa3b, v51
	v_pk_mul_f32 v[52:53], v[52:53], v[60:61]
	v_exp_f32_e32 v60, v57
	v_exp_f32_e32 v51, v51
	v_pk_mul_f32 v[48:49], v[48:49], v[58:59]
	v_cvt_pk_bf16_f32 v46, v46, v47
	v_add_f32_e32 v50, 1.0, v60
	v_add_f32_e32 v51, 1.0, v51
	v_rcp_f32_e32 v50, v50
	v_rcp_f32_e32 v51, v51
	v_cvt_pk_bf16_f32 v47, v48, v49
	s_waitcnt vmcnt(12)
	v_lshlrev_b32_e32 v48, 16, v82
	v_mul_f32_e32 v48, 0xbfb8aa3b, v48
	v_exp_f32_e32 v49, v48
	v_and_b32_e32 v48, 0xffff0000, v82
	v_mul_f32_e32 v48, 0xbfb8aa3b, v48
	v_pk_mul_f32 v[42:43], v[42:43], v[50:51]
	v_exp_f32_e32 v50, v48
	v_cvt_pk_bf16_f32 v57, v52, v53
	v_lshlrev_b32_e32 v52, 16, v137
	v_and_b32_e32 v53, 0xffff0000, v137
	v_mul_f32_e32 v52, 0xbfb8aa3b, v52
	v_mul_f32_e32 v53, 0xbfb8aa3b, v53
	v_cvt_pk_bf16_f32 v48, v42, v43
	v_add_f32_e32 v42, 1.0, v49
	v_lshlrev_b32_e32 v49, 16, v83
	v_exp_f32_e32 v52, v52
	v_exp_f32_e32 v53, v53
	v_add_f32_e32 v43, 1.0, v50
	v_mul_f32_e32 v49, 0xbfb8aa3b, v49
	v_and_b32_e32 v50, 0xffff0000, v83
	v_exp_f32_e32 v49, v49
	v_mul_f32_e32 v50, 0xbfb8aa3b, v50
	v_exp_f32_e32 v51, v50
	v_rcp_f32_e32 v42, v42
	v_rcp_f32_e32 v43, v43
	v_add_f32_e32 v52, 1.0, v52
	v_add_f32_e32 v53, 1.0, v53
	v_rcp_f32_e32 v52, v52
	v_rcp_f32_e32 v53, v53
	v_add_f32_e32 v49, 1.0, v49
	v_rcp_f32_e32 v50, v49
	v_add_f32_e32 v49, 1.0, v51
	v_rcp_f32_e32 v51, v49
	v_lshlrev_b32_e32 v49, 16, v84
	v_pk_mul_f32 v[38:39], v[38:39], v[42:43]
	v_and_b32_e32 v43, 0xffff0000, v84
	v_mul_f32_e32 v49, 0xbfb8aa3b, v49
	v_mul_f32_e32 v43, 0xbfb8aa3b, v43
	v_pk_mul_f32 v[44:45], v[44:45], v[52:53]
	v_exp_f32_e32 v52, v49
	v_exp_f32_e32 v43, v43
	v_pk_mul_f32 v[40:41], v[40:41], v[50:51]
	v_cvt_pk_bf16_f32 v38, v38, v39
	v_add_f32_e32 v42, 1.0, v52
	v_add_f32_e32 v43, 1.0, v43
	v_rcp_f32_e32 v42, v42
	v_rcp_f32_e32 v43, v43
	v_cvt_pk_bf16_f32 v39, v40, v41
	s_waitcnt vmcnt(11)
	v_lshlrev_b32_e32 v40, 16, v78
	v_mul_f32_e32 v40, 0xbfb8aa3b, v40
	v_exp_f32_e32 v41, v40
	v_and_b32_e32 v40, 0xffff0000, v78
	v_mul_f32_e32 v40, 0xbfb8aa3b, v40
	v_pk_mul_f32 v[34:35], v[34:35], v[42:43]
	v_exp_f32_e32 v42, v40
	v_cvt_pk_bf16_f32 v49, v44, v45
	v_lshlrev_b32_e32 v44, 16, v85
	v_and_b32_e32 v45, 0xffff0000, v85
	v_mul_f32_e32 v44, 0xbfb8aa3b, v44
	v_mul_f32_e32 v45, 0xbfb8aa3b, v45
	v_cvt_pk_bf16_f32 v40, v34, v35
	v_add_f32_e32 v34, 1.0, v41
	v_lshlrev_b32_e32 v41, 16, v79
	v_exp_f32_e32 v44, v44
	v_exp_f32_e32 v45, v45
	v_add_f32_e32 v35, 1.0, v42
	v_mul_f32_e32 v41, 0xbfb8aa3b, v41
	v_and_b32_e32 v42, 0xffff0000, v79
	v_exp_f32_e32 v41, v41
	v_mul_f32_e32 v42, 0xbfb8aa3b, v42
	v_exp_f32_e32 v43, v42
	v_rcp_f32_e32 v34, v34
	v_rcp_f32_e32 v35, v35
	v_add_f32_e32 v44, 1.0, v44
	v_add_f32_e32 v45, 1.0, v45
	v_rcp_f32_e32 v44, v44
	v_rcp_f32_e32 v45, v45
	v_add_f32_e32 v41, 1.0, v41
	v_rcp_f32_e32 v42, v41
	v_add_f32_e32 v41, 1.0, v43
	v_rcp_f32_e32 v43, v41
	v_lshlrev_b32_e32 v41, 16, v80
	v_pk_mul_f32 v[30:31], v[30:31], v[34:35]
	v_and_b32_e32 v35, 0xffff0000, v80
	v_mul_f32_e32 v41, 0xbfb8aa3b, v41
	v_mul_f32_e32 v35, 0xbfb8aa3b, v35
	v_pk_mul_f32 v[36:37], v[36:37], v[44:45]
	v_exp_f32_e32 v44, v41
	v_exp_f32_e32 v35, v35
	v_pk_mul_f32 v[32:33], v[32:33], v[42:43]
	v_cvt_pk_bf16_f32 v30, v30, v31
	v_add_f32_e32 v34, 1.0, v44
	v_add_f32_e32 v35, 1.0, v35
	v_rcp_f32_e32 v34, v34
	v_rcp_f32_e32 v35, v35
	v_cvt_pk_bf16_f32 v31, v32, v33
	s_waitcnt vmcnt(10)
	v_lshlrev_b32_e32 v32, 16, v74
	v_mul_f32_e32 v32, 0xbfb8aa3b, v32
	v_exp_f32_e32 v33, v32
	v_and_b32_e32 v32, 0xffff0000, v74
	v_mul_f32_e32 v32, 0xbfb8aa3b, v32
	v_pk_mul_f32 v[26:27], v[26:27], v[34:35]
	v_exp_f32_e32 v34, v32
	v_cvt_pk_bf16_f32 v41, v36, v37
	v_lshlrev_b32_e32 v36, 16, v81
	v_and_b32_e32 v37, 0xffff0000, v81
	v_mul_f32_e32 v36, 0xbfb8aa3b, v36
	v_mul_f32_e32 v37, 0xbfb8aa3b, v37
	v_cvt_pk_bf16_f32 v32, v26, v27
	v_add_f32_e32 v26, 1.0, v33
	v_lshlrev_b32_e32 v33, 16, v75
	v_exp_f32_e32 v36, v36
	v_exp_f32_e32 v37, v37
	v_add_f32_e32 v27, 1.0, v34
	v_mul_f32_e32 v33, 0xbfb8aa3b, v33
	v_and_b32_e32 v34, 0xffff0000, v75
	v_exp_f32_e32 v33, v33
	v_mul_f32_e32 v34, 0xbfb8aa3b, v34
	v_exp_f32_e32 v35, v34
	v_rcp_f32_e32 v26, v26
	v_rcp_f32_e32 v27, v27
	v_add_f32_e32 v36, 1.0, v36
	v_add_f32_e32 v37, 1.0, v37
	v_rcp_f32_e32 v36, v36
	v_rcp_f32_e32 v37, v37
	v_add_f32_e32 v33, 1.0, v33
	v_rcp_f32_e32 v34, v33
	v_add_f32_e32 v33, 1.0, v35
	v_rcp_f32_e32 v35, v33
	v_lshlrev_b32_e32 v33, 16, v76
	v_pk_mul_f32 v[22:23], v[22:23], v[26:27]
	v_and_b32_e32 v27, 0xffff0000, v76
	v_mul_f32_e32 v33, 0xbfb8aa3b, v33
	v_mul_f32_e32 v27, 0xbfb8aa3b, v27
	v_pk_mul_f32 v[28:29], v[28:29], v[36:37]
	v_exp_f32_e32 v36, v33
	v_exp_f32_e32 v27, v27
	v_pk_mul_f32 v[24:25], v[24:25], v[34:35]
	v_cvt_pk_bf16_f32 v22, v22, v23
	v_add_f32_e32 v26, 1.0, v36
	v_add_f32_e32 v27, 1.0, v27
	v_rcp_f32_e32 v26, v26
	v_rcp_f32_e32 v27, v27
	v_cvt_pk_bf16_f32 v23, v24, v25
	s_waitcnt vmcnt(9)
	v_lshlrev_b32_e32 v24, 16, v70
	v_mul_f32_e32 v24, 0xbfb8aa3b, v24
	v_exp_f32_e32 v25, v24
	v_and_b32_e32 v24, 0xffff0000, v70
	v_mul_f32_e32 v24, 0xbfb8aa3b, v24
	v_pk_mul_f32 v[18:19], v[18:19], v[26:27]
	v_exp_f32_e32 v26, v24
	v_cvt_pk_bf16_f32 v33, v28, v29
	v_lshlrev_b32_e32 v28, 16, v77
	v_and_b32_e32 v29, 0xffff0000, v77
	v_mul_f32_e32 v28, 0xbfb8aa3b, v28
	v_mul_f32_e32 v29, 0xbfb8aa3b, v29
	v_cvt_pk_bf16_f32 v24, v18, v19
	v_add_f32_e32 v18, 1.0, v25
	v_lshlrev_b32_e32 v25, 16, v71
	v_exp_f32_e32 v28, v28
	v_exp_f32_e32 v29, v29
	v_add_f32_e32 v19, 1.0, v26
	v_mul_f32_e32 v25, 0xbfb8aa3b, v25
	v_and_b32_e32 v26, 0xffff0000, v71
	v_exp_f32_e32 v25, v25
	v_mul_f32_e32 v26, 0xbfb8aa3b, v26
	v_exp_f32_e32 v27, v26
	v_rcp_f32_e32 v18, v18
	v_rcp_f32_e32 v19, v19
	v_add_f32_e32 v28, 1.0, v28
	v_add_f32_e32 v29, 1.0, v29
	v_rcp_f32_e32 v28, v28
	v_rcp_f32_e32 v29, v29
	v_add_f32_e32 v25, 1.0, v25
	v_rcp_f32_e32 v26, v25
	v_add_f32_e32 v25, 1.0, v27
	v_rcp_f32_e32 v27, v25
	v_lshlrev_b32_e32 v25, 16, v72
	v_pk_mul_f32 v[14:15], v[14:15], v[18:19]
	v_and_b32_e32 v19, 0xffff0000, v72
	v_mul_f32_e32 v25, 0xbfb8aa3b, v25
	v_mul_f32_e32 v19, 0xbfb8aa3b, v19
	v_pk_mul_f32 v[20:21], v[20:21], v[28:29]
	v_exp_f32_e32 v28, v25
	v_exp_f32_e32 v19, v19
	v_pk_mul_f32 v[16:17], v[16:17], v[26:27]
	v_cvt_pk_bf16_f32 v14, v14, v15
	v_add_f32_e32 v18, 1.0, v28
	v_add_f32_e32 v19, 1.0, v19
	v_rcp_f32_e32 v18, v18
	v_rcp_f32_e32 v19, v19
	v_cvt_pk_bf16_f32 v15, v16, v17
	s_waitcnt vmcnt(8)
	v_lshlrev_b32_e32 v16, 16, v66
	v_mul_f32_e32 v16, 0xbfb8aa3b, v16
	v_exp_f32_e32 v17, v16
	v_and_b32_e32 v16, 0xffff0000, v66
	v_mul_f32_e32 v16, 0xbfb8aa3b, v16
	v_pk_mul_f32 v[10:11], v[10:11], v[18:19]
	v_exp_f32_e32 v18, v16
	v_cvt_pk_bf16_f32 v25, v20, v21
	v_lshlrev_b32_e32 v20, 16, v73
	v_and_b32_e32 v21, 0xffff0000, v73
	v_mul_f32_e32 v20, 0xbfb8aa3b, v20
	v_mul_f32_e32 v21, 0xbfb8aa3b, v21
	v_exp_f32_e32 v20, v20
	v_exp_f32_e32 v21, v21
	v_cvt_pk_bf16_f32 v16, v10, v11
	v_add_f32_e32 v10, 1.0, v17
	v_lshlrev_b32_e32 v17, 16, v67
	v_add_f32_e32 v11, 1.0, v18
	v_mul_f32_e32 v17, 0xbfb8aa3b, v17
	v_and_b32_e32 v18, 0xffff0000, v67
	v_exp_f32_e32 v17, v17
	v_mul_f32_e32 v18, 0xbfb8aa3b, v18
	v_exp_f32_e32 v19, v18
	v_add_f32_e32 v20, 1.0, v20
	v_add_f32_e32 v21, 1.0, v21
	v_rcp_f32_e32 v20, v20
	v_rcp_f32_e32 v21, v21
	v_rcp_f32_e32 v10, v10
	v_rcp_f32_e32 v11, v11
	v_add_f32_e32 v17, 1.0, v17
	v_rcp_f32_e32 v18, v17
	v_add_f32_e32 v17, 1.0, v19
	v_rcp_f32_e32 v19, v17
	v_lshlrev_b32_e32 v17, 16, v68
	v_pk_mul_f32 v[12:13], v[12:13], v[20:21]
	v_mul_f32_e32 v17, 0xbfb8aa3b, v17
	v_pk_mul_f32 v[6:7], v[6:7], v[10:11]
	v_and_b32_e32 v11, 0xffff0000, v68
	v_exp_f32_e32 v20, v17
	v_cvt_pk_bf16_f32 v17, v12, v13
	v_mul_f32_e32 v11, 0xbfb8aa3b, v11
	v_lshlrev_b32_e32 v12, 16, v69
	v_and_b32_e32 v13, 0xffff0000, v69
	v_exp_f32_e32 v11, v11
	v_mul_f32_e32 v12, 0xbfb8aa3b, v12
	v_mul_f32_e32 v13, 0xbfb8aa3b, v13
	v_exp_f32_e32 v12, v12
	v_exp_f32_e32 v13, v13
	v_add_f32_e32 v10, 1.0, v20
	v_add_f32_e32 v11, 1.0, v11
	v_rcp_f32_e32 v10, v10
	v_add_f32_e32 v12, 1.0, v12
	v_add_f32_e32 v13, 1.0, v13
	v_rcp_f32_e32 v11, v11
	v_rcp_f32_e32 v12, v12
	v_rcp_f32_e32 v13, v13
	v_pk_mul_f32 v[8:9], v[8:9], v[18:19]
	v_pk_mul_f32 v[2:3], v[2:3], v[10:11]
	v_cvt_pk_bf16_f32 v6, v6, v7
	v_cvt_pk_bf16_f32 v7, v8, v9
	v_pk_mul_f32 v[4:5], v[4:5], v[12:13]
	v_cvt_pk_bf16_f32 v8, v2, v3
	v_lshl_add_u64 v[2:3], s[6:7], 0, v[96:97]
	v_cvt_pk_bf16_f32 v9, v4, v5
	v_lshl_add_u64 v[2:3], v[2:3], 0, v[166:167]
	global_store_dwordx4 v[2:3], v[6:9], off nt
	global_store_dwordx4 v[2:3], v[14:17], off offset:256 nt
	v_lshl_add_u64 v[2:3], s[6:7], 0, v[94:95]
	v_lshl_add_u64 v[2:3], v[2:3], 0, v[166:167]
	global_store_dwordx4 v[2:3], v[22:25], off nt
	global_store_dwordx4 v[2:3], v[30:33], off offset:256 nt
	v_lshl_add_u64 v[2:3], s[6:7], 0, v[88:89]
	v_lshl_add_u64 v[2:3], v[2:3], 0, v[166:167]
	global_store_dwordx4 v[2:3], v[38:41], off nt
	global_store_dwordx4 v[2:3], v[46:49], off offset:256 nt
	v_lshl_add_u64 v[2:3], s[6:7], 0, v[86:87]
	v_lshl_add_u64 v[2:3], v[2:3], 0, v[166:167]
	global_store_dwordx4 v[2:3], v[54:57], off nt
	global_store_dwordx4 v[2:3], v[62:65], off offset:256 nt
	s_cbranch_vccnz .LBB0_763
	s_andn2_b64 vcc, exec, s[10:11]
	s_cbranch_vccnz .LBB0_762
	s_barrier
	s_branch .LBB0_762

.LBB0_796:
	ds_read_b128 v[130:133], v162
	ds_read_b128 v[134:137], v162 offset:1024
	ds_read_b128 v[154:157], v162 offset:2048
	ds_read_b128 v[166:169], v162 offset:3072
	ds_read_b128 v[170:173], v163
	ds_read_b128 v[174:177], v163 offset:1024
	ds_read_b128 v[178:181], v163 offset:2048
	ds_read_b128 v[182:185], v163 offset:3072
	s_add_u32 s28, s0, 0xfff80080
	s_addc_u32 s29, s1, -1
	s_cmp_eq_u32 s54, 28
	s_cselect_b32 s31, s21, s29
	s_cselect_b32 s30, s50, s28
	s_cselect_b32 s29, s19, s53
	s_cselect_b32 s28, s51, s52
	v_lshl_add_u64 v[158:159], s[0:1], 0, v[146:147]
	s_add_i32 m0, s27, 0xc000
	ds_read_b128 v[186:189], v164
	ds_read_b128 v[190:193], v164 offset:1024
	ds_read_b128 v[194:197], v164 offset:2048
	ds_read_b128 v[198:201], v164 offset:3072
	ds_read_b128 v[202:205], v164 offset:4096
	ds_read_b128 v[206:209], v164 offset:5120
	ds_read_b128 v[210:213], v164 offset:6144
	ds_read_b128 v[214:217], v164 offset:7168
	global_load_lds_dwordx4 v[158:159], off
	v_lshl_add_u64 v[158:159], s[0:1], 0, v[148:149]
	s_add_i32 m0, s27, 0xe000
	s_nop 0
	global_load_lds_dwordx4 v[158:159], off
	s_waitcnt vmcnt(8)
	s_waitcnt lgkmcnt(0)
	s_barrier
	s_setprio 1
	s_waitcnt lgkmcnt(0)
	v_mfma_f32_16x16x32_bf16 v[126:129], v[130:133], v[186:189], v[126:129]
	v_mfma_f32_16x16x32_bf16 v[122:125], v[154:157], v[186:189], v[122:125]
	v_mfma_f32_16x16x32_bf16 v[110:113], v[130:133], v[194:197], v[110:113]
	v_mfma_f32_16x16x32_bf16 v[106:109], v[154:157], v[194:197], v[106:109]
	v_mfma_f32_16x16x32_bf16 v[94:97], v[130:133], v[202:205], v[94:97]
	v_mfma_f32_16x16x32_bf16 v[90:93], v[154:157], v[202:205], v[90:93]
	v_mfma_f32_16x16x32_bf16 v[78:81], v[130:133], v[210:213], v[78:81]
	v_mfma_f32_16x16x32_bf16 v[74:77], v[154:157], v[210:213], v[74:77]
	v_mfma_f32_16x16x32_bf16 v[126:129], v[134:137], v[190:193], v[126:129]
	v_mfma_f32_16x16x32_bf16 v[122:125], v[166:169], v[190:193], v[122:125]
	v_mfma_f32_16x16x32_bf16 v[110:113], v[134:137], v[198:201], v[110:113]
	v_mfma_f32_16x16x32_bf16 v[106:109], v[166:169], v[198:201], v[106:109]
	v_mfma_f32_16x16x32_bf16 v[94:97], v[134:137], v[206:209], v[94:97]
	v_mfma_f32_16x16x32_bf16 v[90:93], v[166:169], v[206:209], v[90:93]
	v_mfma_f32_16x16x32_bf16 v[78:81], v[134:137], v[214:217], v[78:81]
	v_mfma_f32_16x16x32_bf16 v[74:77], v[166:169], v[214:217], v[74:77]
	s_setprio 0
	s_setprio 1
	v_mfma_f32_16x16x32_bf16 v[118:121], v[170:173], v[186:189], v[118:121]
	v_mfma_f32_16x16x32_bf16 v[114:117], v[178:181], v[186:189], v[114:117]
	v_mfma_f32_16x16x32_bf16 v[102:105], v[170:173], v[194:197], v[102:105]
	v_mfma_f32_16x16x32_bf16 v[98:101], v[178:181], v[194:197], v[98:101]
	v_mfma_f32_16x16x32_bf16 v[86:89], v[170:173], v[202:205], v[86:89]
	v_mfma_f32_16x16x32_bf16 v[82:85], v[178:181], v[202:205], v[82:85]
	v_mfma_f32_16x16x32_bf16 v[70:73], v[170:173], v[210:213], v[70:73]
	v_mfma_f32_16x16x32_bf16 v[66:69], v[178:181], v[210:213], v[66:69]
	v_mfma_f32_16x16x32_bf16 v[118:121], v[174:177], v[190:193], v[118:121]
	v_mfma_f32_16x16x32_bf16 v[114:117], v[182:185], v[190:193], v[114:117]
	v_mfma_f32_16x16x32_bf16 v[102:105], v[174:177], v[198:201], v[102:105]
	v_mfma_f32_16x16x32_bf16 v[98:101], v[182:185], v[198:201], v[98:101]
	v_mfma_f32_16x16x32_bf16 v[86:89], v[174:177], v[206:209], v[86:89]
	v_mfma_f32_16x16x32_bf16 v[82:85], v[182:185], v[206:209], v[82:85]
	v_mfma_f32_16x16x32_bf16 v[70:73], v[174:177], v[214:217], v[70:73]
	v_mfma_f32_16x16x32_bf16 v[66:69], v[182:185], v[214:217], v[66:69]
	s_setprio 0
	s_barrier
	s_add_i32 s55, s47, s39
	v_lshl_add_u64 v[158:159], s[28:29], 0, v[140:141]
	s_mov_b32 m0, s55
	ds_read_b128 v[186:189], v164 offset:16384
	ds_read_b128 v[190:193], v164 offset:17408
	ds_read_b128 v[194:197], v164 offset:18432
	ds_read_b128 v[198:201], v164 offset:19456
	ds_read_b128 v[202:205], v164 offset:20480
	ds_read_b128 v[206:209], v164 offset:21504
	ds_read_b128 v[210:213], v164 offset:22528
	ds_read_b128 v[214:217], v164 offset:23552
	global_load_lds_dwordx4 v[158:159], off
	s_add_i32 m0, s55, 0x2000
	s_add_u32 s56, s28, 0x80000
	v_lshl_add_u64 v[218:219], s[28:29], 0, v[144:145]
	s_addc_u32 s57, s29, 0
	s_add_i32 s55, s48, s39
	global_load_lds_dwordx4 v[218:219], off
	v_lshl_add_u64 v[220:221], s[56:57], 0, v[140:141]
	s_mov_b32 m0, s55
	v_lshl_add_u64 v[222:223], s[30:31], 0, v[142:143]
	global_load_lds_dwordx4 v[220:221], off
	v_lshl_add_u64 v[220:221], s[56:57], 0, v[144:145]
	s_add_i32 m0, s55, 0x2000
	s_nop 0
	global_load_lds_dwordx4 v[220:221], off
	v_lshl_add_u64 v[220:221], s[30:31], 0, v[138:139]
	s_mov_b32 m0, s27
	s_nop 0
	global_load_lds_dwordx4 v[220:221], off
	s_mov_b32 m0, s40
	s_nop 0
	global_load_lds_dwordx4 v[222:223], off
	s_waitcnt vmcnt(8)
	s_waitcnt lgkmcnt(0)
	s_barrier
	s_setprio 1
	s_waitcnt lgkmcnt(0)
	v_mfma_f32_16x16x32_bf16 v[62:65], v[130:133], v[186:189], v[62:65]
	v_mfma_f32_16x16x32_bf16 v[58:61], v[154:157], v[186:189], v[58:61]
	v_mfma_f32_16x16x32_bf16 v[46:49], v[130:133], v[194:197], v[46:49]
	v_mfma_f32_16x16x32_bf16 v[42:45], v[154:157], v[194:197], v[42:45]
	v_mfma_f32_16x16x32_bf16 v[6:9], v[130:133], v[202:205], v[6:9]
	v_mfma_f32_16x16x32_bf16 v[2:5], v[154:157], v[202:205], v[2:5]
	v_mfma_f32_16x16x32_bf16 v[22:25], v[130:133], v[210:213], v[22:25]
	v_mfma_f32_16x16x32_bf16 v[18:21], v[154:157], v[210:213], v[18:21]
	v_mfma_f32_16x16x32_bf16 v[62:65], v[134:137], v[190:193], v[62:65]
	v_mfma_f32_16x16x32_bf16 v[58:61], v[166:169], v[190:193], v[58:61]
	v_mfma_f32_16x16x32_bf16 v[46:49], v[134:137], v[198:201], v[46:49]
	v_mfma_f32_16x16x32_bf16 v[42:45], v[166:169], v[198:201], v[42:45]
	v_mfma_f32_16x16x32_bf16 v[6:9], v[134:137], v[206:209], v[6:9]
	v_mfma_f32_16x16x32_bf16 v[2:5], v[166:169], v[206:209], v[2:5]
	v_mfma_f32_16x16x32_bf16 v[22:25], v[134:137], v[214:217], v[22:25]
	v_mfma_f32_16x16x32_bf16 v[18:21], v[166:169], v[214:217], v[18:21]
	s_setprio 0
	s_setprio 1
	v_mfma_f32_16x16x32_bf16 v[54:57], v[170:173], v[186:189], v[54:57]
	v_mfma_f32_16x16x32_bf16 v[50:53], v[178:181], v[186:189], v[50:53]
	v_mfma_f32_16x16x32_bf16 v[38:41], v[170:173], v[194:197], v[38:41]
	v_mfma_f32_16x16x32_bf16 v[34:37], v[178:181], v[194:197], v[34:37]
	v_mfma_f32_16x16x32_bf16 v[14:17], v[170:173], v[202:205], v[14:17]
	v_mfma_f32_16x16x32_bf16 v[10:13], v[178:181], v[202:205], v[10:13]
	v_mfma_f32_16x16x32_bf16 v[30:33], v[170:173], v[210:213], v[30:33]
	v_mfma_f32_16x16x32_bf16 v[26:29], v[178:181], v[210:213], v[26:29]
	v_mfma_f32_16x16x32_bf16 v[54:57], v[174:177], v[190:193], v[54:57]
	v_mfma_f32_16x16x32_bf16 v[50:53], v[182:185], v[190:193], v[50:53]
	v_mfma_f32_16x16x32_bf16 v[38:41], v[174:177], v[198:201], v[38:41]
	v_mfma_f32_16x16x32_bf16 v[34:37], v[182:185], v[198:201], v[34:37]
	v_mfma_f32_16x16x32_bf16 v[14:17], v[174:177], v[206:209], v[14:17]
	v_mfma_f32_16x16x32_bf16 v[10:13], v[182:185], v[206:209], v[10:13]
	v_mfma_f32_16x16x32_bf16 v[30:33], v[174:177], v[214:217], v[30:33]
	v_mfma_f32_16x16x32_bf16 v[26:29], v[182:185], v[214:217], v[26:29]
	s_setprio 0
	s_barrier
	s_cmp_lg_u32 s54, 28
	s_cbranch_scc1 .Lmy_p6_nox
	v_lshl_add_u32 v152, s26, 8, v1
	v_lshl_or_b32 v153, s49, 8, v161
	v_lshl_add_u32 v152, v152, 10, v153
	v_lshlrev_b32_e32 v150, 1, v152
	v_add_u32_e32 v151, 0x8000, v150
	global_load_dwordx4 v[226:229], v150, s[8:9] nt
	global_load_dwordx4 v[230:233], v150, s[10:11] nt
	global_load_dwordx4 v[234:237], v150, s[8:9] offset:256 nt
	global_load_dwordx4 v[238:241], v150, s[10:11] offset:256 nt
	global_load_dwordx4 v[242:245], v151, s[8:9] nt
	global_load_dwordx4 v[246:249], v151, s[10:11] nt
	global_load_dwordx4 v[250:253], v151, s[8:9] offset:256 nt
	global_load_dwordx4 v[150:153], v151, s[10:11] offset:256 nt

.LBB0_799:
	v_lshl_add_u32 v156, s26, 8, v1
	v_lshl_or_b32 v154, s49, 8, v161
	v_ashrrev_i32_e32 v157, 31, v156
	v_ashrrev_i32_e32 v155, 31, v154
	v_lshlrev_b64 v[130:131], 10, v[156:157]
	v_lshl_add_u64 v[130:131], v[130:131], 0, v[154:155]
	v_lshlrev_b64 v[130:131], 1, v[130:131]
	v_lshl_add_u64 v[132:133], s[8:9], 0, v[130:131]
	s_waitcnt vmcnt(8)
	v_mov_b32_e32 v166, v226
	v_mov_b32_e32 v167, v227
	v_mov_b32_e32 v168, v228
	v_mov_b32_e32 v169, v229
	v_lshl_add_u64 v[132:133], s[10:11], 0, v[130:131]
	v_or_b32_e32 v130, 0x100, v130
	v_mov_b32_e32 v170, v230
	v_mov_b32_e32 v171, v231
	v_mov_b32_e32 v172, v232
	v_mov_b32_e32 v173, v233
	v_lshl_add_u64 v[132:133], s[8:9], 0, v[130:131]
	v_lshl_add_u64 v[130:131], s[10:11], 0, v[130:131]
	v_mov_b32_e32 v174, v234
	v_mov_b32_e32 v175, v235
	v_mov_b32_e32 v176, v236
	v_mov_b32_e32 v177, v237
	v_mov_b32_e32 v178, v238
	v_mov_b32_e32 v179, v239
	v_mov_b32_e32 v180, v240
	v_mov_b32_e32 v181, v241
	v_or_b32_e32 v158, 16, v156
	v_ashrrev_i32_e32 v159, 31, v158
	v_lshlrev_b64 v[130:131], 10, v[158:159]
	v_lshl_add_u64 v[130:131], v[130:131], 0, v[154:155]
	v_lshlrev_b64 v[130:131], 1, v[130:131]
	v_lshl_add_u64 v[132:133], s[8:9], 0, v[130:131]
	v_lshl_add_u64 v[134:135], s[10:11], 0, v[130:131]
	v_mov_b32_e32 v182, v242
	v_mov_b32_e32 v183, v243
	v_mov_b32_e32 v184, v244
	v_mov_b32_e32 v185, v245
	v_mov_b32_e32 v186, v246
	v_mov_b32_e32 v187, v247
	v_mov_b32_e32 v188, v248
	v_mov_b32_e32 v189, v249
	v_or_b32_e32 v130, 0x100, v130
	v_lshl_add_u64 v[132:133], s[8:9], 0, v[130:131]
	v_lshl_add_u64 v[130:131], s[10:11], 0, v[130:131]
	v_mov_b32_e32 v134, v250
	v_mov_b32_e32 v135, v251
	v_mov_b32_e32 v136, v252
	v_mov_b32_e32 v137, v253
	s_nop 0
	v_mov_b32_e32 v130, v150
	v_mov_b32_e32 v131, v151
	v_mov_b32_e32 v132, v152
	v_mov_b32_e32 v133, v153
	s_andn2_b64 vcc, exec, s[2:3]
	s_mov_b64 s[0:1], -1
	s_waitcnt vmcnt(8)
	v_lshlrev_b32_e32 v165, 16, v166
	v_and_b32_e32 v190, 0xffff0000, v166
	v_lshlrev_b32_e32 v191, 16, v167
	v_lshlrev_b32_e32 v193, 16, v168
	v_and_b32_e32 v194, 0xffff0000, v168
	v_lshlrev_b32_e32 v195, 16, v169
	v_and_b32_e32 v196, 0xffff0000, v169
	v_and_b32_e32 v192, 0xffff0000, v167
	v_mul_f32_e32 v165, 0xbfb8aa3b, v165
	v_mul_f32_e32 v193, 0xbfb8aa3b, v193
	v_mul_f32_e32 v190, 0xbfb8aa3b, v190
	v_mul_f32_e32 v194, 0xbfb8aa3b, v194
	v_mul_f32_e32 v191, 0xbfb8aa3b, v191
	v_mul_f32_e32 v195, 0xbfb8aa3b, v195
	v_mul_f32_e32 v196, 0xbfb8aa3b, v196
	v_mul_f32_e32 v192, 0xbfb8aa3b, v192
	v_lshlrev_b32_e32 v202, 16, v176
	v_and_b32_e32 v203, 0xffff0000, v176
	v_lshlrev_b32_e32 v204, 16, v177
	v_and_b32_e32 v205, 0xffff0000, v177
	v_lshlrev_b32_e32 v176, 16, v179
	v_and_b32_e32 v177, 0xffff0000, v179
	v_exp_f32_e32 v165, v165
	v_exp_f32_e32 v179, v193
	v_exp_f32_e32 v190, v190
	v_exp_f32_e32 v193, v194
	v_exp_f32_e32 v191, v191
	v_exp_f32_e32 v194, v195
	v_exp_f32_e32 v195, v196
	v_exp_f32_e32 v192, v192
	v_add_f32_e32 v165, 1.0, v165
	v_add_f32_e32 v179, 1.0, v179
	v_add_f32_e32 v196, 1.0, v190
	v_add_f32_e32 v193, 1.0, v193
	v_add_f32_e32 v197, 1.0, v191
	v_add_f32_e32 v206, 1.0, v194
	v_add_f32_e32 v208, 1.0, v195
	v_add_f32_e32 v207, 1.0, v192
	v_rcp_f32_e32 v190, v165
	v_rcp_f32_e32 v192, v179
	v_rcp_f32_e32 v191, v196
	v_rcp_f32_e32 v194, v197
	v_rcp_f32_e32 v196, v206
	v_rcp_f32_e32 v197, v208
	v_rcp_f32_e32 v193, v193
	v_rcp_f32_e32 v195, v207
	v_lshlrev_b32_e32 v166, 16, v170
	v_and_b32_e32 v167, 0xffff0000, v170
	v_lshlrev_b32_e32 v168, 16, v171
	v_and_b32_e32 v169, 0xffff0000, v171
	v_lshlrev_b32_e32 v170, 16, v172
	v_and_b32_e32 v171, 0xffff0000, v172
	v_lshlrev_b32_e32 v172, 16, v173
	v_and_b32_e32 v173, 0xffff0000, v173
	v_lshlrev_b32_e32 v200, 16, v175
	v_pk_fma_f32 v[126:127], v[126:127], v[190:191], v[166:167]
	v_pk_fma_f32 v[166:167], v[124:125], v[196:197], v[172:173]
	v_pk_fma_f32 v[124:125], v[122:123], v[192:193], v[170:171]
	v_pk_fma_f32 v[128:129], v[128:129], v[194:195], v[168:169]
	v_cvt_pk_bf16_f32 v124, v124, v125
	v_cvt_pk_bf16_f32 v125, v166, v167
	v_mul_f32_e32 v167, 0xbfb8aa3b, v200
	v_and_b32_e32 v199, 0xffff0000, v174
	v_cvt_pk_bf16_f32 v123, v128, v129
	v_mul_f32_e32 v129, 0xbfb8aa3b, v202
	v_exp_f32_e32 v167, v167
	v_mul_f32_e32 v168, 0xbfb8aa3b, v204
	v_exp_f32_e32 v129, v129
	v_mul_f32_e32 v165, 0xbfb8aa3b, v199
	v_exp_f32_e32 v169, v168
	v_exp_f32_e32 v165, v165
	v_and_b32_e32 v201, 0xffff0000, v175
	v_add_f32_e32 v167, 1.0, v167
	v_add_f32_e32 v129, 1.0, v129
	v_rcp_f32_e32 v168, v167
	v_add_f32_e32 v167, 1.0, v169
	v_mul_f32_e32 v169, 0xbfb8aa3b, v201
	v_rcp_f32_e32 v166, v129
	v_add_f32_e32 v129, 1.0, v165
	v_mul_f32_e32 v165, 0xbfb8aa3b, v203
	v_exp_f32_e32 v169, v169
	v_mul_f32_e32 v170, 0xbfb8aa3b, v205
	v_exp_f32_e32 v165, v165
	v_exp_f32_e32 v171, v170
	v_rcp_f32_e32 v170, v167
	v_add_f32_e32 v167, 1.0, v169
	v_add_f32_e32 v165, 1.0, v165
	v_rcp_f32_e32 v169, v167
	v_add_f32_e32 v167, 1.0, v171
	v_rcp_f32_e32 v171, v167
	v_rcp_f32_e32 v167, v165
	v_lshlrev_b32_e32 v198, 16, v174
	v_cvt_pk_bf16_f32 v122, v126, v127
	v_mul_f32_e32 v126, 0xbfb8aa3b, v198
	v_lshlrev_b32_e32 v174, 16, v178
	v_and_b32_e32 v175, 0xffff0000, v178
	v_lshlrev_b32_e32 v178, 16, v180
	v_exp_f32_e32 v128, v126
	v_and_b32_e32 v179, 0xffff0000, v180
	v_lshlrev_b32_e32 v126, 16, v181
	v_and_b32_e32 v127, 0xffff0000, v181
	v_pk_fma_f32 v[126:127], v[116:117], v[170:171], v[126:127]
	v_pk_fma_f32 v[116:117], v[114:115], v[166:167], v[178:179]
	v_and_b32_e32 v165, 0xffff0000, v182
	v_cvt_pk_bf16_f32 v116, v116, v117
	v_cvt_pk_bf16_f32 v117, v126, v127
	v_lshlrev_b32_e32 v127, 16, v182
	v_lshlrev_b32_e32 v166, 16, v184
	v_mul_f32_e32 v127, 0xbfb8aa3b, v127
	v_exp_f32_e32 v167, v127
	v_mul_f32_e32 v166, 0xbfb8aa3b, v166
	v_mul_f32_e32 v165, 0xbfb8aa3b, v165
	v_pk_fma_f32 v[120:121], v[120:121], v[168:169], v[176:177]
	v_exp_f32_e32 v168, v166
	v_exp_f32_e32 v165, v165
	v_lshlrev_b32_e32 v169, 16, v183
	v_add_f32_e32 v167, 1.0, v167
	v_and_b32_e32 v170, 0xffff0000, v184
	v_lshlrev_b32_e32 v172, 16, v185
	v_rcp_f32_e32 v166, v167
	v_add_f32_e32 v167, 1.0, v168
	v_add_f32_e32 v165, 1.0, v165
	v_mul_f32_e32 v169, 0xbfb8aa3b, v169
	v_rcp_f32_e32 v168, v167
	v_rcp_f32_e32 v167, v165
	v_mul_f32_e32 v165, 0xbfb8aa3b, v170
	v_exp_f32_e32 v169, v169
	v_mul_f32_e32 v170, 0xbfb8aa3b, v172
	v_exp_f32_e32 v172, v170
	v_and_b32_e32 v171, 0xffff0000, v183
	v_and_b32_e32 v173, 0xffff0000, v185
	v_add_f32_e32 v169, 1.0, v169
	v_mul_f32_e32 v171, 0xbfb8aa3b, v171
	v_rcp_f32_e32 v170, v169
	v_add_f32_e32 v169, 1.0, v172
	v_exp_f32_e32 v171, v171
	v_mul_f32_e32 v172, 0xbfb8aa3b, v173
	v_exp_f32_e32 v173, v172
	v_exp_f32_e32 v165, v165
	v_add_f32_e32 v128, 1.0, v128
	v_rcp_f32_e32 v172, v169
	v_add_f32_e32 v169, 1.0, v171
	v_rcp_f32_e32 v128, v128
	v_rcp_f32_e32 v129, v129
	v_rcp_f32_e32 v171, v169
	v_add_f32_e32 v169, 1.0, v173
	v_rcp_f32_e32 v173, v169
	v_add_f32_e32 v165, 1.0, v165
	v_rcp_f32_e32 v169, v165
	v_pk_fma_f32 v[118:119], v[118:119], v[128:129], v[174:175]
	v_lshlrev_b32_e32 v128, 16, v189
	v_and_b32_e32 v129, 0xffff0000, v189
	v_cvt_pk_bf16_f32 v115, v120, v121
	v_lshlrev_b32_e32 v120, 16, v187
	v_and_b32_e32 v121, 0xffff0000, v187
	v_pk_fma_f32 v[108:109], v[108:109], v[172:173], v[128:129]
	v_lshlrev_b32_e32 v126, 16, v188
	v_and_b32_e32 v127, 0xffff0000, v188
	v_pk_fma_f32 v[112:113], v[112:113], v[170:171], v[120:121]
	v_cvt_pk_bf16_f32 v121, v108, v109
	v_or_b32_e32 v108, 32, v156
	v_pk_fma_f32 v[106:107], v[106:107], v[168:169], v[126:127]
	v_ashrrev_i32_e32 v109, 31, v108
	v_cvt_pk_bf16_f32 v120, v106, v107
	v_lshlrev_b64 v[106:107], 10, v[108:109]
	v_cvt_pk_bf16_f32 v114, v118, v119
	v_lshlrev_b32_e32 v118, 16, v186
	v_and_b32_e32 v119, 0xffff0000, v186
	v_lshl_add_u64 v[106:107], v[106:107], 0, v[154:155]
	v_pk_fma_f32 v[110:111], v[110:111], v[166:167], v[118:119]
	v_lshlrev_b64 v[106:107], 1, v[106:107]
	v_cvt_pk_bf16_f32 v118, v110, v111
	v_or_b32_e32 v110, 0x100, v106
	v_mov_b32_e32 v111, v107
	v_cvt_pk_bf16_f32 v119, v112, v113
	v_lshl_add_u64 v[112:113], s[8:9], 0, v[110:111]
	v_lshlrev_b32_e32 v165, 16, v134
	v_and_b32_e32 v174, 0xffff0000, v134
	v_lshlrev_b32_e32 v175, 16, v135
	v_and_b32_e32 v177, 0xffff0000, v135
	v_lshl_add_u64 v[134:135], s[8:9], 0, v[106:107]
	global_load_dwordx4 v[126:129], v[112:113], off nt
	global_load_dwordx4 v[166:169], v[134:135], off nt
	v_lshl_add_u64 v[110:111], s[10:11], 0, v[110:111]
	v_lshl_add_u64 v[106:107], s[10:11], 0, v[106:107]
	v_lshlrev_b32_e32 v176, 16, v136
	v_and_b32_e32 v178, 0xffff0000, v136
	v_lshlrev_b32_e32 v179, 16, v137
	v_and_b32_e32 v180, 0xffff0000, v137
	global_load_dwordx4 v[134:137], v[110:111], off nt
	global_load_dwordx4 v[170:173], v[106:107], off nt
	v_mul_f32_e32 v107, 0xbfb8aa3b, v165
	v_exp_f32_e32 v165, v107
	v_lshlrev_b32_e32 v110, 16, v133
	v_and_b32_e32 v111, 0xffff0000, v133
	v_mul_f32_e32 v133, 0xbfb8aa3b, v176
	v_lshlrev_b32_e32 v106, 16, v132
	v_and_b32_e32 v107, 0xffff0000, v132
	v_add_f32_e32 v132, 1.0, v165
	v_exp_f32_e32 v133, v133
	v_mul_f32_e32 v165, 0xbfb8aa3b, v174
	v_exp_f32_e32 v165, v165
	v_mul_f32_e32 v175, 0xbfb8aa3b, v175
	v_add_f32_e32 v133, 1.0, v133
	v_exp_f32_e32 v175, v175
	v_mul_f32_e32 v176, 0xbfb8aa3b, v179
	v_rcp_f32_e32 v174, v133
	v_add_f32_e32 v133, 1.0, v165
	v_mul_f32_e32 v165, 0xbfb8aa3b, v178
	v_exp_f32_e32 v178, v176
	v_add_f32_e32 v175, 1.0, v175
	v_mul_f32_e32 v177, 0xbfb8aa3b, v177
	v_rcp_f32_e32 v176, v175
	v_add_f32_e32 v175, 1.0, v178
	v_exp_f32_e32 v177, v177
	v_mul_f32_e32 v178, 0xbfb8aa3b, v180
	v_exp_f32_e32 v179, v178
	v_exp_f32_e32 v165, v165
	v_rcp_f32_e32 v178, v175
	v_add_f32_e32 v175, 1.0, v177
	v_rcp_f32_e32 v177, v175
	v_add_f32_e32 v175, 1.0, v179
	v_add_f32_e32 v165, 1.0, v165
	v_rcp_f32_e32 v179, v175
	v_rcp_f32_e32 v175, v165
	v_rcp_f32_e32 v132, v132
	v_rcp_f32_e32 v133, v133
	v_pk_fma_f32 v[100:101], v[100:101], v[178:179], v[110:111]
	v_or_b32_e32 v110, 48, v156
	v_lshlrev_b32_e32 v112, 16, v130
	v_and_b32_e32 v113, 0xffff0000, v130
	v_pk_fma_f32 v[98:99], v[98:99], v[174:175], v[106:107]
	v_ashrrev_i32_e32 v111, 31, v110
	v_pk_fma_f32 v[102:103], v[102:103], v[132:133], v[112:113]
	v_cvt_pk_bf16_f32 v132, v98, v99
	v_lshlrev_b64 v[98:99], 10, v[110:111]
	v_lshl_add_u64 v[98:99], v[98:99], 0, v[154:155]
	v_lshlrev_b64 v[98:99], 1, v[98:99]
	v_lshlrev_b32_e32 v130, 16, v131
	v_and_b32_e32 v131, 0xffff0000, v131
	v_cvt_pk_bf16_f32 v133, v100, v101
	v_or_b32_e32 v100, 0x100, v98
	v_mov_b32_e32 v101, v99
	v_pk_fma_f32 v[104:105], v[104:105], v[176:177], v[130:131]
	v_cvt_pk_bf16_f32 v130, v102, v103
	v_lshl_add_u64 v[102:103], s[8:9], 0, v[100:101]
	v_cvt_pk_bf16_f32 v131, v104, v105
	v_lshl_add_u64 v[106:107], s[8:9], 0, v[98:99]
	global_load_dwordx4 v[102:105], v[102:103], off nt
	s_nop 0
	global_load_dwordx4 v[174:177], v[106:107], off nt
	v_lshl_add_u64 v[100:101], s[10:11], 0, v[100:101]
	v_lshl_add_u64 v[106:107], s[10:11], 0, v[98:99]
	global_load_dwordx4 v[98:101], v[100:101], off nt
	s_nop 0
	global_load_dwordx4 v[178:181], v[106:107], off nt
	v_lshlrev_b64 v[106:107], 11, v[156:157]
	v_lshl_add_u64 v[112:113], s[12:13], 0, v[106:107]
	v_lshlrev_b64 v[106:107], 1, v[154:155]
	v_lshl_add_u64 v[112:113], v[112:113], 0, v[106:107]
	global_store_dwordx4 v[112:113], v[122:125], off nt
	global_store_dwordx4 v[112:113], v[114:117], off offset:256 nt
	v_lshlrev_b64 v[112:113], 11, v[158:159]
	v_lshl_add_u64 v[112:113], s[12:13], 0, v[112:113]
	v_lshl_add_u64 v[112:113], v[112:113], 0, v[106:107]
	global_store_dwordx4 v[112:113], v[118:121], off nt
	global_store_dwordx4 v[112:113], v[130:133], off offset:256 nt
	v_lshlrev_b64 v[108:109], 11, v[108:109]
	v_lshl_add_u64 v[108:109], s[12:13], 0, v[108:109]
	s_waitcnt vmcnt(10)
	v_lshlrev_b32_e32 v117, 16, v166
	v_lshlrev_b32_e32 v123, 16, v167
	v_lshlrev_b32_e32 v121, 16, v168
	v_and_b32_e32 v120, 0xffff0000, v166
	v_and_b32_e32 v124, 0xffff0000, v168
	v_lshlrev_b32_e32 v130, 16, v169
	v_mul_f32_e32 v117, 0xbfb8aa3b, v117
	v_mul_f32_e32 v121, 0xbfb8aa3b, v121
	v_mul_f32_e32 v123, 0xbfb8aa3b, v123
	v_exp_f32_e32 v122, v117
	v_exp_f32_e32 v121, v121
	v_mul_f32_e32 v120, 0xbfb8aa3b, v120
	v_mul_f32_e32 v124, 0xbfb8aa3b, v124
	v_exp_f32_e32 v123, v123
	v_mul_f32_e32 v130, 0xbfb8aa3b, v130
	v_exp_f32_e32 v132, v120
	v_exp_f32_e32 v124, v124
	v_exp_f32_e32 v130, v130
	v_and_b32_e32 v125, 0xffff0000, v167
	v_and_b32_e32 v131, 0xffff0000, v169
	v_add_f32_e32 v122, 1.0, v122
	v_add_f32_e32 v121, 1.0, v121
	v_add_f32_e32 v123, 1.0, v123
	v_mul_f32_e32 v125, 0xbfb8aa3b, v125
	v_rcp_f32_e32 v120, v122
	v_rcp_f32_e32 v122, v121
	v_add_f32_e32 v121, 1.0, v132
	v_add_f32_e32 v132, 1.0, v124
	v_rcp_f32_e32 v124, v123
	v_add_f32_e32 v123, 1.0, v130
	v_exp_f32_e32 v125, v125
	v_mul_f32_e32 v130, 0xbfb8aa3b, v131
	v_exp_f32_e32 v131, v130
	v_rcp_f32_e32 v130, v123
	v_add_f32_e32 v123, 1.0, v125
	v_rcp_f32_e32 v125, v123
	v_add_f32_e32 v123, 1.0, v131
	v_rcp_f32_e32 v121, v121
	v_rcp_f32_e32 v131, v123
	v_rcp_f32_e32 v123, v132
	s_waitcnt vmcnt(8)
	v_lshlrev_b32_e32 v112, 16, v170
	v_and_b32_e32 v113, 0xffff0000, v170
	v_lshlrev_b32_e32 v116, 16, v172
	v_and_b32_e32 v117, 0xffff0000, v172
	v_lshlrev_b32_e32 v118, 16, v173
	v_and_b32_e32 v119, 0xffff0000, v173
	v_pk_fma_f32 v[94:95], v[94:95], v[120:121], v[112:113]
	v_pk_fma_f32 v[112:113], v[92:93], v[130:131], v[118:119]
	v_pk_fma_f32 v[92:93], v[90:91], v[122:123], v[116:117]
	v_lshlrev_b32_e32 v119, 16, v127
	v_cvt_pk_bf16_f32 v92, v92, v93
	v_cvt_pk_bf16_f32 v93, v112, v113
	v_lshlrev_b32_e32 v113, 16, v126
	v_lshlrev_b32_e32 v117, 16, v128
	v_and_b32_e32 v116, 0xffff0000, v126
	v_and_b32_e32 v120, 0xffff0000, v128
	v_lshlrev_b32_e32 v122, 16, v129
	v_mul_f32_e32 v113, 0xbfb8aa3b, v113
	v_mul_f32_e32 v117, 0xbfb8aa3b, v117
	v_mul_f32_e32 v119, 0xbfb8aa3b, v119
	v_lshlrev_b32_e32 v114, 16, v171
	v_and_b32_e32 v115, 0xffff0000, v171
	v_exp_f32_e32 v118, v113
	v_exp_f32_e32 v117, v117
	v_mul_f32_e32 v116, 0xbfb8aa3b, v116
	v_mul_f32_e32 v120, 0xbfb8aa3b, v120
	v_exp_f32_e32 v119, v119
	v_mul_f32_e32 v122, 0xbfb8aa3b, v122
	v_pk_fma_f32 v[96:97], v[96:97], v[124:125], v[114:115]
	v_exp_f32_e32 v124, v116
	v_exp_f32_e32 v120, v120
	v_exp_f32_e32 v122, v122
	v_and_b32_e32 v121, 0xffff0000, v127
	v_and_b32_e32 v123, 0xffff0000, v129
	v_add_f32_e32 v118, 1.0, v118
	v_add_f32_e32 v117, 1.0, v117
	v_add_f32_e32 v119, 1.0, v119
	v_mul_f32_e32 v121, 0xbfb8aa3b, v121
	v_rcp_f32_e32 v116, v118
	v_rcp_f32_e32 v118, v117
	v_add_f32_e32 v117, 1.0, v124
	v_add_f32_e32 v124, 1.0, v120
	v_rcp_f32_e32 v120, v119
	v_add_f32_e32 v119, 1.0, v122
	v_exp_f32_e32 v121, v121
	v_mul_f32_e32 v122, 0xbfb8aa3b, v123
	v_exp_f32_e32 v123, v122
	v_rcp_f32_e32 v122, v119
	v_add_f32_e32 v119, 1.0, v121
	v_rcp_f32_e32 v121, v119
	v_add_f32_e32 v119, 1.0, v123
	v_rcp_f32_e32 v117, v117
	v_rcp_f32_e32 v123, v119
	v_rcp_f32_e32 v119, v124
	v_cvt_pk_bf16_f32 v90, v94, v95
	v_lshlrev_b32_e32 v94, 16, v134
	v_and_b32_e32 v95, 0xffff0000, v134
	v_lshlrev_b32_e32 v112, 16, v136
	v_and_b32_e32 v113, 0xffff0000, v136
	v_lshlrev_b32_e32 v114, 16, v137
	v_and_b32_e32 v115, 0xffff0000, v137
	v_pk_fma_f32 v[86:87], v[86:87], v[116:117], v[94:95]
	v_pk_fma_f32 v[94:95], v[84:85], v[122:123], v[114:115]
	v_pk_fma_f32 v[84:85], v[82:83], v[118:119], v[112:113]
	s_waitcnt vmcnt(6)
	v_lshlrev_b32_e32 v115, 16, v175
	v_cvt_pk_bf16_f32 v84, v84, v85
	v_cvt_pk_bf16_f32 v85, v94, v95
	v_lshlrev_b32_e32 v95, 16, v174
	v_lshlrev_b32_e32 v113, 16, v176
	v_and_b32_e32 v112, 0xffff0000, v174
	v_and_b32_e32 v116, 0xffff0000, v176
	v_lshlrev_b32_e32 v118, 16, v177
	v_mul_f32_e32 v95, 0xbfb8aa3b, v95
	v_mul_f32_e32 v113, 0xbfb8aa3b, v113
	v_mul_f32_e32 v115, 0xbfb8aa3b, v115
	v_cvt_pk_bf16_f32 v91, v96, v97
	v_lshlrev_b32_e32 v96, 16, v135
	v_and_b32_e32 v97, 0xffff0000, v135
	v_exp_f32_e32 v114, v95
	v_exp_f32_e32 v113, v113
	v_mul_f32_e32 v112, 0xbfb8aa3b, v112
	v_mul_f32_e32 v116, 0xbfb8aa3b, v116
	v_exp_f32_e32 v115, v115
	v_mul_f32_e32 v118, 0xbfb8aa3b, v118
	v_pk_fma_f32 v[88:89], v[88:89], v[120:121], v[96:97]
	v_exp_f32_e32 v120, v112
	v_exp_f32_e32 v116, v116
	v_exp_f32_e32 v118, v118
	v_and_b32_e32 v117, 0xffff0000, v175
	v_and_b32_e32 v119, 0xffff0000, v177
	v_add_f32_e32 v114, 1.0, v114
	v_add_f32_e32 v113, 1.0, v113
	v_add_f32_e32 v115, 1.0, v115
	v_mul_f32_e32 v117, 0xbfb8aa3b, v117
	v_rcp_f32_e32 v112, v114
	v_rcp_f32_e32 v114, v113
	v_add_f32_e32 v113, 1.0, v120
	v_add_f32_e32 v120, 1.0, v116
	v_rcp_f32_e32 v116, v115
	v_add_f32_e32 v115, 1.0, v118
	v_exp_f32_e32 v117, v117
	v_mul_f32_e32 v118, 0xbfb8aa3b, v119
	v_exp_f32_e32 v119, v118
	v_rcp_f32_e32 v118, v115
	v_add_f32_e32 v115, 1.0, v117
	v_rcp_f32_e32 v117, v115
	v_add_f32_e32 v115, 1.0, v119
	v_rcp_f32_e32 v113, v113
	v_rcp_f32_e32 v119, v115
	v_rcp_f32_e32 v115, v120
	v_cvt_pk_bf16_f32 v82, v86, v87
	v_cvt_pk_bf16_f32 v83, v88, v89
	s_waitcnt vmcnt(4)
	v_lshlrev_b32_e32 v86, 16, v178
	v_and_b32_e32 v87, 0xffff0000, v178
	v_lshlrev_b32_e32 v88, 16, v179
	v_and_b32_e32 v89, 0xffff0000, v179
	v_lshlrev_b32_e32 v94, 16, v180
	v_and_b32_e32 v95, 0xffff0000, v180
	v_pk_fma_f32 v[80:81], v[80:81], v[116:117], v[88:89]
	v_pk_fma_f32 v[78:79], v[78:79], v[112:113], v[86:87]
	v_pk_fma_f32 v[74:75], v[74:75], v[114:115], v[94:95]
	v_lshlrev_b32_e32 v96, 16, v181
	v_and_b32_e32 v97, 0xffff0000, v181
	v_cvt_pk_bf16_f32 v78, v78, v79
	v_cvt_pk_bf16_f32 v79, v80, v81
	v_cvt_pk_bf16_f32 v80, v74, v75
	v_add_u32_e32 v74, 0x80, v156
	v_pk_fma_f32 v[76:77], v[76:77], v[118:119], v[96:97]
	v_ashrrev_i32_e32 v75, 31, v74
	v_cvt_pk_bf16_f32 v81, v76, v77
	v_lshlrev_b64 v[76:77], 10, v[74:75]
	v_lshl_add_u64 v[76:77], v[76:77], 0, v[154:155]
	v_lshlrev_b64 v[76:77], 1, v[76:77]
	v_lshlrev_b32_e32 v118, 16, v102
	v_and_b32_e32 v119, 0xffff0000, v102
	v_lshlrev_b32_e32 v121, 16, v103
	v_and_b32_e32 v123, 0xffff0000, v103
	v_or_b32_e32 v102, 0x100, v76
	v_mov_b32_e32 v103, v77
	v_lshl_add_u64 v[86:87], s[8:9], 0, v[102:103]
	v_lshl_add_u64 v[94:95], s[8:9], 0, v[76:77]
	global_load_dwordx4 v[86:89], v[86:87], off nt
	s_nop 0
	global_load_dwordx4 v[94:97], v[94:95], off nt
	v_and_b32_e32 v122, 0xffff0000, v104
	v_lshlrev_b32_e32 v124, 16, v105
	v_mul_f32_e32 v121, 0xbfb8aa3b, v121
	v_lshl_add_u64 v[102:103], s[10:11], 0, v[102:103]
	v_mul_f32_e32 v122, 0xbfb8aa3b, v122
	v_exp_f32_e32 v121, v121
	v_mul_f32_e32 v124, 0xbfb8aa3b, v124
	v_lshlrev_b32_e32 v120, 16, v104
	v_and_b32_e32 v125, 0xffff0000, v105
	v_lshl_add_u64 v[76:77], s[10:11], 0, v[76:77]
	global_load_dwordx4 v[102:105], v[102:103], off nt
	s_nop 0
	global_load_dwordx4 v[112:115], v[76:77], off nt
	v_exp_f32_e32 v122, v122
	v_exp_f32_e32 v124, v124
	v_add_f32_e32 v121, 1.0, v121
	v_mul_f32_e32 v123, 0xbfb8aa3b, v123
	v_mul_f32_e32 v120, 0xbfb8aa3b, v120
	v_add_f32_e32 v126, 1.0, v122
	v_rcp_f32_e32 v122, v121
	v_add_f32_e32 v121, 1.0, v124
	v_exp_f32_e32 v123, v123
	v_mul_f32_e32 v124, 0xbfb8aa3b, v125
	v_exp_f32_e32 v120, v120
	v_exp_f32_e32 v125, v124
	v_lshlrev_b32_e32 v76, 16, v99
	v_and_b32_e32 v77, 0xffff0000, v99
	v_mul_f32_e32 v99, 0xbfb8aa3b, v118
	v_mul_f32_e32 v119, 0xbfb8aa3b, v119
	v_rcp_f32_e32 v124, v121
	v_add_f32_e32 v121, 1.0, v123
	v_exp_f32_e32 v118, v99
	v_exp_f32_e32 v119, v119
	v_add_f32_e32 v120, 1.0, v120
	v_rcp_f32_e32 v123, v121
	v_add_f32_e32 v121, 1.0, v125
	v_rcp_f32_e32 v120, v120
	v_rcp_f32_e32 v125, v121
	v_rcp_f32_e32 v121, v126
	v_lshlrev_b32_e32 v116, 16, v98
	v_and_b32_e32 v117, 0xffff0000, v98
	v_lshlrev_b32_e32 v98, 16, v100
	v_and_b32_e32 v99, 0xffff0000, v100
	v_add_f32_e32 v118, 1.0, v118
	v_add_f32_e32 v119, 1.0, v119
	v_pk_fma_f32 v[72:73], v[72:73], v[122:123], v[76:77]
	v_add_u32_e32 v76, 0x90, v156
	v_lshlrev_b32_e32 v100, 16, v101
	v_and_b32_e32 v101, 0xffff0000, v101
	v_rcp_f32_e32 v118, v118
	v_rcp_f32_e32 v119, v119
	v_pk_fma_f32 v[66:67], v[66:67], v[120:121], v[98:99]
	v_ashrrev_i32_e32 v77, 31, v76
	v_pk_fma_f32 v[68:69], v[68:69], v[124:125], v[100:101]
	v_cvt_pk_bf16_f32 v100, v66, v67
	v_lshlrev_b64 v[66:67], 10, v[76:77]
	v_lshl_add_u64 v[66:67], v[66:67], 0, v[154:155]
	v_lshlrev_b64 v[66:67], 1, v[66:67]
	v_pk_fma_f32 v[70:71], v[70:71], v[118:119], v[116:117]
	v_cvt_pk_bf16_f32 v101, v68, v69
	v_or_b32_e32 v68, 0x100, v66
	v_mov_b32_e32 v69, v67
	v_cvt_pk_bf16_f32 v98, v70, v71
	v_lshl_add_u64 v[70:71], s[8:9], 0, v[68:69]
	v_lshl_add_u64 v[116:117], s[8:9], 0, v[66:67]
	v_cvt_pk_bf16_f32 v99, v72, v73
	global_load_dwordx4 v[70:73], v[70:71], off nt
	s_nop 0
	global_load_dwordx4 v[116:119], v[116:117], off nt
	v_lshl_add_u64 v[68:69], s[10:11], 0, v[68:69]
	v_lshl_add_u64 v[120:121], s[10:11], 0, v[66:67]
	global_load_dwordx4 v[66:69], v[68:69], off nt
	s_nop 0
	global_load_dwordx4 v[120:123], v[120:121], off nt
	v_lshl_add_u64 v[108:109], v[108:109], 0, v[106:107]
	global_store_dwordx4 v[108:109], v[90:93], off nt
	global_store_dwordx4 v[108:109], v[82:85], off offset:256 nt
	v_lshlrev_b64 v[74:75], 11, v[74:75]
	v_lshl_add_u64 v[74:75], s[12:13], 0, v[74:75]
	v_lshlrev_b64 v[82:83], 11, v[110:111]
	v_lshl_add_u64 v[82:83], s[12:13], 0, v[82:83]
	v_lshl_add_u64 v[82:83], v[82:83], 0, v[106:107]
	global_store_dwordx4 v[82:83], v[78:81], off nt
	global_store_dwordx4 v[82:83], v[98:101], off offset:256 nt
	v_lshl_add_u64 v[74:75], v[74:75], 0, v[106:107]
	s_waitcnt vmcnt(10)
	v_lshlrev_b32_e32 v83, 16, v94
	v_lshlrev_b32_e32 v93, 16, v95
	v_lshlrev_b32_e32 v91, 16, v96
	v_and_b32_e32 v90, 0xffff0000, v94
	v_and_b32_e32 v94, 0xffff0000, v96
	v_lshlrev_b32_e32 v96, 16, v97
	v_mul_f32_e32 v83, 0xbfb8aa3b, v83
	v_mul_f32_e32 v91, 0xbfb8aa3b, v91
	v_mul_f32_e32 v93, 0xbfb8aa3b, v93
	v_exp_f32_e32 v92, v83
	v_exp_f32_e32 v91, v91
	v_mul_f32_e32 v90, 0xbfb8aa3b, v90
	v_mul_f32_e32 v94, 0xbfb8aa3b, v94
	v_exp_f32_e32 v93, v93
	v_mul_f32_e32 v96, 0xbfb8aa3b, v96
	v_exp_f32_e32 v98, v90
	v_exp_f32_e32 v94, v94
	v_exp_f32_e32 v96, v96
	v_and_b32_e32 v95, 0xffff0000, v95
	v_and_b32_e32 v97, 0xffff0000, v97
	v_add_f32_e32 v92, 1.0, v92
	v_add_f32_e32 v91, 1.0, v91
	v_add_f32_e32 v93, 1.0, v93
	v_mul_f32_e32 v95, 0xbfb8aa3b, v95
	v_rcp_f32_e32 v90, v92
	v_rcp_f32_e32 v92, v91
	v_add_f32_e32 v91, 1.0, v98
	v_add_f32_e32 v98, 1.0, v94
	v_rcp_f32_e32 v94, v93
	v_add_f32_e32 v93, 1.0, v96
	v_exp_f32_e32 v95, v95
	v_mul_f32_e32 v96, 0xbfb8aa3b, v97
	v_exp_f32_e32 v97, v96
	v_rcp_f32_e32 v96, v93
	v_add_f32_e32 v93, 1.0, v95
	v_rcp_f32_e32 v95, v93
	v_add_f32_e32 v93, 1.0, v97
	v_rcp_f32_e32 v91, v91
	v_rcp_f32_e32 v97, v93
	v_rcp_f32_e32 v93, v98
	s_waitcnt vmcnt(8)
	v_lshlrev_b32_e32 v78, 16, v112
	v_and_b32_e32 v79, 0xffff0000, v112
	v_lshlrev_b32_e32 v82, 16, v114
	v_and_b32_e32 v83, 0xffff0000, v114
	v_lshlrev_b32_e32 v84, 16, v115
	v_and_b32_e32 v85, 0xffff0000, v115
	v_pk_fma_f32 v[62:63], v[62:63], v[90:91], v[78:79]
	v_pk_fma_f32 v[78:79], v[60:61], v[96:97], v[84:85]
	v_pk_fma_f32 v[60:61], v[58:59], v[92:93], v[82:83]
	v_lshlrev_b32_e32 v85, 16, v87
	v_cvt_pk_bf16_f32 v60, v60, v61
	v_cvt_pk_bf16_f32 v61, v78, v79
	v_lshlrev_b32_e32 v79, 16, v86
	v_lshlrev_b32_e32 v83, 16, v88
	v_and_b32_e32 v82, 0xffff0000, v86
	v_and_b32_e32 v86, 0xffff0000, v88
	v_lshlrev_b32_e32 v88, 16, v89
	v_mul_f32_e32 v79, 0xbfb8aa3b, v79
	v_mul_f32_e32 v83, 0xbfb8aa3b, v83
	v_mul_f32_e32 v85, 0xbfb8aa3b, v85
	v_exp_f32_e32 v84, v79
	v_exp_f32_e32 v83, v83
	v_mul_f32_e32 v82, 0xbfb8aa3b, v82
	v_mul_f32_e32 v86, 0xbfb8aa3b, v86
	v_exp_f32_e32 v85, v85
	v_mul_f32_e32 v88, 0xbfb8aa3b, v88
	v_exp_f32_e32 v90, v82
	v_exp_f32_e32 v86, v86
	v_exp_f32_e32 v88, v88
	v_and_b32_e32 v87, 0xffff0000, v87
	v_and_b32_e32 v89, 0xffff0000, v89
	v_add_f32_e32 v84, 1.0, v84
	v_add_f32_e32 v83, 1.0, v83
	v_add_f32_e32 v85, 1.0, v85
	v_mul_f32_e32 v87, 0xbfb8aa3b, v87
	v_rcp_f32_e32 v82, v84
	v_rcp_f32_e32 v84, v83
	v_add_f32_e32 v83, 1.0, v90
	v_add_f32_e32 v90, 1.0, v86
	v_rcp_f32_e32 v86, v85
	v_add_f32_e32 v85, 1.0, v88
	v_exp_f32_e32 v87, v87
	v_mul_f32_e32 v88, 0xbfb8aa3b, v89
	v_exp_f32_e32 v89, v88
	v_rcp_f32_e32 v88, v85
	v_add_f32_e32 v85, 1.0, v87
	v_rcp_f32_e32 v87, v85
	v_add_f32_e32 v85, 1.0, v89
	v_rcp_f32_e32 v83, v83
	v_rcp_f32_e32 v89, v85
	v_rcp_f32_e32 v85, v90
	v_lshlrev_b32_e32 v80, 16, v113
	v_and_b32_e32 v81, 0xffff0000, v113
	v_pk_fma_f32 v[64:65], v[64:65], v[94:95], v[80:81]
	v_cvt_pk_bf16_f32 v58, v62, v63
	v_lshlrev_b32_e32 v62, 16, v102
	v_and_b32_e32 v63, 0xffff0000, v102
	v_lshlrev_b32_e32 v78, 16, v104
	v_and_b32_e32 v79, 0xffff0000, v104
	v_lshlrev_b32_e32 v80, 16, v105
	v_and_b32_e32 v81, 0xffff0000, v105
	v_pk_fma_f32 v[54:55], v[54:55], v[82:83], v[62:63]
	v_pk_fma_f32 v[62:63], v[52:53], v[88:89], v[80:81]
	v_pk_fma_f32 v[52:53], v[50:51], v[84:85], v[78:79]
	s_waitcnt vmcnt(6)
	v_lshlrev_b32_e32 v81, 16, v117
	v_cvt_pk_bf16_f32 v52, v52, v53
	v_cvt_pk_bf16_f32 v53, v62, v63
	v_lshlrev_b32_e32 v63, 16, v116
	v_lshlrev_b32_e32 v79, 16, v118
	v_and_b32_e32 v78, 0xffff0000, v116
	v_and_b32_e32 v82, 0xffff0000, v118
	v_lshlrev_b32_e32 v84, 16, v119
	v_mul_f32_e32 v63, 0xbfb8aa3b, v63
	v_mul_f32_e32 v79, 0xbfb8aa3b, v79
	v_mul_f32_e32 v81, 0xbfb8aa3b, v81
	v_cvt_pk_bf16_f32 v59, v64, v65
	v_lshlrev_b32_e32 v64, 16, v103
	v_and_b32_e32 v65, 0xffff0000, v103
	v_exp_f32_e32 v80, v63
	v_exp_f32_e32 v79, v79
	v_mul_f32_e32 v78, 0xbfb8aa3b, v78
	v_mul_f32_e32 v82, 0xbfb8aa3b, v82
	v_exp_f32_e32 v81, v81
	v_mul_f32_e32 v84, 0xbfb8aa3b, v84
	v_pk_fma_f32 v[56:57], v[56:57], v[86:87], v[64:65]
	v_exp_f32_e32 v86, v78
	v_exp_f32_e32 v82, v82
	v_exp_f32_e32 v84, v84
	v_and_b32_e32 v83, 0xffff0000, v117
	v_and_b32_e32 v85, 0xffff0000, v119
	v_add_f32_e32 v80, 1.0, v80
	v_add_f32_e32 v79, 1.0, v79
	v_add_f32_e32 v81, 1.0, v81
	v_mul_f32_e32 v83, 0xbfb8aa3b, v83
	v_rcp_f32_e32 v78, v80
	v_rcp_f32_e32 v80, v79
	v_add_f32_e32 v79, 1.0, v86
	v_add_f32_e32 v86, 1.0, v82
	v_rcp_f32_e32 v82, v81
	v_add_f32_e32 v81, 1.0, v84
	v_exp_f32_e32 v83, v83
	v_mul_f32_e32 v84, 0xbfb8aa3b, v85
	v_exp_f32_e32 v85, v84
	v_rcp_f32_e32 v84, v81
	v_add_f32_e32 v81, 1.0, v83
	v_rcp_f32_e32 v79, v79
	v_rcp_f32_e32 v83, v81
	v_add_f32_e32 v81, 1.0, v85
	v_rcp_f32_e32 v85, v81
	v_rcp_f32_e32 v81, v86
	v_cvt_pk_bf16_f32 v50, v54, v55
	s_waitcnt vmcnt(4)
	v_lshlrev_b32_e32 v54, 16, v120
	v_and_b32_e32 v55, 0xffff0000, v120
	v_lshlrev_b32_e32 v62, 16, v122
	v_and_b32_e32 v63, 0xffff0000, v122
	v_pk_fma_f32 v[46:47], v[46:47], v[78:79], v[54:55]
	v_add_u32_e32 v54, 0xb0, v156
	v_lshlrev_b32_e32 v64, 16, v123
	v_and_b32_e32 v65, 0xffff0000, v123
	v_pk_fma_f32 v[42:43], v[42:43], v[80:81], v[62:63]
	v_ashrrev_i32_e32 v55, 31, v54
	v_pk_fma_f32 v[44:45], v[44:45], v[84:85], v[64:65]
	v_cvt_pk_bf16_f32 v64, v42, v43
	v_lshlrev_b64 v[42:43], 10, v[54:55]
	v_lshl_add_u64 v[42:43], v[42:43], 0, v[154:155]
	v_cvt_pk_bf16_f32 v62, v46, v47
	v_lshlrev_b64 v[46:47], 1, v[42:43]
	v_or_b32_e32 v42, 0x100, v46
	v_mov_b32_e32 v43, v47
	v_cvt_pk_bf16_f32 v65, v44, v45
	v_lshlrev_b32_e32 v85, 16, v72
	v_lshl_add_u64 v[44:45], s[8:9], 0, v[42:43]
	v_cvt_pk_bf16_f32 v51, v56, v57
	v_lshlrev_b32_e32 v56, 16, v121
	v_and_b32_e32 v57, 0xffff0000, v121
	global_load_dwordx4 v[78:81], v[44:45], off nt
	v_lshlrev_b32_e32 v44, 16, v66
	v_and_b32_e32 v45, 0xffff0000, v66
	v_mul_f32_e32 v66, 0xbfb8aa3b, v85
	v_pk_fma_f32 v[48:49], v[48:49], v[82:83], v[56:57]
	v_and_b32_e32 v57, 0xffff0000, v70
	v_exp_f32_e32 v66, v66
	v_mul_f32_e32 v57, 0xbfb8aa3b, v57
	v_exp_f32_e32 v57, v57
	v_and_b32_e32 v72, 0xffff0000, v72
	v_add_f32_e32 v66, 1.0, v66
	v_lshl_add_u64 v[42:43], s[10:11], 0, v[42:43]
	v_cvt_pk_bf16_f32 v63, v48, v49
	v_lshlrev_b32_e32 v56, 16, v70
	v_lshlrev_b32_e32 v70, 16, v71
	v_lshlrev_b32_e32 v48, 16, v67
	v_and_b32_e32 v49, 0xffff0000, v67
	v_lshlrev_b32_e32 v82, 16, v68
	v_and_b32_e32 v83, 0xffff0000, v68
	v_lshlrev_b32_e32 v84, 16, v69
	v_and_b32_e32 v85, 0xffff0000, v69
	v_rcp_f32_e32 v86, v66
	global_load_dwordx4 v[66:69], v[42:43], off nt
	v_mul_f32_e32 v43, 0xbfb8aa3b, v72
	v_add_f32_e32 v42, 1.0, v57
	v_exp_f32_e32 v43, v43
	v_mul_f32_e32 v57, 0xbfb8aa3b, v70
	v_exp_f32_e32 v70, v57
	v_lshlrev_b32_e32 v88, 16, v73
	v_mul_f32_e32 v56, 0xbfb8aa3b, v56
	v_and_b32_e32 v71, 0xffff0000, v71
	v_exp_f32_e32 v56, v56
	v_rcp_f32_e32 v57, v42
	v_add_f32_e32 v42, 1.0, v43
	v_mul_f32_e32 v43, 0xbfb8aa3b, v88
	v_rcp_f32_e32 v87, v42
	v_add_f32_e32 v42, 1.0, v70
	v_exp_f32_e32 v43, v43
	v_mul_f32_e32 v70, 0xbfb8aa3b, v71
	v_exp_f32_e32 v70, v70
	v_and_b32_e32 v73, 0xffff0000, v73
	v_add_f32_e32 v56, 1.0, v56
	v_rcp_f32_e32 v56, v56
	v_add_f32_e32 v71, 1.0, v43
	v_mul_f32_e32 v43, 0xbfb8aa3b, v73
	v_exp_f32_e32 v72, v43
	v_add_f32_e32 v43, 1.0, v70
	v_rcp_f32_e32 v42, v42
	v_rcp_f32_e32 v43, v43
	v_pk_fma_f32 v[38:39], v[38:39], v[56:57], v[44:45]
	v_add_u32_e32 v56, 0xa0, v156
	v_ashrrev_i32_e32 v57, 31, v56
	v_pk_fma_f32 v[40:41], v[40:41], v[42:43], v[48:49]
	v_lshlrev_b64 v[42:43], 10, v[56:57]
	v_lshl_add_u64 v[42:43], v[42:43], 0, v[154:155]
	v_lshlrev_b64 v[48:49], 1, v[42:43]
	v_add_f32_e32 v70, 1.0, v72
	v_or_b32_e32 v90, 0x100, v48
	v_mov_b32_e32 v91, v49
	v_rcp_f32_e32 v88, v71
	v_rcp_f32_e32 v89, v70
	v_lshl_add_u64 v[42:43], s[8:9], 0, v[90:91]
	v_lshl_add_u64 v[70:71], s[8:9], 0, v[46:47]
	global_load_dwordx4 v[42:45], v[42:43], off nt
	s_nop 0
	global_load_dwordx4 v[70:73], v[70:71], off nt
	v_pk_fma_f32 v[34:35], v[34:35], v[86:87], v[82:83]
	v_pk_fma_f32 v[36:37], v[36:37], v[88:89], v[84:85]
	v_cvt_pk_bf16_f32 v84, v34, v35
	v_lshl_add_u64 v[34:35], s[8:9], 0, v[48:49]
	v_cvt_pk_bf16_f32 v82, v38, v39
	v_cvt_pk_bf16_f32 v83, v40, v41
	global_load_dwordx4 v[38:41], v[34:35], off nt
	v_lshl_add_u64 v[34:35], s[10:11], 0, v[46:47]
	global_load_dwordx4 v[86:89], v[34:35], off nt
	v_cvt_pk_bf16_f32 v85, v36, v37
	v_lshl_add_u64 v[34:35], s[10:11], 0, v[90:91]
	v_lshl_add_u64 v[36:37], s[10:11], 0, v[48:49]
	global_load_dwordx4 v[46:49], v[34:35], off nt
	s_nop 0
	global_load_dwordx4 v[34:37], v[36:37], off nt
	s_nop 0
	global_store_dwordx4 v[74:75], v[58:61], off nt
	global_store_dwordx4 v[74:75], v[50:53], off offset:256 nt
	s_waitcnt vmcnt(8)
	v_lshlrev_b32_e32 v58, 16, v66
	v_lshlrev_b32_e32 v52, 16, v78
	v_and_b32_e32 v53, 0xffff0000, v78
	v_mul_f32_e32 v52, 0xbfb8aa3b, v52
	v_mul_f32_e32 v53, 0xbfb8aa3b, v53
	v_exp_f32_e32 v52, v52
	v_exp_f32_e32 v53, v53
	v_lshlrev_b64 v[50:51], 11, v[76:77]
	v_lshl_add_u64 v[50:51], s[12:13], 0, v[50:51]
	v_lshl_add_u64 v[50:51], v[50:51], 0, v[106:107]
	global_store_dwordx4 v[50:51], v[62:65], off nt
	global_store_dwordx4 v[50:51], v[82:85], off offset:256 nt
	v_add_f32_e32 v50, 1.0, v52
	v_add_f32_e32 v51, 1.0, v53
	v_rcp_f32_e32 v50, v50
	v_rcp_f32_e32 v51, v51
	v_lshlrev_b32_e32 v52, 16, v79
	v_and_b32_e32 v53, 0xffff0000, v79
	v_mul_f32_e32 v52, 0xbfb8aa3b, v52
	v_mul_f32_e32 v53, 0xbfb8aa3b, v53
	v_exp_f32_e32 v52, v52
	v_exp_f32_e32 v53, v53
	v_and_b32_e32 v59, 0xffff0000, v66
	v_pk_fma_f32 v[30:31], v[30:31], v[50:51], v[58:59]
	v_add_f32_e32 v52, 1.0, v52
	v_cvt_pk_bf16_f32 v30, v30, v31
	v_lshlrev_b32_e32 v31, 16, v80
	v_mul_f32_e32 v31, 0xbfb8aa3b, v31
	v_add_f32_e32 v53, 1.0, v53
	v_exp_f32_e32 v50, v31
	v_and_b32_e32 v31, 0xffff0000, v80
	v_rcp_f32_e32 v52, v52
	v_rcp_f32_e32 v53, v53
	v_mul_f32_e32 v31, 0xbfb8aa3b, v31
	v_exp_f32_e32 v51, v31
	v_lshlrev_b32_e32 v60, 16, v67
	v_and_b32_e32 v61, 0xffff0000, v67
	v_pk_fma_f32 v[32:33], v[32:33], v[52:53], v[60:61]
	v_lshlrev_b32_e32 v52, 16, v68
	v_cvt_pk_bf16_f32 v31, v32, v33
	v_add_f32_e32 v32, 1.0, v50
	v_add_f32_e32 v33, 1.0, v51
	v_rcp_f32_e32 v32, v32
	v_rcp_f32_e32 v33, v33
	v_lshlrev_b32_e32 v50, 16, v81
	v_and_b32_e32 v51, 0xffff0000, v81
	v_mul_f32_e32 v50, 0xbfb8aa3b, v50
	v_mul_f32_e32 v51, 0xbfb8aa3b, v51
	v_exp_f32_e32 v50, v50
	v_exp_f32_e32 v51, v51
	v_and_b32_e32 v53, 0xffff0000, v68
	v_pk_fma_f32 v[26:27], v[26:27], v[32:33], v[52:53]
	v_add_f32_e32 v50, 1.0, v50
	v_cvt_pk_bf16_f32 v32, v26, v27
	s_waitcnt vmcnt(8)
	v_lshlrev_b32_e32 v26, 16, v70
	v_and_b32_e32 v27, 0xffff0000, v70
	v_mul_f32_e32 v26, 0xbfb8aa3b, v26
	v_mul_f32_e32 v27, 0xbfb8aa3b, v27
	v_add_f32_e32 v51, 1.0, v51
	v_exp_f32_e32 v26, v26
	v_exp_f32_e32 v27, v27
	v_rcp_f32_e32 v50, v50
	v_rcp_f32_e32 v51, v51
	v_lshlrev_b32_e32 v58, 16, v69
	v_and_b32_e32 v59, 0xffff0000, v69
	v_add_f32_e32 v26, 1.0, v26
	v_add_f32_e32 v27, 1.0, v27
	v_pk_fma_f32 v[28:29], v[28:29], v[50:51], v[58:59]
	v_rcp_f32_e32 v26, v26
	v_rcp_f32_e32 v27, v27
	v_cvt_pk_bf16_f32 v33, v28, v29
	v_lshlrev_b32_e32 v28, 16, v71
	v_and_b32_e32 v29, 0xffff0000, v71
	v_mul_f32_e32 v28, 0xbfb8aa3b, v28
	v_mul_f32_e32 v29, 0xbfb8aa3b, v29
	v_exp_f32_e32 v28, v28
	v_exp_f32_e32 v29, v29
	s_waitcnt vmcnt(6)
	v_lshlrev_b32_e32 v50, 16, v86
	v_and_b32_e32 v51, 0xffff0000, v86
	v_pk_fma_f32 v[22:23], v[22:23], v[26:27], v[50:51]
	v_add_f32_e32 v28, 1.0, v28
	v_cvt_pk_bf16_f32 v22, v22, v23
	v_lshlrev_b32_e32 v23, 16, v72
	v_mul_f32_e32 v23, 0xbfb8aa3b, v23
	v_add_f32_e32 v29, 1.0, v29
	v_exp_f32_e32 v26, v23
	v_and_b32_e32 v23, 0xffff0000, v72
	v_rcp_f32_e32 v28, v28
	v_rcp_f32_e32 v29, v29
	v_mul_f32_e32 v23, 0xbfb8aa3b, v23
	v_exp_f32_e32 v27, v23
	v_lshlrev_b32_e32 v52, 16, v87
	v_and_b32_e32 v53, 0xffff0000, v87
	v_pk_fma_f32 v[24:25], v[24:25], v[28:29], v[52:53]
	v_lshlrev_b32_e32 v28, 16, v88
	v_cvt_pk_bf16_f32 v23, v24, v25
	v_add_f32_e32 v24, 1.0, v26
	v_add_f32_e32 v25, 1.0, v27
	v_rcp_f32_e32 v24, v24
	v_rcp_f32_e32 v25, v25
	v_lshlrev_b32_e32 v26, 16, v73
	v_and_b32_e32 v27, 0xffff0000, v73
	v_mul_f32_e32 v26, 0xbfb8aa3b, v26
	v_mul_f32_e32 v27, 0xbfb8aa3b, v27
	v_exp_f32_e32 v26, v26
	v_exp_f32_e32 v27, v27
	v_and_b32_e32 v29, 0xffff0000, v88
	v_pk_fma_f32 v[18:19], v[18:19], v[24:25], v[28:29]
	v_add_f32_e32 v26, 1.0, v26
	v_cvt_pk_bf16_f32 v24, v18, v19
	v_lshlrev_b32_e32 v18, 16, v42
	v_and_b32_e32 v19, 0xffff0000, v42
	v_mul_f32_e32 v18, 0xbfb8aa3b, v18
	v_mul_f32_e32 v19, 0xbfb8aa3b, v19
	v_add_f32_e32 v27, 1.0, v27
	v_exp_f32_e32 v18, v18
	v_exp_f32_e32 v19, v19
	v_rcp_f32_e32 v26, v26
	v_rcp_f32_e32 v27, v27
	v_lshlrev_b32_e32 v50, 16, v89
	v_and_b32_e32 v51, 0xffff0000, v89
	v_add_f32_e32 v18, 1.0, v18
	v_add_f32_e32 v19, 1.0, v19
	v_pk_fma_f32 v[20:21], v[20:21], v[26:27], v[50:51]
	v_rcp_f32_e32 v18, v18
	v_rcp_f32_e32 v19, v19
	v_cvt_pk_bf16_f32 v25, v20, v21
	v_lshlrev_b32_e32 v20, 16, v43
	v_and_b32_e32 v21, 0xffff0000, v43
	v_mul_f32_e32 v20, 0xbfb8aa3b, v20
	v_mul_f32_e32 v21, 0xbfb8aa3b, v21
	v_exp_f32_e32 v20, v20
	v_exp_f32_e32 v21, v21
	s_waitcnt vmcnt(5)
	v_lshlrev_b32_e32 v26, 16, v46
	v_and_b32_e32 v27, 0xffff0000, v46
	v_pk_fma_f32 v[14:15], v[14:15], v[18:19], v[26:27]
	v_add_f32_e32 v20, 1.0, v20
	v_cvt_pk_bf16_f32 v14, v14, v15
	v_lshlrev_b32_e32 v15, 16, v44
	v_mul_f32_e32 v15, 0xbfb8aa3b, v15
	v_add_f32_e32 v21, 1.0, v21
	v_exp_f32_e32 v18, v15
	v_and_b32_e32 v15, 0xffff0000, v44
	v_rcp_f32_e32 v20, v20
	v_rcp_f32_e32 v21, v21
	v_mul_f32_e32 v15, 0xbfb8aa3b, v15
	v_exp_f32_e32 v19, v15
	v_lshlrev_b32_e32 v28, 16, v47
	v_and_b32_e32 v29, 0xffff0000, v47
	v_pk_fma_f32 v[16:17], v[16:17], v[20:21], v[28:29]
	v_lshlrev_b32_e32 v20, 16, v48
	v_cvt_pk_bf16_f32 v15, v16, v17
	v_add_f32_e32 v16, 1.0, v18
	v_add_f32_e32 v17, 1.0, v19
	v_rcp_f32_e32 v16, v16
	v_rcp_f32_e32 v17, v17
	v_lshlrev_b32_e32 v18, 16, v45
	v_and_b32_e32 v19, 0xffff0000, v45
	v_mul_f32_e32 v18, 0xbfb8aa3b, v18
	v_mul_f32_e32 v19, 0xbfb8aa3b, v19
	v_exp_f32_e32 v18, v18
	v_exp_f32_e32 v19, v19
	v_and_b32_e32 v21, 0xffff0000, v48
	v_pk_fma_f32 v[10:11], v[10:11], v[16:17], v[20:21]
	v_add_f32_e32 v18, 1.0, v18
	v_cvt_pk_bf16_f32 v16, v10, v11
	v_lshlrev_b32_e32 v10, 16, v38
	v_and_b32_e32 v11, 0xffff0000, v38
	v_mul_f32_e32 v10, 0xbfb8aa3b, v10
	v_mul_f32_e32 v11, 0xbfb8aa3b, v11
	v_add_f32_e32 v19, 1.0, v19
	v_exp_f32_e32 v10, v10
	v_exp_f32_e32 v11, v11
	v_rcp_f32_e32 v18, v18
	v_rcp_f32_e32 v19, v19
	v_lshlrev_b32_e32 v26, 16, v49
	v_and_b32_e32 v27, 0xffff0000, v49
	v_add_f32_e32 v10, 1.0, v10
	v_add_f32_e32 v11, 1.0, v11
	v_pk_fma_f32 v[12:13], v[12:13], v[18:19], v[26:27]
	v_rcp_f32_e32 v10, v10
	v_rcp_f32_e32 v11, v11
	v_cvt_pk_bf16_f32 v17, v12, v13
	v_lshlrev_b32_e32 v12, 16, v39
	v_and_b32_e32 v13, 0xffff0000, v39
	v_mul_f32_e32 v12, 0xbfb8aa3b, v12
	v_mul_f32_e32 v13, 0xbfb8aa3b, v13
	v_exp_f32_e32 v12, v12
	v_exp_f32_e32 v13, v13
	s_waitcnt vmcnt(4)
	v_lshlrev_b32_e32 v18, 16, v34
	v_and_b32_e32 v19, 0xffff0000, v34
	v_pk_fma_f32 v[6:7], v[6:7], v[10:11], v[18:19]
	v_add_f32_e32 v12, 1.0, v12
	v_cvt_pk_bf16_f32 v6, v6, v7
	v_lshlrev_b32_e32 v7, 16, v40
	v_mul_f32_e32 v7, 0xbfb8aa3b, v7
	v_add_f32_e32 v13, 1.0, v13
	v_exp_f32_e32 v10, v7
	v_and_b32_e32 v7, 0xffff0000, v40
	v_rcp_f32_e32 v12, v12
	v_rcp_f32_e32 v13, v13
	v_mul_f32_e32 v7, 0xbfb8aa3b, v7
	v_exp_f32_e32 v11, v7
	v_lshlrev_b32_e32 v20, 16, v35
	v_and_b32_e32 v21, 0xffff0000, v35
	v_pk_fma_f32 v[8:9], v[8:9], v[12:13], v[20:21]
	v_lshlrev_b32_e32 v12, 16, v36
	v_cvt_pk_bf16_f32 v7, v8, v9
	v_add_f32_e32 v8, 1.0, v10
	v_add_f32_e32 v9, 1.0, v11
	v_lshlrev_b32_e32 v10, 16, v41
	v_and_b32_e32 v11, 0xffff0000, v41
	v_mul_f32_e32 v10, 0xbfb8aa3b, v10
	v_mul_f32_e32 v11, 0xbfb8aa3b, v11
	v_exp_f32_e32 v10, v10
	v_exp_f32_e32 v11, v11
	v_rcp_f32_e32 v8, v8
	v_rcp_f32_e32 v9, v9
	v_add_f32_e32 v10, 1.0, v10
	v_add_f32_e32 v11, 1.0, v11
	v_rcp_f32_e32 v10, v10
	v_rcp_f32_e32 v11, v11
	v_and_b32_e32 v13, 0xffff0000, v36
	v_pk_fma_f32 v[2:3], v[2:3], v[8:9], v[12:13]
	v_lshlrev_b32_e32 v18, 16, v37
	v_and_b32_e32 v19, 0xffff0000, v37
	v_cvt_pk_bf16_f32 v8, v2, v3
	v_lshlrev_b64 v[2:3], 11, v[56:57]
	v_pk_fma_f32 v[4:5], v[4:5], v[10:11], v[18:19]
	v_lshl_add_u64 v[2:3], s[12:13], 0, v[2:3]
	v_cvt_pk_bf16_f32 v9, v4, v5
	v_lshl_add_u64 v[2:3], v[2:3], 0, v[106:107]
	global_store_dwordx4 v[2:3], v[6:9], off nt
	global_store_dwordx4 v[2:3], v[14:17], off offset:256 nt
	v_lshlrev_b64 v[2:3], 11, v[54:55]
	v_lshl_add_u64 v[2:3], s[12:13], 0, v[2:3]
	v_lshl_add_u64 v[2:3], v[2:3], 0, v[106:107]
	global_store_dwordx4 v[2:3], v[22:25], off nt
	global_store_dwordx4 v[2:3], v[30:33], off offset:256 nt
	s_cbranch_vccnz .LBB0_788
	s_andn2_b64 vcc, exec, s[6:7]
	s_cbranch_vccnz .LBB0_787
	s_barrier
	s_branch .LBB0_787

.LBB0_878:
	v_lshl_add_u32 v180, s36, 8, v1
	v_lshl_or_b32 v178, s10, 8, v191
	v_ashrrev_i32_e32 v179, 31, v178
	v_ashrrev_i32_e32 v181, 31, v180
	v_lshl_add_u64 v[182:183], v[178:179], 2, s[8:9]
	v_lshlrev_b64 v[130:131], 12, v[180:181]
	v_or_b32_e32 v188, 16, v180
	v_lshl_add_u64 v[130:131], v[182:183], 0, v[130:131]
	v_ashrrev_i32_e32 v189, 31, v188
	global_load_dwordx4 v[196:199], v[130:131], off nt
	global_load_dwordx4 v[200:203], v[130:131], off offset:16 nt
	global_load_dwordx4 v[204:207], v[130:131], off offset:512 nt
	global_load_dwordx4 v[208:211], v[130:131], off offset:528 nt
	v_lshlrev_b64 v[130:131], 12, v[188:189]
	v_lshl_add_u64 v[130:131], v[182:183], 0, v[130:131]
	global_load_dwordx4 v[212:215], v[130:131], off nt
	global_load_dwordx4 v[216:219], v[130:131], off offset:16 nt
	global_load_dwordx4 v[220:223], v[130:131], off offset:528 nt
	global_load_dwordx4 v[224:227], v[130:131], off offset:512 nt
	v_or_b32_e32 v186, 32, v180
	v_or_b32_e32 v184, 48, v180
	v_ashrrev_i32_e32 v187, 31, v186
	v_ashrrev_i32_e32 v185, 31, v184
	v_lshlrev_b64 v[130:131], 12, v[186:187]
	v_lshlrev_b64 v[132:133], 12, v[184:185]
	v_lshl_add_u64 v[130:131], v[182:183], 0, v[130:131]
	v_lshl_add_u64 v[134:135], v[182:183], 0, v[132:133]
	global_load_dwordx4 v[154:157], v[130:131], off offset:16 nt
	global_load_dwordx4 v[158:161], v[130:131], off nt
	global_load_dwordx4 v[146:149], v[130:131], off offset:528 nt
	global_load_dwordx4 v[150:153], v[130:131], off offset:512 nt
	global_load_dwordx4 v[138:141], v[134:135], off offset:16 nt
	global_load_dwordx4 v[142:145], v[134:135], off nt
	s_nop 0
	global_load_dwordx4 v[130:133], v[134:135], off offset:528 nt
	s_nop 0
	global_load_dwordx4 v[134:137], v[134:135], off offset:512 nt
	s_waitcnt vmcnt(0)
	v_pk_add_f32 v[128:129], v[128:129], v[198:199]
	v_pk_add_f32 v[126:127], v[126:127], v[196:197]
	v_pk_add_f32 v[196:197], v[124:125], v[202:203]
	v_pk_add_f32 v[198:199], v[122:123], v[200:201]
	v_pk_add_f32 v[202:203], v[114:115], v[204:205]
	v_pk_add_f32 v[106:107], v[106:107], v[208:209]
	v_pk_add_f32 v[200:201], v[116:117], v[206:207]
	v_cvt_pk_bf16_f32 v116, v198, v199
	v_mul_f32_e32 v195, v199, v199
	v_cvt_pk_bf16_f32 v122, v202, v203
	v_mul_f32_e32 v199, v203, v203
	v_mul_f32_e32 v203, v107, v107
	v_pk_add_f32 v[120:121], v[120:121], v[214:215]
	v_pk_add_f32 v[118:119], v[118:119], v[212:213]
	v_cvt_pk_bf16_f32 v114, v126, v127
	v_mul_f32_e32 v127, v127, v127
	v_cvt_pk_bf16_f32 v124, v106, v107
	v_pk_add_f32 v[110:111], v[110:111], v[216:217]
	v_fmac_f32_e32 v203, v106, v106
	v_cvt_pk_bf16_f32 v106, v118, v119
	v_cvt_pk_bf16_f32 v107, v120, v121
	v_mul_f32_e32 v119, v119, v119
	v_mul_f32_e32 v121, v121, v121
	v_pk_add_f32 v[108:109], v[108:109], v[210:211]
	v_pk_add_f32 v[112:113], v[112:113], v[218:219]
	v_fmac_f32_e32 v127, v126, v126
	v_mul_f32_e32 v126, v111, v111
	v_fmac_f32_e32 v119, v118, v118
	v_fmac_f32_e32 v121, v120, v120
	v_cvt_pk_bf16_f32 v125, v108, v109
	v_mul_f32_e32 v204, v109, v109
	v_cvt_pk_bf16_f32 v109, v112, v113
	v_fmac_f32_e32 v126, v110, v110
	v_add_f32_e32 v118, v119, v121
	v_mul_f32_e32 v113, v113, v113
	v_add_f32_e32 v118, v118, v126
	v_fmac_f32_e32 v113, v112, v112
	v_pk_add_f32 v[102:103], v[102:103], v[224:225]
	v_add_f32_e32 v120, v113, v118
	v_pk_add_f32 v[104:105], v[104:105], v[226:227]
	v_pk_add_f32 v[118:119], v[98:99], v[220:221]
	v_cvt_pk_bf16_f32 v98, v102, v103
	v_mul_f32_e32 v103, v103, v103
	v_fmac_f32_e32 v103, v102, v102
	v_mul_f32_e32 v102, v105, v105
	v_fmac_f32_e32 v102, v104, v104
	v_add_f32_e32 v102, v103, v102
	v_mul_f32_e32 v103, v119, v119
	v_cvt_pk_bf16_f32 v115, v128, v129
	v_mul_f32_e32 v129, v129, v129
	v_cvt_pk_bf16_f32 v123, v200, v201
	v_mul_f32_e32 v201, v201, v201
	v_pk_add_f32 v[112:113], v[100:101], v[222:223]
	v_fmac_f32_e32 v103, v118, v118
	v_fmac_f32_e32 v129, v128, v128
	v_fmac_f32_e32 v199, v202, v202
	v_fmac_f32_e32 v201, v200, v200
	v_add_f32_e32 v102, v102, v103
	v_mul_f32_e32 v103, v113, v113
	v_cvt_pk_bf16_f32 v117, v196, v197
	v_mul_f32_e32 v197, v197, v197
	v_fmac_f32_e32 v195, v198, v198
	v_fmac_f32_e32 v204, v108, v108
	v_cvt_pk_bf16_f32 v108, v110, v111
	v_add_f32_e32 v111, v127, v129
	v_add_f32_e32 v127, v199, v201
	v_fmac_f32_e32 v103, v112, v112
	v_fmac_f32_e32 v197, v196, v196
	v_add_f32_e32 v110, v111, v195
	v_add_f32_e32 v111, v127, v203
	v_add_f32_e32 v102, v103, v102
	v_add_f32_e32 v110, v197, v110
	v_add_f32_e32 v111, v204, v111
	v_add_f32_e32 v102, v120, v102
	v_add_f32_e32 v110, v110, v111
	v_mov_b32_e32 v103, v102
	v_mov_b32_e32 v111, v110
	s_nop 0
	v_permlane16_swap_b32_e32 v102, v103
	v_permlane16_swap_b32_e32 v110, v111
	v_cvt_pk_bf16_f32 v99, v104, v105
	v_add_f32_e32 v104, v102, v103
	v_lshlrev_b64 v[102:103], 11, v[180:181]
	v_add_f32_e32 v110, v110, v111
	v_lshl_add_u64 v[102:103], s[14:15], 0, v[102:103]
	v_mov_b32_e32 v111, v110
	v_mov_b32_e32 v105, v104
	v_lshl_add_u64 v[120:121], v[178:179], 1, v[102:103]
	v_lshlrev_b64 v[102:103], 11, v[188:189]
	v_permlane32_swap_b32_e32 v110, v111
	v_cvt_pk_bf16_f32 v100, v118, v119
	v_cvt_pk_bf16_f32 v101, v112, v113
	v_permlane32_swap_b32_e32 v104, v105
	v_lshl_add_u64 v[102:103], s[14:15], 0, v[102:103]
	global_store_dwordx4 v[120:121], v[114:117], off nt
	global_store_dwordx4 v[120:121], v[122:125], off offset:256 nt
	s_and_saveexec_b64 s[0:1], s[2:3]
	s_xor_b64 s[0:1], exec, s[0:1]
	s_cbranch_execz .LBB0_880
	v_lshl_add_u64 v[102:103], v[178:179], 1, v[102:103]
	global_store_dwordx4 v[102:103], v[106:109], off nt
	global_store_dwordx4 v[102:103], v[98:101], off offset:256 nt

.LBB0_882:
	s_or_b64 exec, exec, s[36:37]
	v_pk_add_f32 v[94:95], v[94:95], v[158:159]
	v_pk_add_f32 v[96:97], v[96:97], v[160:161]
	v_pk_add_f32 v[90:91], v[90:91], v[154:155]
	v_cvt_pk_bf16_f32 v154, v94, v95
	v_mul_f32_e32 v95, v95, v95
	v_add_u32_e32 v126, 0x80, v180
	v_fmac_f32_e32 v95, v94, v94
	v_mul_f32_e32 v94, v97, v97
	v_ashrrev_i32_e32 v127, 31, v126
	v_pk_add_f32 v[92:93], v[92:93], v[156:157]
	v_cvt_pk_bf16_f32 v156, v90, v91
	v_fmac_f32_e32 v94, v96, v96
	v_mul_f32_e32 v91, v91, v91
	v_pk_add_f32 v[128:129], v[88:89], v[152:153]
	v_lshlrev_b64 v[88:89], 12, v[126:127]
	v_add_u32_e32 v124, 0x90, v180
	v_add_f32_e32 v94, v95, v94
	v_fmac_f32_e32 v91, v90, v90
	v_lshl_add_u64 v[88:89], v[182:183], 0, v[88:89]
	v_ashrrev_i32_e32 v125, 31, v124
	v_add_f32_e32 v90, v94, v91
	v_mul_f32_e32 v91, v93, v93
	global_load_dwordx4 v[112:115], v[88:89], off offset:16 nt
	global_load_dwordx4 v[116:119], v[88:89], off nt
	global_load_dwordx4 v[104:107], v[88:89], off offset:528 nt
	global_load_dwordx4 v[108:111], v[88:89], off offset:512 nt
	v_lshlrev_b64 v[88:89], 12, v[124:125]
	v_cvt_pk_bf16_f32 v157, v92, v93
	v_fmac_f32_e32 v91, v92, v92
	v_lshl_add_u64 v[92:93], v[182:183], 0, v[88:89]
	v_cvt_pk_bf16_f32 v155, v96, v97
	v_add_f32_e32 v158, v91, v90
	global_load_dwordx4 v[96:99], v[92:93], off offset:16 nt
	global_load_dwordx4 v[100:103], v[92:93], off nt
	global_load_dwordx4 v[88:91], v[92:93], off offset:528 nt
	s_nop 0
	global_load_dwordx4 v[92:95], v[92:93], off offset:512 nt
	v_pk_add_f32 v[86:87], v[86:87], v[150:151]
	v_pk_add_f32 v[78:79], v[78:79], v[146:147]
	v_cvt_pk_bf16_f32 v146, v86, v87
	v_mul_f32_e32 v87, v87, v87
	v_fmac_f32_e32 v87, v86, v86
	v_mul_f32_e32 v86, v129, v129
	v_pk_add_f32 v[80:81], v[80:81], v[148:149]
	v_cvt_pk_bf16_f32 v148, v78, v79
	v_fmac_f32_e32 v86, v128, v128
	v_mul_f32_e32 v79, v79, v79
	v_add_f32_e32 v86, v87, v86
	v_fmac_f32_e32 v79, v78, v78
	v_add_f32_e32 v78, v86, v79
	v_mul_f32_e32 v79, v81, v81
	v_cvt_pk_bf16_f32 v149, v80, v81
	v_fmac_f32_e32 v79, v80, v80
	v_pk_add_f32 v[80:81], v[84:85], v[144:145]
	v_pk_add_f32 v[82:83], v[82:83], v[142:143]
	v_pk_add_f32 v[86:87], v[74:75], v[138:139]
	v_cvt_pk_bf16_f32 v74, v82, v83
	v_cvt_pk_bf16_f32 v75, v80, v81
	v_mul_f32_e32 v83, v83, v83
	v_mul_f32_e32 v81, v81, v81
	v_fmac_f32_e32 v83, v82, v82
	v_fmac_f32_e32 v81, v80, v80
	v_pk_add_f32 v[70:71], v[70:71], v[134:135]
	v_add_f32_e32 v80, v83, v81
	v_mul_f32_e32 v81, v87, v87
	v_pk_add_f32 v[72:73], v[72:73], v[136:137]
	v_pk_add_f32 v[82:83], v[66:67], v[130:131]
	v_cvt_pk_bf16_f32 v66, v70, v71
	v_mul_f32_e32 v71, v71, v71
	v_pk_add_f32 v[84:85], v[76:77], v[140:141]
	v_fmac_f32_e32 v81, v86, v86
	v_fmac_f32_e32 v71, v70, v70
	v_mul_f32_e32 v70, v73, v73
	v_add_f32_e32 v80, v80, v81
	v_mul_f32_e32 v81, v85, v85
	v_fmac_f32_e32 v70, v72, v72
	v_fmac_f32_e32 v81, v84, v84
	v_add_f32_e32 v70, v71, v70
	v_mul_f32_e32 v71, v83, v83
	v_cvt_pk_bf16_f32 v77, v84, v85
	v_add_f32_e32 v84, v81, v80
	v_pk_add_f32 v[80:81], v[68:69], v[132:133]
	v_fmac_f32_e32 v71, v82, v82
	v_add_f32_e32 v70, v70, v71
	v_mul_f32_e32 v71, v81, v81
	v_fmac_f32_e32 v71, v80, v80
	v_add_f32_e32 v70, v71, v70
	v_add_f32_e32 v70, v84, v70
	v_add_f32_e32 v78, v79, v78
	v_mov_b32_e32 v71, v70
	v_add_f32_e32 v78, v158, v78
	s_nop 0
	v_permlane16_swap_b32_e32 v70, v71
	v_mov_b32_e32 v79, v78
	v_cvt_pk_bf16_f32 v67, v72, v73
	v_add_f32_e32 v72, v70, v71
	v_lshlrev_b64 v[70:71], 11, v[186:187]
	v_permlane16_swap_b32_e32 v78, v79
	v_lshl_add_u64 v[70:71], s[14:15], 0, v[70:71]
	v_add_f32_e32 v78, v78, v79
	v_lshl_add_u64 v[70:71], v[178:179], 1, v[70:71]
	v_cvt_pk_bf16_f32 v147, v128, v129
	v_mov_b32_e32 v79, v78
	v_mov_b32_e32 v73, v72
	global_store_dwordx4 v[70:71], v[154:157], off nt
	global_store_dwordx4 v[70:71], v[146:149], off offset:256 nt
	v_lshlrev_b64 v[70:71], 11, v[184:185]
	v_permlane32_swap_b32_e32 v78, v79
	v_cvt_pk_bf16_f32 v76, v86, v87
	v_cvt_pk_bf16_f32 v68, v82, v83
	v_cvt_pk_bf16_f32 v69, v80, v81
	v_permlane32_swap_b32_e32 v72, v73
	v_lshl_add_u64 v[70:71], s[14:15], 0, v[70:71]
	s_and_saveexec_b64 s[36:37], s[2:3]
	s_xor_b64 s[36:37], exec, s[36:37]
	s_cbranch_execz .LBB0_884
	v_lshl_add_u64 v[70:71], v[178:179], 1, v[70:71]
	global_store_dwordx4 v[70:71], v[74:77], off nt
	global_store_dwordx4 v[70:71], v[66:69], off offset:256 nt

.LBB0_886:
	s_or_b64 exec, exec, s[36:37]
	s_waitcnt vmcnt(8)
	v_pk_add_f32 v[62:63], v[62:63], v[116:117]
	v_pk_add_f32 v[64:65], v[64:65], v[118:119]
	v_cvt_pk_bf16_f32 v116, v62, v63
	v_mul_f32_e32 v63, v63, v63
	v_pk_add_f32 v[58:59], v[58:59], v[112:113]
	v_fmac_f32_e32 v63, v62, v62
	v_mul_f32_e32 v62, v65, v65
	v_cvt_pk_bf16_f32 v118, v58, v59
	v_fmac_f32_e32 v62, v64, v64
	v_mul_f32_e32 v59, v59, v59
	v_or_b32_e32 v86, 32, v126
	v_add_f32_e32 v62, v63, v62
	v_fmac_f32_e32 v59, v58, v58
	v_ashrrev_i32_e32 v87, 31, v86
	v_add_f32_e32 v128, v62, v59
	v_lshlrev_b64 v[58:59], 12, v[86:87]
	v_lshl_add_u64 v[58:59], v[182:183], 0, v[58:59]
	v_pk_add_f32 v[60:61], v[60:61], v[114:115]
	global_load_dwordx4 v[82:85], v[58:59], off offset:16 nt
	global_load_dwordx4 v[112:115], v[58:59], off nt
	global_load_dwordx4 v[74:77], v[58:59], off offset:528 nt
	global_load_dwordx4 v[78:81], v[58:59], off offset:512 nt
	v_or_b32_e32 v58, 48, v126
	v_ashrrev_i32_e32 v59, 31, v58
	v_lshlrev_b64 v[58:59], 12, v[58:59]
	v_mul_f32_e32 v129, v61, v61
	v_lshl_add_u64 v[62:63], v[182:183], 0, v[58:59]
	v_cvt_pk_bf16_f32 v117, v64, v65
	v_cvt_pk_bf16_f32 v119, v60, v61
	v_fmac_f32_e32 v129, v60, v60
	global_load_dwordx4 v[66:69], v[62:63], off offset:16 nt
	global_load_dwordx4 v[70:73], v[62:63], off nt
	global_load_dwordx4 v[58:61], v[62:63], off offset:528 nt
	s_nop 0
	global_load_dwordx4 v[62:65], v[62:63], off offset:512 nt
	s_waitcnt vmcnt(14)
	v_pk_add_f32 v[110:111], v[56:57], v[110:111]
	v_pk_add_f32 v[108:109], v[54:55], v[108:109]
	v_pk_add_f32 v[46:47], v[46:47], v[104:105]
	v_mul_f32_e32 v104, v109, v109
	v_mul_f32_e32 v105, v111, v111
	v_cvt_pk_bf16_f32 v56, v46, v47
	v_fmac_f32_e32 v104, v108, v108
	v_fmac_f32_e32 v105, v110, v110
	v_mul_f32_e32 v47, v47, v47
	v_pk_add_f32 v[48:49], v[48:49], v[106:107]
	v_add_f32_e32 v104, v104, v105
	v_fmac_f32_e32 v47, v46, v46
	v_add_f32_e32 v46, v104, v47
	v_mul_f32_e32 v47, v49, v49
	v_cvt_pk_bf16_f32 v57, v48, v49
	v_fmac_f32_e32 v47, v48, v48
	s_waitcnt vmcnt(12)
	v_pk_add_f32 v[48:49], v[52:53], v[102:103]
	v_pk_add_f32 v[50:51], v[50:51], v[100:101]
	v_pk_add_f32 v[96:97], v[42:43], v[96:97]
	v_cvt_pk_bf16_f32 v42, v50, v51
	v_cvt_pk_bf16_f32 v43, v48, v49
	v_mul_f32_e32 v51, v51, v51
	v_mul_f32_e32 v49, v49, v49
	v_fmac_f32_e32 v51, v50, v50
	v_fmac_f32_e32 v49, v48, v48
	s_waitcnt vmcnt(10)
	v_pk_add_f32 v[38:39], v[38:39], v[92:93]
	v_add_f32_e32 v48, v51, v49
	v_mul_f32_e32 v49, v97, v97
	v_pk_add_f32 v[40:41], v[40:41], v[94:95]
	v_pk_add_f32 v[50:51], v[34:35], v[88:89]
	v_cvt_pk_bf16_f32 v34, v38, v39
	v_mul_f32_e32 v39, v39, v39
	v_pk_add_f32 v[52:53], v[44:45], v[98:99]
	v_fmac_f32_e32 v49, v96, v96
	v_fmac_f32_e32 v39, v38, v38
	v_mul_f32_e32 v38, v41, v41
	v_add_f32_e32 v48, v48, v49
	v_mul_f32_e32 v49, v53, v53
	v_fmac_f32_e32 v38, v40, v40
	v_fmac_f32_e32 v49, v52, v52
	v_add_f32_e32 v38, v39, v38
	v_mul_f32_e32 v39, v51, v51
	v_cvt_pk_bf16_f32 v45, v52, v53
	v_add_f32_e32 v52, v49, v48
	v_pk_add_f32 v[48:49], v[36:37], v[90:91]
	v_fmac_f32_e32 v39, v50, v50
	v_add_f32_e32 v38, v38, v39
	v_mul_f32_e32 v39, v49, v49
	v_fmac_f32_e32 v39, v48, v48
	v_add_f32_e32 v128, v129, v128
	v_add_f32_e32 v46, v47, v46
	v_add_f32_e32 v38, v39, v38
	v_add_f32_e32 v46, v128, v46
	v_add_f32_e32 v38, v52, v38
	v_mov_b32_e32 v47, v46
	v_mov_b32_e32 v39, v38
	s_nop 0
	v_permlane16_swap_b32_e32 v46, v47
	v_permlane16_swap_b32_e32 v38, v39
	v_add_f32_e32 v46, v46, v47
	v_cvt_pk_bf16_f32 v35, v40, v41
	v_add_f32_e32 v38, v38, v39
	v_lshlrev_b64 v[40:41], 11, v[126:127]
	v_mov_b32_e32 v47, v46
	v_mov_b32_e32 v39, v38
	v_lshl_add_u64 v[40:41], s[14:15], 0, v[40:41]
	v_permlane32_swap_b32_e32 v46, v47
	v_cvt_pk_bf16_f32 v44, v96, v97
	v_cvt_pk_bf16_f32 v36, v50, v51
	v_cvt_pk_bf16_f32 v37, v48, v49
	v_permlane32_swap_b32_e32 v38, v39
	v_lshl_add_u64 v[40:41], v[178:179], 1, v[40:41]
	v_cvt_pk_bf16_f32 v54, v108, v109
	v_cvt_pk_bf16_f32 v55, v110, v111
	global_store_dwordx4 v[40:41], v[116:119], off nt
	global_store_dwordx4 v[40:41], v[54:57], off offset:256 nt
	s_and_saveexec_b64 s[36:37], s[2:3]
	s_xor_b64 s[36:37], exec, s[36:37]
	s_cbranch_execz .LBB0_888
	v_add_co_u32_e32 v40, vcc, 0x48000, v120
	v_lshl_add_u64 v[38:39], v[120:121], 0, s[22:23]
	s_nop 0
	v_addc_co_u32_e32 v41, vcc, 0, v121, vcc
	global_store_dwordx4 v[40:41], v[42:45], off nt
	global_store_dwordx4 v[38:39], v[34:37], off offset:256 nt

.LBB0_971:
	ds_read_b128 v[156:159], v151
	ds_read_b128 v[160:163], v151 offset:1024
	ds_read_b128 v[164:167], v151 offset:2048
	ds_read_b128 v[168:171], v151 offset:3072
	ds_read_b128 v[172:175], v153
	ds_read_b128 v[176:179], v153 offset:1024
	ds_read_b128 v[180:183], v153 offset:2048
	ds_read_b128 v[184:187], v153 offset:3072
	s_add_u32 s6, s64, s12
	s_addc_u32 s7, s65, 0
	s_add_u32 s68, s66, s12
	s_addc_u32 s69, s67, 0
	s_cmp_eq_u32 s12, s0
	s_cselect_b32 s9, s37, s7
	s_cselect_b32 s8, s61, s6
	s_cselect_b32 s7, s35, s69
	s_cselect_b32 s6, s62, s68
	s_add_i32 s69, s46, 0xc000
	v_lshl_add_u64 v[138:139], v[142:143], 0, s[12:13]
	s_mov_b32 m0, s69
	s_add_i32 s68, s46, 0xe000
	ds_read_b128 v[188:191], v155
	ds_read_b128 v[192:195], v155 offset:1024
	ds_read_b128 v[196:199], v155 offset:2048
	ds_read_b128 v[200:203], v155 offset:3072
	ds_read_b128 v[204:207], v155 offset:4096
	ds_read_b128 v[208:211], v155 offset:5120
	ds_read_b128 v[212:215], v155 offset:6144
	ds_read_b128 v[216:219], v155 offset:7168
	global_load_lds_dwordx4 v[138:139], off
	v_lshl_add_u64 v[138:139], v[144:145], 0, s[12:13]
	s_mov_b32 m0, s68
	s_nop 0
	global_load_lds_dwordx4 v[138:139], off
	s_waitcnt vmcnt(8)
	s_waitcnt lgkmcnt(0)
	s_barrier
	s_setprio 1
	s_waitcnt lgkmcnt(0)
	v_mfma_f32_16x16x32_bf16 v[126:129], v[156:159], v[188:191], v[126:129]
	v_mfma_f32_16x16x32_bf16 v[122:125], v[164:167], v[188:191], v[122:125]
	v_mfma_f32_16x16x32_bf16 v[110:113], v[156:159], v[196:199], v[110:113]
	v_mfma_f32_16x16x32_bf16 v[106:109], v[164:167], v[196:199], v[106:109]
	v_mfma_f32_16x16x32_bf16 v[94:97], v[156:159], v[204:207], v[94:97]
	v_mfma_f32_16x16x32_bf16 v[90:93], v[164:167], v[204:207], v[90:93]
	v_mfma_f32_16x16x32_bf16 v[78:81], v[156:159], v[212:215], v[78:81]
	v_mfma_f32_16x16x32_bf16 v[74:77], v[164:167], v[212:215], v[74:77]
	v_mfma_f32_16x16x32_bf16 v[126:129], v[160:163], v[192:195], v[126:129]
	v_mfma_f32_16x16x32_bf16 v[122:125], v[168:171], v[192:195], v[122:125]
	v_mfma_f32_16x16x32_bf16 v[110:113], v[160:163], v[200:203], v[110:113]
	v_mfma_f32_16x16x32_bf16 v[106:109], v[168:171], v[200:203], v[106:109]
	v_mfma_f32_16x16x32_bf16 v[94:97], v[160:163], v[208:211], v[94:97]
	v_mfma_f32_16x16x32_bf16 v[90:93], v[168:171], v[208:211], v[90:93]
	v_mfma_f32_16x16x32_bf16 v[78:81], v[160:163], v[216:219], v[78:81]
	v_mfma_f32_16x16x32_bf16 v[74:77], v[168:171], v[216:219], v[74:77]
	s_setprio 0
	s_setprio 1
	v_mfma_f32_16x16x32_bf16 v[118:121], v[172:175], v[188:191], v[118:121]
	v_mfma_f32_16x16x32_bf16 v[114:117], v[180:183], v[188:191], v[114:117]
	v_mfma_f32_16x16x32_bf16 v[102:105], v[172:175], v[196:199], v[102:105]
	v_mfma_f32_16x16x32_bf16 v[98:101], v[180:183], v[196:199], v[98:101]
	v_mfma_f32_16x16x32_bf16 v[86:89], v[172:175], v[204:207], v[86:89]
	v_mfma_f32_16x16x32_bf16 v[82:85], v[180:183], v[204:207], v[82:85]
	v_mfma_f32_16x16x32_bf16 v[70:73], v[172:175], v[212:215], v[70:73]
	v_mfma_f32_16x16x32_bf16 v[66:69], v[180:183], v[212:215], v[66:69]
	v_mfma_f32_16x16x32_bf16 v[118:121], v[176:179], v[192:195], v[118:121]
	v_mfma_f32_16x16x32_bf16 v[114:117], v[184:187], v[192:195], v[114:117]
	v_mfma_f32_16x16x32_bf16 v[102:105], v[176:179], v[200:203], v[102:105]
	v_mfma_f32_16x16x32_bf16 v[98:101], v[184:187], v[200:203], v[98:101]
	v_mfma_f32_16x16x32_bf16 v[86:89], v[176:179], v[208:211], v[86:89]
	v_mfma_f32_16x16x32_bf16 v[82:85], v[184:187], v[208:211], v[82:85]
	v_mfma_f32_16x16x32_bf16 v[70:73], v[176:179], v[216:219], v[70:73]
	v_mfma_f32_16x16x32_bf16 v[66:69], v[184:187], v[216:219], v[66:69]
	s_setprio 0
	s_barrier
	s_cmp_lg_u32 s12, s0
	s_cbranch_scc1 .Lmy_p8_noload
	s_lshl_b32 s98, s4, 14
	v_lshl_add_u32 v252, v0, 5, s98
	global_load_dwordx4 v[228:231], v252, s[16:17] nt
	global_load_dwordx4 v[232:235], v252, s[16:17] offset:16 nt

.LBB0_1054:
	s_lshl_b32 s5, s52, 8
	s_lshl_b32 s2, s4, 8
	v_mov_b32_e32 v219, v211
	v_mov_b32_e32 v192, v210
	s_add_i32 s45, s5, s72
	s_or_b32 s2, s2, s73
	s_nop 0
	v_add_u32_e32 v128, s45, v192
	v_lshl_add_u32 v204, v219, 3, s2
	v_ashrrev_i32_e32 v205, 31, v204
	v_ashrrev_i32_e32 v129, 31, v128
	v_lshl_add_u64 v[130:131], v[204:205], 1, s[16:17]
	v_lshlrev_b64 v[128:129], 11, v[128:129]
	v_lshl_add_u64 v[128:129], v[130:131], 0, v[128:129]
	global_load_dwordx4 v[206:209], v[128:129], off nt
	global_load_dwordx4 v[220:223], v[128:129], off offset:256 nt
	s_mov_b64 s[2:3], 0x8000
	v_add_co_u32_e32 v132, vcc, s76, v128
	v_lshl_add_u64 v[130:131], v[128:129], 0, s[2:3]
	s_nop 0
	v_addc_co_u32_e32 v133, vcc, 0, v129, vcc
	s_mov_b64 s[2:3], 0x10000
	global_load_dwordx4 v[180:183], v[132:133], off nt
	global_load_dwordx4 v[176:179], v[130:131], off offset:256 nt
	v_lshl_add_u64 v[130:131], v[128:129], 0, s[2:3]
	s_mov_b32 s2, 0x10000
	v_add_co_u32_e32 v132, vcc, s2, v128
	s_mov_b32 s2, 0x18000
	s_nop 0
	v_addc_co_u32_e32 v133, vcc, 0, v129, vcc
	global_load_dwordx4 v[172:175], v[132:133], off nt
	global_load_dwordx4 v[168:171], v[130:131], off offset:256 nt
	v_add_co_u32_e32 v132, vcc, s2, v128
	v_lshl_add_u64 v[130:131], v[128:129], 0, s[24:25]
	s_nop 0
	v_addc_co_u32_e32 v133, vcc, 0, v129, vcc
	global_load_dwordx4 v[164:167], v[132:133], off nt
	global_load_dwordx4 v[160:163], v[130:131], off offset:256 nt
	v_add_co_u32_e32 v132, vcc, s84, v128
	v_lshl_add_u64 v[130:131], v[128:129], 0, s[26:27]
	s_nop 0
	v_addc_co_u32_e32 v133, vcc, 0, v129, vcc
	global_load_dwordx4 v[156:159], v[132:133], off nt
	global_load_dwordx4 v[152:155], v[130:131], off offset:256 nt
	v_add_co_u32_e32 v132, vcc, s85, v128
	v_lshl_add_u64 v[130:131], v[128:129], 0, s[28:29]
	s_nop 0
	v_addc_co_u32_e32 v133, vcc, 0, v129, vcc
	global_load_dwordx4 v[148:151], v[132:133], off nt
	global_load_dwordx4 v[144:147], v[130:131], off offset:256 nt
	v_add_co_u32_e32 v132, vcc, s86, v128
	v_lshl_add_u64 v[130:131], v[128:129], 0, s[30:31]
	s_nop 0
	v_addc_co_u32_e32 v133, vcc, 0, v129, vcc
	global_load_dwordx4 v[140:143], v[132:133], off nt
	global_load_dwordx4 v[136:139], v[130:131], off offset:256 nt
	v_lshl_add_u64 v[130:131], v[128:129], 0, s[34:35]
	v_add_co_u32_e32 v128, vcc, s87, v128
	v_add_u32_e32 v230, s72, v192
	s_nop 0
	v_addc_co_u32_e32 v129, vcc, 0, v129, vcc
	global_load_dwordx4 v[132:135], v[128:129], off nt
	s_nop 0
	global_load_dwordx4 v[128:131], v[130:131], off offset:256 nt
	v_cmp_eq_u32_e32 vcc, 0, v219
	s_waitcnt vmcnt(0)
	v_lshlrev_b32_e32 v224, 16, v206
	v_and_b32_e32 v225, 0xffff0000, v206
	v_lshlrev_b32_e32 v206, 16, v207
	v_and_b32_e32 v207, 0xffff0000, v207
	v_lshlrev_b32_e32 v226, 16, v208
	v_and_b32_e32 v227, 0xffff0000, v208
	v_pk_add_f32 v[126:127], v[126:127], v[206:207]
	v_pk_add_f32 v[124:125], v[124:125], v[224:225]
	v_lshlrev_b32_e32 v208, 16, v209
	v_and_b32_e32 v209, 0xffff0000, v209
	v_pk_add_f32 v[120:121], v[120:121], v[226:227]
	v_mul_f32_e32 v206, v125, v125
	v_mul_f32_e32 v207, v127, v127
	v_pk_add_f32 v[122:123], v[122:123], v[208:209]
	v_mul_f32_e32 v208, v121, v121
	v_fmac_f32_e32 v206, v124, v124
	v_fmac_f32_e32 v207, v126, v126
	v_mul_f32_e32 v209, v123, v123
	v_fmac_f32_e32 v208, v120, v120
	v_add_f32_e32 v206, v206, v207
	v_lshlrev_b32_e32 v228, 16, v220
	v_and_b32_e32 v229, 0xffff0000, v220
	v_lshlrev_b32_e32 v220, 16, v221
	v_fmac_f32_e32 v209, v122, v122
	v_add_f32_e32 v206, v208, v206
	v_and_b32_e32 v221, 0xffff0000, v221
	v_add_f32_e32 v224, v209, v206
	v_lshlrev_b32_e32 v206, 16, v222
	v_and_b32_e32 v207, 0xffff0000, v222
	v_pk_add_f32 v[118:119], v[118:119], v[220:221]
	v_pk_add_f32 v[116:117], v[116:117], v[228:229]
	v_pk_add_f32 v[112:113], v[112:113], v[206:207]
	v_mul_f32_e32 v206, v117, v117
	v_mul_f32_e32 v207, v119, v119
	v_fmac_f32_e32 v206, v116, v116
	v_fmac_f32_e32 v207, v118, v118
	v_lshlrev_b32_e32 v208, 16, v223
	v_and_b32_e32 v209, 0xffff0000, v223
	v_add_f32_e32 v206, v206, v207
	v_mul_f32_e32 v207, v113, v113
	v_pk_add_f32 v[114:115], v[114:115], v[208:209]
	v_fmac_f32_e32 v207, v112, v112
	v_add_f32_e32 v206, v207, v206
	v_mul_f32_e32 v207, v115, v115
	v_fmac_f32_e32 v207, v114, v114
	v_add_f32_e32 v206, v207, v206
	v_add_f32_e32 v206, v224, v206
	v_mov_b32_e32 v207, v206
	s_nop 1
	v_permlane16_swap_b32_e32 v206, v207
	v_add_f32_e32 v206, v206, v207
	v_mov_b32_e32 v207, v206
	s_nop 1
	v_permlane32_swap_b32_e32 v206, v207
	v_lshl_add_u32 v220, v230, 4, s80
	s_and_saveexec_b64 s[2:3], vcc
	v_add_f32_e32 v206, v206, v207
	ds_write_b32 v220, v206
	s_or_b64 exec, exec, s[2:3]
	v_lshlrev_b32_e32 v206, 16, v180
	v_and_b32_e32 v207, 0xffff0000, v180
	v_lshlrev_b32_e32 v180, 16, v181
	v_and_b32_e32 v181, 0xffff0000, v181
	v_lshlrev_b32_e32 v208, 16, v182
	v_and_b32_e32 v209, 0xffff0000, v182
	v_pk_add_f32 v[180:181], v[110:111], v[180:181]
	v_pk_add_f32 v[206:207], v[108:109], v[206:207]
	v_pk_add_f32 v[208:209], v[104:105], v[208:209]
	v_mul_f32_e32 v104, v207, v207
	v_mul_f32_e32 v105, v181, v181
	v_fmac_f32_e32 v104, v206, v206
	v_fmac_f32_e32 v105, v180, v180
	v_lshlrev_b32_e32 v182, 16, v183
	v_and_b32_e32 v183, 0xffff0000, v183
	v_add_f32_e32 v104, v104, v105
	v_mul_f32_e32 v105, v209, v209
	v_pk_add_f32 v[182:183], v[106:107], v[182:183]
	v_fmac_f32_e32 v105, v208, v208
	v_add_f32_e32 v104, v105, v104
	v_mul_f32_e32 v105, v183, v183
	v_fmac_f32_e32 v105, v182, v182
	v_add_f32_e32 v221, v105, v104
	v_lshlrev_b32_e32 v104, 16, v176
	v_and_b32_e32 v105, 0xffff0000, v176
	v_lshlrev_b32_e32 v106, 16, v177
	v_and_b32_e32 v107, 0xffff0000, v177
	v_pk_add_f32 v[102:103], v[102:103], v[106:107]
	v_pk_add_f32 v[100:101], v[100:101], v[104:105]
	v_lshlrev_b32_e32 v108, 16, v178
	v_and_b32_e32 v109, 0xffff0000, v178
	v_mul_f32_e32 v104, v101, v101
	v_mul_f32_e32 v105, v103, v103
	v_pk_add_f32 v[96:97], v[96:97], v[108:109]
	v_fmac_f32_e32 v104, v100, v100
	v_fmac_f32_e32 v105, v102, v102
	v_lshlrev_b32_e32 v110, 16, v179
	v_and_b32_e32 v111, 0xffff0000, v179
	v_add_f32_e32 v104, v104, v105
	v_mul_f32_e32 v105, v97, v97
	v_pk_add_f32 v[98:99], v[98:99], v[110:111]
	v_fmac_f32_e32 v105, v96, v96
	v_add_f32_e32 v104, v105, v104
	v_mul_f32_e32 v105, v99, v99
	v_fmac_f32_e32 v105, v98, v98
	v_add_f32_e32 v104, v105, v104
	v_add_f32_e32 v104, v221, v104
	v_mov_b32_e32 v105, v104
	s_nop 1
	v_permlane16_swap_b32_e32 v104, v105
	v_add_f32_e32 v104, v104, v105
	v_mov_b32_e32 v105, v104
	s_nop 1
	v_permlane32_swap_b32_e32 v104, v105
	s_and_saveexec_b64 s[2:3], vcc
	v_add_f32_e32 v104, v104, v105
	ds_write_b32 v220, v104 offset:256
	s_or_b64 exec, exec, s[2:3]
	v_lshlrev_b32_e32 v104, 16, v172
	v_and_b32_e32 v105, 0xffff0000, v172
	v_lshlrev_b32_e32 v106, 16, v173
	v_and_b32_e32 v107, 0xffff0000, v173
	v_pk_add_f32 v[94:95], v[94:95], v[106:107]
	v_pk_add_f32 v[92:93], v[92:93], v[104:105]
	v_lshlrev_b32_e32 v108, 16, v174
	v_and_b32_e32 v109, 0xffff0000, v174
	v_mul_f32_e32 v104, v93, v93
	v_mul_f32_e32 v105, v95, v95
	v_pk_add_f32 v[88:89], v[88:89], v[108:109]
	v_fmac_f32_e32 v104, v92, v92
	v_fmac_f32_e32 v105, v94, v94
	v_lshlrev_b32_e32 v110, 16, v175
	v_and_b32_e32 v111, 0xffff0000, v175
	v_add_f32_e32 v104, v104, v105
	v_mul_f32_e32 v105, v89, v89
	v_pk_add_f32 v[90:91], v[90:91], v[110:111]
	v_fmac_f32_e32 v105, v88, v88
	v_add_f32_e32 v104, v105, v104
	v_mul_f32_e32 v105, v91, v91
	v_fmac_f32_e32 v105, v90, v90
	v_add_f32_e32 v172, v105, v104
	v_lshlrev_b32_e32 v104, 16, v168
	v_and_b32_e32 v105, 0xffff0000, v168
	v_lshlrev_b32_e32 v106, 16, v169
	v_and_b32_e32 v107, 0xffff0000, v169
	v_pk_add_f32 v[86:87], v[86:87], v[106:107]
	v_pk_add_f32 v[84:85], v[84:85], v[104:105]
	v_lshlrev_b32_e32 v108, 16, v170
	v_and_b32_e32 v109, 0xffff0000, v170
	v_mul_f32_e32 v104, v85, v85
	v_mul_f32_e32 v105, v87, v87
	v_pk_add_f32 v[80:81], v[80:81], v[108:109]
	v_fmac_f32_e32 v104, v84, v84
	v_fmac_f32_e32 v105, v86, v86
	v_lshlrev_b32_e32 v110, 16, v171
	v_and_b32_e32 v111, 0xffff0000, v171
	v_add_f32_e32 v104, v104, v105
	v_mul_f32_e32 v105, v81, v81
	v_pk_add_f32 v[82:83], v[82:83], v[110:111]
	v_fmac_f32_e32 v105, v80, v80
	v_add_f32_e32 v104, v105, v104
	v_mul_f32_e32 v105, v83, v83
	v_fmac_f32_e32 v105, v82, v82
	v_add_f32_e32 v104, v105, v104
	v_add_f32_e32 v104, v172, v104
	v_mov_b32_e32 v105, v104
	s_nop 1
	v_permlane16_swap_b32_e32 v104, v105
	v_add_f32_e32 v104, v104, v105
	v_mov_b32_e32 v105, v104
	s_nop 1
	v_permlane32_swap_b32_e32 v104, v105
	s_and_saveexec_b64 s[2:3], vcc
	v_add_f32_e32 v104, v104, v105
	ds_write_b32 v220, v104 offset:512
	s_or_b64 exec, exec, s[2:3]
	v_lshlrev_b32_e32 v104, 16, v164
	v_and_b32_e32 v105, 0xffff0000, v164
	v_lshlrev_b32_e32 v106, 16, v165
	v_and_b32_e32 v107, 0xffff0000, v165
	v_pk_add_f32 v[78:79], v[78:79], v[106:107]
	v_pk_add_f32 v[76:77], v[76:77], v[104:105]
	v_lshlrev_b32_e32 v108, 16, v166
	v_and_b32_e32 v109, 0xffff0000, v166
	v_mul_f32_e32 v104, v77, v77
	v_mul_f32_e32 v105, v79, v79
	v_pk_add_f32 v[72:73], v[72:73], v[108:109]
	v_fmac_f32_e32 v104, v76, v76
	v_fmac_f32_e32 v105, v78, v78
	v_lshlrev_b32_e32 v110, 16, v167
	v_and_b32_e32 v111, 0xffff0000, v167
	v_add_f32_e32 v104, v104, v105
	v_mul_f32_e32 v105, v73, v73
	v_pk_add_f32 v[74:75], v[74:75], v[110:111]
	v_fmac_f32_e32 v105, v72, v72
	v_add_f32_e32 v104, v105, v104
	v_mul_f32_e32 v105, v75, v75
	v_fmac_f32_e32 v105, v74, v74
	v_add_f32_e32 v164, v105, v104
	v_lshlrev_b32_e32 v104, 16, v160
	v_and_b32_e32 v105, 0xffff0000, v160
	v_lshlrev_b32_e32 v106, 16, v161
	v_and_b32_e32 v107, 0xffff0000, v161
	v_pk_add_f32 v[70:71], v[70:71], v[106:107]
	v_pk_add_f32 v[68:69], v[68:69], v[104:105]
	v_lshlrev_b32_e32 v108, 16, v162
	v_and_b32_e32 v109, 0xffff0000, v162
	v_mul_f32_e32 v104, v69, v69
	v_mul_f32_e32 v105, v71, v71
	v_pk_add_f32 v[64:65], v[64:65], v[108:109]
	v_fmac_f32_e32 v104, v68, v68
	v_fmac_f32_e32 v105, v70, v70
	v_lshlrev_b32_e32 v110, 16, v163
	v_and_b32_e32 v111, 0xffff0000, v163
	v_add_f32_e32 v104, v104, v105
	v_mul_f32_e32 v105, v65, v65
	v_pk_add_f32 v[66:67], v[66:67], v[110:111]
	v_fmac_f32_e32 v105, v64, v64
	v_add_f32_e32 v104, v105, v104
	v_mul_f32_e32 v105, v67, v67
	v_fmac_f32_e32 v105, v66, v66
	v_add_f32_e32 v104, v105, v104
	v_add_f32_e32 v104, v164, v104
	v_mov_b32_e32 v105, v104
	s_nop 1
	v_permlane16_swap_b32_e32 v104, v105
	v_add_f32_e32 v104, v104, v105
	v_mov_b32_e32 v105, v104
	s_nop 1
	v_permlane32_swap_b32_e32 v104, v105
	s_and_saveexec_b64 s[2:3], vcc
	v_add_f32_e32 v104, v104, v105
	ds_write_b32 v220, v104 offset:768
	s_or_b64 exec, exec, s[2:3]
	v_lshlrev_b32_e32 v104, 16, v156
	v_and_b32_e32 v105, 0xffff0000, v156
	v_lshlrev_b32_e32 v106, 16, v157
	v_and_b32_e32 v107, 0xffff0000, v157
	v_pk_add_f32 v[62:63], v[62:63], v[106:107]
	v_pk_add_f32 v[60:61], v[60:61], v[104:105]
	v_lshlrev_b32_e32 v108, 16, v158
	v_and_b32_e32 v109, 0xffff0000, v158
	v_mul_f32_e32 v104, v61, v61
	v_mul_f32_e32 v105, v63, v63
	v_pk_add_f32 v[56:57], v[56:57], v[108:109]
	v_fmac_f32_e32 v104, v60, v60
	v_fmac_f32_e32 v105, v62, v62
	v_lshlrev_b32_e32 v110, 16, v159
	v_and_b32_e32 v111, 0xffff0000, v159
	v_add_f32_e32 v104, v104, v105
	v_mul_f32_e32 v105, v57, v57
	v_pk_add_f32 v[58:59], v[58:59], v[110:111]
	v_fmac_f32_e32 v105, v56, v56
	v_add_f32_e32 v104, v105, v104
	v_mul_f32_e32 v105, v59, v59
	v_fmac_f32_e32 v105, v58, v58
	v_add_f32_e32 v156, v105, v104
	v_lshlrev_b32_e32 v104, 16, v152
	v_and_b32_e32 v105, 0xffff0000, v152
	v_lshlrev_b32_e32 v106, 16, v153
	v_and_b32_e32 v107, 0xffff0000, v153
	v_pk_add_f32 v[54:55], v[54:55], v[106:107]
	v_pk_add_f32 v[52:53], v[52:53], v[104:105]
	v_lshlrev_b32_e32 v108, 16, v154
	v_and_b32_e32 v109, 0xffff0000, v154
	v_mul_f32_e32 v104, v53, v53
	v_mul_f32_e32 v105, v55, v55
	v_pk_add_f32 v[48:49], v[48:49], v[108:109]
	v_fmac_f32_e32 v104, v52, v52
	v_fmac_f32_e32 v105, v54, v54
	v_lshlrev_b32_e32 v110, 16, v155
	v_and_b32_e32 v111, 0xffff0000, v155
	v_add_f32_e32 v104, v104, v105
	v_mul_f32_e32 v105, v49, v49
	v_pk_add_f32 v[50:51], v[50:51], v[110:111]
	v_fmac_f32_e32 v105, v48, v48
	v_add_f32_e32 v104, v105, v104
	v_mul_f32_e32 v105, v51, v51
	v_fmac_f32_e32 v105, v50, v50
	v_add_f32_e32 v104, v105, v104
	v_add_f32_e32 v104, v156, v104
	v_mov_b32_e32 v105, v104
	s_nop 1
	v_permlane16_swap_b32_e32 v104, v105
	v_add_f32_e32 v104, v104, v105
	v_mov_b32_e32 v105, v104
	s_nop 1
	v_permlane32_swap_b32_e32 v104, v105
	s_and_saveexec_b64 s[2:3], vcc
	v_add_f32_e32 v104, v104, v105
	ds_write_b32 v220, v104 offset:2048
	s_or_b64 exec, exec, s[2:3]
	v_lshlrev_b32_e32 v104, 16, v148
	v_and_b32_e32 v105, 0xffff0000, v148
	v_lshlrev_b32_e32 v106, 16, v149
	v_and_b32_e32 v107, 0xffff0000, v149
	v_pk_add_f32 v[46:47], v[46:47], v[106:107]
	v_pk_add_f32 v[44:45], v[44:45], v[104:105]
	v_lshlrev_b32_e32 v108, 16, v150
	v_and_b32_e32 v109, 0xffff0000, v150
	v_mul_f32_e32 v104, v45, v45
	v_mul_f32_e32 v105, v47, v47
	v_pk_add_f32 v[40:41], v[40:41], v[108:109]
	v_fmac_f32_e32 v104, v44, v44
	v_fmac_f32_e32 v105, v46, v46
	v_lshlrev_b32_e32 v110, 16, v151
	v_and_b32_e32 v111, 0xffff0000, v151
	v_add_f32_e32 v104, v104, v105
	v_mul_f32_e32 v105, v41, v41
	v_pk_add_f32 v[42:43], v[42:43], v[110:111]
	v_fmac_f32_e32 v105, v40, v40
	v_add_f32_e32 v104, v105, v104
	v_mul_f32_e32 v105, v43, v43
	v_fmac_f32_e32 v105, v42, v42
	v_add_f32_e32 v148, v105, v104
	v_lshlrev_b32_e32 v104, 16, v144
	v_and_b32_e32 v105, 0xffff0000, v144
	v_lshlrev_b32_e32 v106, 16, v145
	v_and_b32_e32 v107, 0xffff0000, v145
	v_pk_add_f32 v[38:39], v[38:39], v[106:107]
	v_pk_add_f32 v[36:37], v[36:37], v[104:105]
	v_lshlrev_b32_e32 v108, 16, v146
	v_and_b32_e32 v109, 0xffff0000, v146
	v_mul_f32_e32 v104, v37, v37
	v_mul_f32_e32 v105, v39, v39
	v_pk_add_f32 v[32:33], v[32:33], v[108:109]
	v_fmac_f32_e32 v104, v36, v36
	v_fmac_f32_e32 v105, v38, v38
	v_lshlrev_b32_e32 v110, 16, v147
	v_and_b32_e32 v111, 0xffff0000, v147
	v_add_f32_e32 v104, v104, v105
	v_mul_f32_e32 v105, v33, v33
	v_pk_add_f32 v[34:35], v[34:35], v[110:111]
	v_fmac_f32_e32 v105, v32, v32
	v_add_f32_e32 v104, v105, v104
	v_mul_f32_e32 v105, v35, v35
	v_fmac_f32_e32 v105, v34, v34
	v_add_f32_e32 v104, v105, v104
	v_add_f32_e32 v104, v148, v104
	v_mov_b32_e32 v105, v104
	s_nop 1
	v_permlane16_swap_b32_e32 v104, v105
	v_add_f32_e32 v104, v104, v105
	v_mov_b32_e32 v105, v104
	s_nop 1
	v_permlane32_swap_b32_e32 v104, v105
	s_and_saveexec_b64 s[2:3], vcc
	v_add_f32_e32 v104, v104, v105
	ds_write_b32 v220, v104 offset:2304
	s_or_b64 exec, exec, s[2:3]
	v_lshlrev_b32_e32 v104, 16, v140
	v_and_b32_e32 v105, 0xffff0000, v140
	v_lshlrev_b32_e32 v106, 16, v141
	v_and_b32_e32 v107, 0xffff0000, v141
	v_lshlrev_b32_e32 v108, 16, v142
	v_and_b32_e32 v109, 0xffff0000, v142
	v_pk_add_f32 v[30:31], v[30:31], v[106:107]
	v_pk_add_f32 v[104:105], v[28:29], v[104:105]
	v_pk_add_f32 v[108:109], v[24:25], v[108:109]
	v_mul_f32_e32 v24, v105, v105
	v_mul_f32_e32 v25, v31, v31
	v_fmac_f32_e32 v24, v104, v104
	v_fmac_f32_e32 v25, v30, v30
	v_lshlrev_b32_e32 v110, 16, v143
	v_and_b32_e32 v111, 0xffff0000, v143
	v_add_f32_e32 v24, v24, v25
	v_mul_f32_e32 v25, v109, v109
	v_pk_add_f32 v[26:27], v[26:27], v[110:111]
	v_fmac_f32_e32 v25, v108, v108
	v_add_f32_e32 v24, v25, v24
	v_mul_f32_e32 v25, v27, v27
	v_fmac_f32_e32 v25, v26, v26
	v_add_f32_e32 v140, v25, v24
	v_lshlrev_b32_e32 v24, 16, v136
	v_and_b32_e32 v25, 0xffff0000, v136
	v_lshlrev_b32_e32 v28, 16, v137
	v_and_b32_e32 v29, 0xffff0000, v137
	v_pk_add_f32 v[22:23], v[22:23], v[28:29]
	v_pk_add_f32 v[20:21], v[20:21], v[24:25]
	v_lshlrev_b32_e32 v106, 16, v138
	v_and_b32_e32 v107, 0xffff0000, v138
	v_mul_f32_e32 v24, v21, v21
	v_mul_f32_e32 v25, v23, v23
	v_pk_add_f32 v[16:17], v[16:17], v[106:107]
	v_fmac_f32_e32 v24, v20, v20
	v_fmac_f32_e32 v25, v22, v22
	v_lshlrev_b32_e32 v110, 16, v139
	v_and_b32_e32 v111, 0xffff0000, v139
	v_add_f32_e32 v24, v24, v25
	v_mul_f32_e32 v25, v17, v17
	v_pk_add_f32 v[18:19], v[18:19], v[110:111]
	v_fmac_f32_e32 v25, v16, v16
	v_add_f32_e32 v24, v25, v24
	v_mul_f32_e32 v25, v19, v19
	v_fmac_f32_e32 v25, v18, v18
	v_add_f32_e32 v24, v25, v24
	v_add_f32_e32 v24, v140, v24
	v_mov_b32_e32 v25, v24
	s_nop 1
	v_permlane16_swap_b32_e32 v24, v25
	v_add_f32_e32 v24, v24, v25
	v_mov_b32_e32 v25, v24
	s_nop 1
	v_permlane32_swap_b32_e32 v24, v25
	s_and_saveexec_b64 s[2:3], vcc
	v_add_f32_e32 v24, v24, v25
	ds_write_b32 v220, v24 offset:2560
	s_or_b64 exec, exec, s[2:3]
	v_lshlrev_b32_e32 v24, 16, v132
	v_and_b32_e32 v25, 0xffff0000, v132
	v_lshlrev_b32_e32 v28, 16, v133
	v_and_b32_e32 v29, 0xffff0000, v133
	v_lshlrev_b32_e32 v106, 16, v134
	v_and_b32_e32 v107, 0xffff0000, v134
	v_lshlrev_b32_e32 v132, 16, v135
	v_and_b32_e32 v133, 0xffff0000, v135
	v_pk_add_f32 v[110:111], v[14:15], v[28:29]
	v_pk_add_f32 v[134:135], v[12:13], v[24:25]
	v_pk_add_f32 v[136:137], v[8:9], v[106:107]
	v_mul_f32_e32 v8, v135, v135
	v_mul_f32_e32 v9, v111, v111
	v_fmac_f32_e32 v8, v134, v134
	v_fmac_f32_e32 v9, v110, v110
	v_add_f32_e32 v8, v8, v9
	v_mul_f32_e32 v9, v137, v137
	v_pk_add_f32 v[132:133], v[10:11], v[132:133]
	v_fmac_f32_e32 v9, v136, v136
	v_add_f32_e32 v8, v9, v8
	v_mul_f32_e32 v9, v133, v133
	v_fmac_f32_e32 v9, v132, v132
	v_add_f32_e32 v138, v9, v8
	v_lshlrev_b32_e32 v8, 16, v128
	v_and_b32_e32 v9, 0xffff0000, v128
	v_lshlrev_b32_e32 v10, 16, v129
	v_and_b32_e32 v11, 0xffff0000, v129
	v_lshlrev_b32_e32 v12, 16, v130
	v_and_b32_e32 v13, 0xffff0000, v130
	v_pk_add_f32 v[24:25], v[6:7], v[10:11]
	v_pk_add_f32 v[106:107], v[4:5], v[8:9]
	v_pk_add_f32 v[128:129], v[0:1], v[12:13]
	v_mul_f32_e32 v0, v107, v107
	v_mul_f32_e32 v1, v25, v25
	v_fmac_f32_e32 v0, v106, v106
	v_fmac_f32_e32 v1, v24, v24
	v_lshlrev_b32_e32 v14, 16, v131
	v_and_b32_e32 v15, 0xffff0000, v131
	v_add_f32_e32 v0, v0, v1
	v_mul_f32_e32 v1, v129, v129
	v_pk_add_f32 v[28:29], v[2:3], v[14:15]
	v_fmac_f32_e32 v1, v128, v128
	v_add_f32_e32 v0, v1, v0
	v_mul_f32_e32 v1, v29, v29
	v_fmac_f32_e32 v1, v28, v28
	v_add_f32_e32 v0, v1, v0
	v_add_f32_e32 v0, v138, v0
	v_mov_b32_e32 v1, v0
	s_nop 1
	v_permlane16_swap_b32_e32 v0, v1
	v_add_f32_e32 v0, v0, v1
	v_mov_b32_e32 v1, v0
	s_nop 1
	v_permlane32_swap_b32_e32 v0, v1
	s_and_saveexec_b64 s[2:3], vcc
	v_add_f32_e32 v0, v0, v1
	ds_write_b32 v220, v0 offset:2816
	s_or_b64 exec, exec, s[2:3]
	v_lshl_add_u32 v3, v219, 4, v192
	s_waitcnt lgkmcnt(0)
	s_barrier
	v_and_or_b32 v2, v3, 31, s77
	v_add_u32_e32 v0, s5, v2
	v_cmp_gt_i32_e64 s[2:3], 32, v3
	v_ashrrev_i32_e32 v1, 31, v0
	s_and_saveexec_b64 s[6:7], s[2:3]
	s_cbranch_execz .LBB0_1072
	v_lshl_add_u32 v4, v2, 4, 0
	v_add_u32_e32 v4, 0x20800, v4
	ds_read_b128 v[4:7], v4
	v_lshl_add_u64 v[8:9], v[0:1], 4, s[10:11]
	s_ashr_i32 s5, s4, 31
	v_lshl_add_u64 v[8:9], s[4:5], 2, v[8:9]
	s_waitcnt lgkmcnt(0)
	v_mov_b32_e32 v10, v5
	v_mov_b32_e32 v11, v6
	v_mov_b32_e32 v5, v7
	v_pk_add_f32 v[4:5], v[10:11], v[4:5]
	s_nop 0
	v_pk_add_f32 v[4:5], v[4:5], v[4:5] op_sel:[0,1] op_sel_hi:[1,0]
	global_store_dword v[8:9], v4, off sc1

.LBB0_1094:
	s_or_b64 exec, exec, s[4:5]
	v_lshlrev_b64 v[138:139], 2, v[204:205]
	s_waitcnt vmcnt(0) lgkmcnt(0)
	s_barrier
	v_lshl_add_u64 v[0:1], s[12:13], 0, v[138:139]
	global_load_dwordx4 v[12:15], v[0:1], off nt
	global_load_dwordx4 v[8:11], v[0:1], off offset:16 nt
	global_load_dwordx4 v[4:7], v[0:1], off offset:512 nt
	s_nop 0
	global_load_dwordx4 v[0:3], v[0:1], off offset:528 nt
	v_lshl_add_u32 v142, v192, 2, s81
	ds_read2_b32 v[144:145], v142 offset1:16
	v_and_or_b32 v140, v192, 7, s45
	v_ashrrev_i32_e32 v141, 31, v140
	v_or_b32_e32 v130, 16, v140
	v_lshlrev_b64 v[146:147], 12, v[140:141]
	s_waitcnt lgkmcnt(0)
	v_pk_mul_f32 v[124:125], v[124:125], v[144:145] op_sel_hi:[1,0]
	v_pk_mul_f32 v[126:127], v[126:127], v[144:145] op_sel_hi:[1,0]
	v_pk_mul_f32 v[120:121], v[120:121], v[144:145] op_sel_hi:[1,0]
	v_pk_mul_f32 v[122:123], v[122:123], v[144:145] op_sel_hi:[1,0]
	v_cmp_gt_i32_e32 vcc, 8, v192
	v_ashrrev_i32_e32 v131, 31, v130
	v_lshl_add_u64 v[146:147], s[8:9], 0, v[146:147]
	v_pk_mul_f32 v[116:117], v[116:117], v[144:145] op_sel_hi:[1,0]
	v_pk_mul_f32 v[118:119], v[118:119], v[144:145] op_sel_hi:[1,0]
	v_pk_mul_f32 v[112:113], v[112:113], v[144:145] op_sel_hi:[1,0]
	v_pk_mul_f32 v[114:115], v[114:115], v[144:145] op_sel_hi:[1,0]
	v_cndmask_b32_e64 v192, 16, 0, vcc
	v_lshlrev_b64 v[148:149], 12, v[130:131]
	v_lshl_add_u64 v[130:131], v[146:147], 0, v[138:139]
	v_mov_b32_e32 v144, v145
	v_lshl_add_u64 v[130:131], v[130:131], 0, v[192:193]
	v_pk_mul_f32 v[150:151], v[206:207], v[144:145] op_sel_hi:[1,0]
	v_pk_mul_f32 v[152:153], v[180:181], v[144:145] op_sel_hi:[1,0]
	v_pk_mul_f32 v[154:155], v[208:209], v[144:145] op_sel_hi:[1,0]
	v_pk_mul_f32 v[156:157], v[182:183], v[144:145] op_sel_hi:[1,0]
	v_add_co_u32_e64 v146, s[2:3], s76, v130
	s_waitcnt vmcnt(3)
	v_pk_mul_f32 v[126:127], v[14:15], v[126:127]
	v_pk_mul_f32 v[124:125], v[12:13], v[124:125]
	s_waitcnt vmcnt(2)
	v_pk_mul_f32 v[122:123], v[10:11], v[122:123]
	v_pk_mul_f32 v[120:121], v[8:9], v[120:121]
	s_waitcnt vmcnt(1)
	v_pk_mul_f32 v[158:159], v[6:7], v[118:119]
	v_pk_mul_f32 v[160:161], v[4:5], v[116:117]
	s_waitcnt vmcnt(0)
	v_pk_mul_f32 v[162:163], v[2:3], v[114:115]
	v_pk_mul_f32 v[164:165], v[0:1], v[112:113]
	v_cndmask_b32_e32 v112, v127, v123, vcc
	v_cndmask_b32_e32 v113, v126, v122, vcc
	v_cndmask_b32_e32 v114, v125, v121, vcc
	v_cndmask_b32_e32 v115, v124, v120, vcc
	v_cndmask_b32_e32 v116, v159, v163, vcc
	v_cndmask_b32_e32 v117, v158, v162, vcc
	v_cndmask_b32_e32 v118, v161, v165, vcc
	v_cndmask_b32_e32 v119, v160, v164, vcc
	v_mov_b32_dpp v141, v115 row_ror:8 row_mask:0xf bank_mask:0xf bound_ctrl:1
	v_mov_b32_dpp v143, v114 row_ror:8 row_mask:0xf bank_mask:0xf bound_ctrl:1
	v_mov_b32_dpp v145, v113 row_ror:8 row_mask:0xf bank_mask:0xf bound_ctrl:1
	v_mov_b32_dpp v166, v112 row_ror:8 row_mask:0xf bank_mask:0xf bound_ctrl:1
	v_pk_mul_f32 v[152:153], v[14:15], v[152:153]
	v_pk_mul_f32 v[156:157], v[10:11], v[156:157]
	v_mov_b32_dpp v167, v119 row_ror:8 row_mask:0xf bank_mask:0xf bound_ctrl:1
	v_mov_b32_dpp v168, v118 row_ror:8 row_mask:0xf bank_mask:0xf bound_ctrl:1
	v_mov_b32_dpp v169, v117 row_ror:8 row_mask:0xf bank_mask:0xf bound_ctrl:1
	v_mov_b32_dpp v170, v116 row_ror:8 row_mask:0xf bank_mask:0xf bound_ctrl:1
	v_cndmask_b32_e32 v115, v166, v127, vcc
	v_cndmask_b32_e32 v114, v145, v126, vcc
	v_cndmask_b32_e32 v113, v143, v125, vcc
	v_cndmask_b32_e32 v112, v141, v124, vcc
	v_addc_co_u32_e64 v147, s[2:3], 0, v131, s[2:3]
	v_pk_mul_f32 v[150:151], v[12:13], v[150:151]
	v_pk_mul_f32 v[154:155], v[8:9], v[154:155]
	v_cndmask_b32_e32 v119, v123, v166, vcc
	v_cndmask_b32_e32 v118, v122, v145, vcc
	v_cndmask_b32_e32 v117, v121, v143, vcc
	v_cndmask_b32_e32 v116, v120, v141, vcc
	v_cndmask_b32_e32 v123, v170, v159, vcc
	v_cndmask_b32_e32 v122, v169, v158, vcc
	v_cndmask_b32_e32 v121, v168, v161, vcc
	v_cndmask_b32_e32 v120, v167, v160, vcc
	v_cndmask_b32_e32 v127, v163, v170, vcc
	v_cndmask_b32_e32 v126, v162, v169, vcc
	v_cndmask_b32_e32 v125, v165, v168, vcc
	v_cndmask_b32_e32 v124, v164, v167, vcc
	global_store_dwordx4 v[130:131], v[112:115], off nt
	global_store_dwordx4 v[146:147], v[116:119], off nt
	global_store_dwordx4 v[130:131], v[120:123], off offset:512 nt
	global_store_dwordx4 v[146:147], v[124:127], off offset:512 nt
	v_cndmask_b32_e32 v112, v153, v157, vcc
	v_cndmask_b32_e32 v113, v152, v156, vcc
	v_cndmask_b32_e32 v114, v151, v155, vcc
	v_cndmask_b32_e32 v115, v150, v154, vcc
	v_mov_b32_dpp v120, v113 row_ror:8 row_mask:0xf bank_mask:0xf bound_ctrl:1
	v_mov_b32_dpp v121, v112 row_ror:8 row_mask:0xf bank_mask:0xf bound_ctrl:1
	v_lshl_add_u64 v[112:113], s[8:9], 0, v[148:149]
	v_mov_b32_dpp v118, v115 row_ror:8 row_mask:0xf bank_mask:0xf bound_ctrl:1
	v_mov_b32_dpp v119, v114 row_ror:8 row_mask:0xf bank_mask:0xf bound_ctrl:1
	v_lshl_add_u64 v[112:113], v[112:113], 0, v[138:139]
	v_lshl_add_u64 v[116:117], v[112:113], 0, v[192:193]
	v_cndmask_b32_e32 v115, v121, v153, vcc
	v_cndmask_b32_e32 v114, v120, v152, vcc
	v_cndmask_b32_e32 v113, v119, v151, vcc
	v_cndmask_b32_e32 v112, v118, v150, vcc
	global_store_dwordx4 v[116:117], v[112:115], off nt
	v_pk_mul_f32 v[100:101], v[100:101], v[144:145] op_sel_hi:[1,0]
	v_pk_mul_f32 v[96:97], v[96:97], v[144:145] op_sel_hi:[1,0]
	v_cndmask_b32_e32 v112, v154, v118, vcc
	v_add_co_u32_e64 v118, s[2:3], s76, v116
	v_cndmask_b32_e32 v115, v157, v121, vcc
	v_cndmask_b32_e32 v114, v156, v120, vcc
	v_cndmask_b32_e32 v113, v155, v119, vcc
	v_addc_co_u32_e64 v119, s[2:3], 0, v117, s[2:3]
	global_store_dwordx4 v[118:119], v[112:115], off nt
	v_pk_mul_f32 v[102:103], v[102:103], v[144:145] op_sel_hi:[1,0]
	v_pk_mul_f32 v[100:101], v[4:5], v[100:101]
	v_pk_mul_f32 v[98:99], v[98:99], v[144:145] op_sel_hi:[1,0]
	v_pk_mul_f32 v[114:115], v[0:1], v[96:97]
	v_pk_mul_f32 v[102:103], v[6:7], v[102:103]
	v_pk_mul_f32 v[112:113], v[2:3], v[98:99]
	v_cndmask_b32_e32 v98, v101, v115, vcc
	v_cndmask_b32_e32 v99, v100, v114, vcc
	v_cndmask_b32_e32 v96, v103, v113, vcc
	v_cndmask_b32_e32 v97, v102, v112, vcc
	v_mov_b32_dpp v120, v99 row_ror:8 row_mask:0xf bank_mask:0xf bound_ctrl:1
	v_mov_b32_dpp v121, v98 row_ror:8 row_mask:0xf bank_mask:0xf bound_ctrl:1
	v_mov_b32_dpp v122, v97 row_ror:8 row_mask:0xf bank_mask:0xf bound_ctrl:1
	v_mov_b32_dpp v123, v96 row_ror:8 row_mask:0xf bank_mask:0xf bound_ctrl:1
	v_cndmask_b32_e32 v97, v121, v101, vcc
	v_cndmask_b32_e32 v96, v120, v100, vcc
	ds_read2_b32 v[100:101], v142 offset0:32 offset1:48
	v_cndmask_b32_e32 v99, v123, v103, vcc
	v_cndmask_b32_e32 v98, v122, v102, vcc
	global_store_dwordx4 v[116:117], v[96:99], off offset:512 nt
	s_waitcnt lgkmcnt(0)
	v_pk_mul_f32 v[94:95], v[94:95], v[100:101] op_sel_hi:[1,0]
	v_cndmask_b32_e32 v99, v113, v123, vcc
	v_cndmask_b32_e32 v98, v112, v122, vcc
	v_cndmask_b32_e32 v97, v115, v121, vcc
	v_cndmask_b32_e32 v96, v114, v120, vcc
	global_store_dwordx4 v[118:119], v[96:99], off offset:512 nt
	v_pk_mul_f32 v[90:91], v[90:91], v[100:101] op_sel_hi:[1,0]
	v_pk_mul_f32 v[94:95], v[14:15], v[94:95]
	v_or_b32_e32 v96, 32, v140
	v_ashrrev_i32_e32 v97, 31, v96
	v_pk_mul_f32 v[88:89], v[88:89], v[100:101] op_sel_hi:[1,0]
	v_pk_mul_f32 v[98:99], v[10:11], v[90:91]
	v_lshlrev_b64 v[96:97], 12, v[96:97]
	v_pk_mul_f32 v[92:93], v[92:93], v[100:101] op_sel_hi:[1,0]
	v_pk_mul_f32 v[102:103], v[8:9], v[88:89]
	v_cndmask_b32_e32 v88, v95, v99, vcc
	v_cndmask_b32_e32 v89, v94, v98, vcc
	v_pk_mul_f32 v[92:93], v[12:13], v[92:93]
	v_mov_b32_dpp v115, v88 row_ror:8 row_mask:0xf bank_mask:0xf bound_ctrl:1
	v_mov_b32_dpp v114, v89 row_ror:8 row_mask:0xf bank_mask:0xf bound_ctrl:1
	v_lshl_add_u64 v[88:89], s[8:9], 0, v[96:97]
	v_cndmask_b32_e32 v90, v93, v103, vcc
	v_cndmask_b32_e32 v91, v92, v102, vcc
	v_lshl_add_u64 v[88:89], v[88:89], 0, v[138:139]
	v_mov_b32_dpp v113, v90 row_ror:8 row_mask:0xf bank_mask:0xf bound_ctrl:1
	v_mov_b32_dpp v112, v91 row_ror:8 row_mask:0xf bank_mask:0xf bound_ctrl:1
	v_lshl_add_u64 v[96:97], v[88:89], 0, v[192:193]
	v_cndmask_b32_e32 v91, v115, v95, vcc
	v_cndmask_b32_e32 v90, v114, v94, vcc
	v_cndmask_b32_e32 v89, v113, v93, vcc
	v_cndmask_b32_e32 v88, v112, v92, vcc
	v_add_co_u32_e64 v92, s[2:3], s76, v96
	global_store_dwordx4 v[96:97], v[88:91], off nt
	s_nop 0
	v_addc_co_u32_e64 v93, s[2:3], 0, v97, s[2:3]
	v_cndmask_b32_e32 v91, v99, v115, vcc
	v_cndmask_b32_e32 v90, v98, v114, vcc
	v_cndmask_b32_e32 v89, v103, v113, vcc
	v_cndmask_b32_e32 v88, v102, v112, vcc
	v_pk_mul_f32 v[84:85], v[84:85], v[100:101] op_sel_hi:[1,0]
	v_pk_mul_f32 v[86:87], v[86:87], v[100:101] op_sel_hi:[1,0]
	v_pk_mul_f32 v[80:81], v[80:81], v[100:101] op_sel_hi:[1,0]
	v_pk_mul_f32 v[82:83], v[82:83], v[100:101] op_sel_hi:[1,0]
	global_store_dwordx4 v[92:93], v[88:91], off nt
	v_pk_mul_f32 v[86:87], v[6:7], v[86:87]
	v_pk_mul_f32 v[84:85], v[4:5], v[84:85]
	v_pk_mul_f32 v[88:89], v[2:3], v[82:83]
	v_pk_mul_f32 v[90:91], v[0:1], v[80:81]
	v_cndmask_b32_e32 v80, v87, v89, vcc
	v_cndmask_b32_e32 v81, v86, v88, vcc
	v_cndmask_b32_e32 v82, v85, v91, vcc
	v_cndmask_b32_e32 v83, v84, v90, vcc
	v_mov_b32_dpp v98, v81 row_ror:8 row_mask:0xf bank_mask:0xf bound_ctrl:1
	v_mov_b32_dpp v95, v82 row_ror:8 row_mask:0xf bank_mask:0xf bound_ctrl:1
	v_mov_b32_dpp v94, v83 row_ror:8 row_mask:0xf bank_mask:0xf bound_ctrl:1
	v_mov_b32_dpp v99, v80 row_ror:8 row_mask:0xf bank_mask:0xf bound_ctrl:1
	v_cndmask_b32_e32 v83, v99, v87, vcc
	v_cndmask_b32_e32 v82, v98, v86, vcc
	v_cndmask_b32_e32 v81, v95, v85, vcc
	v_cndmask_b32_e32 v80, v94, v84, vcc
	global_store_dwordx4 v[96:97], v[80:83], off offset:512 nt
	s_nop 1
	v_cndmask_b32_e32 v83, v89, v99, vcc
	v_cndmask_b32_e32 v82, v88, v98, vcc
	v_cndmask_b32_e32 v81, v91, v95, vcc
	v_cndmask_b32_e32 v80, v90, v94, vcc
	global_store_dwordx4 v[92:93], v[80:83], off offset:512 nt
	s_nop 1
	v_mov_b32_e32 v82, v101
	v_or_b32_e32 v80, 48, v140
	v_pk_mul_f32 v[78:79], v[78:79], v[82:83] op_sel_hi:[1,0]
	v_pk_mul_f32 v[74:75], v[74:75], v[82:83] op_sel_hi:[1,0]
	v_ashrrev_i32_e32 v81, 31, v80
	v_pk_mul_f32 v[78:79], v[14:15], v[78:79]
	v_pk_mul_f32 v[72:73], v[72:73], v[82:83] op_sel_hi:[1,0]
	v_pk_mul_f32 v[84:85], v[10:11], v[74:75]
	v_lshlrev_b64 v[80:81], 12, v[80:81]
	v_pk_mul_f32 v[76:77], v[76:77], v[82:83] op_sel_hi:[1,0]
	v_pk_mul_f32 v[86:87], v[8:9], v[72:73]
	v_cndmask_b32_e32 v72, v79, v85, vcc
	v_cndmask_b32_e32 v73, v78, v84, vcc
	v_pk_mul_f32 v[76:77], v[12:13], v[76:77]
	v_mov_b32_dpp v90, v72 row_ror:8 row_mask:0xf bank_mask:0xf bound_ctrl:1
	v_mov_b32_dpp v89, v73 row_ror:8 row_mask:0xf bank_mask:0xf bound_ctrl:1
	v_lshl_add_u64 v[72:73], s[8:9], 0, v[80:81]
	v_cndmask_b32_e32 v74, v77, v87, vcc
	v_cndmask_b32_e32 v75, v76, v86, vcc
	v_lshl_add_u64 v[72:73], v[72:73], 0, v[138:139]
	v_mov_b32_dpp v88, v74 row_ror:8 row_mask:0xf bank_mask:0xf bound_ctrl:1
	v_mov_b32_dpp v83, v75 row_ror:8 row_mask:0xf bank_mask:0xf bound_ctrl:1
	v_lshl_add_u64 v[80:81], v[72:73], 0, v[192:193]
	v_cndmask_b32_e32 v75, v90, v79, vcc
	v_cndmask_b32_e32 v74, v89, v78, vcc
	v_cndmask_b32_e32 v73, v88, v77, vcc
	v_cndmask_b32_e32 v72, v83, v76, vcc
	v_add_co_u32_e64 v76, s[2:3], s76, v80
	global_store_dwordx4 v[80:81], v[72:75], off nt
	s_nop 0
	v_addc_co_u32_e64 v77, s[2:3], 0, v81, s[2:3]
	v_cndmask_b32_e32 v75, v85, v90, vcc
	v_cndmask_b32_e32 v74, v84, v89, vcc
	v_cndmask_b32_e32 v73, v87, v88, vcc
	v_cndmask_b32_e32 v72, v86, v83, vcc
	v_pk_mul_f32 v[68:69], v[68:69], v[82:83] op_sel_hi:[1,0]
	v_pk_mul_f32 v[64:65], v[64:65], v[82:83] op_sel_hi:[1,0]
	global_store_dwordx4 v[76:77], v[72:75], off nt
	v_pk_mul_f32 v[70:71], v[70:71], v[82:83] op_sel_hi:[1,0]
	v_pk_mul_f32 v[68:69], v[4:5], v[68:69]
	v_pk_mul_f32 v[66:67], v[66:67], v[82:83] op_sel_hi:[1,0]
	v_pk_mul_f32 v[74:75], v[0:1], v[64:65]
	v_pk_mul_f32 v[70:71], v[6:7], v[70:71]
	v_pk_mul_f32 v[72:73], v[2:3], v[66:67]
	v_cndmask_b32_e32 v66, v69, v75, vcc
	v_cndmask_b32_e32 v67, v68, v74, vcc
	v_cndmask_b32_e32 v64, v71, v73, vcc
	v_cndmask_b32_e32 v65, v70, v72, vcc
	v_mov_b32_dpp v78, v67 row_ror:8 row_mask:0xf bank_mask:0xf bound_ctrl:1
	v_mov_b32_dpp v79, v66 row_ror:8 row_mask:0xf bank_mask:0xf bound_ctrl:1
	v_mov_b32_dpp v82, v65 row_ror:8 row_mask:0xf bank_mask:0xf bound_ctrl:1
	v_mov_b32_dpp v83, v64 row_ror:8 row_mask:0xf bank_mask:0xf bound_ctrl:1
	v_cndmask_b32_e32 v65, v79, v69, vcc
	v_cndmask_b32_e32 v64, v78, v68, vcc
	ds_read2_b32 v[68:69], v142 offset0:128 offset1:144
	v_cndmask_b32_e32 v67, v83, v71, vcc
	v_cndmask_b32_e32 v66, v82, v70, vcc
	global_store_dwordx4 v[80:81], v[64:67], off offset:512 nt
	v_lshl_add_u64 v[70:71], v[130:131], 0, s[36:37]
	s_waitcnt lgkmcnt(0)
	v_pk_mul_f32 v[60:61], v[60:61], v[68:69] op_sel_hi:[1,0]
	v_cndmask_b32_e32 v67, v73, v83, vcc
	v_cndmask_b32_e32 v66, v72, v82, vcc
	v_cndmask_b32_e32 v65, v75, v79, vcc
	v_cndmask_b32_e32 v64, v74, v78, vcc
	v_pk_mul_f32 v[56:57], v[56:57], v[68:69] op_sel_hi:[1,0]
	global_store_dwordx4 v[76:77], v[64:67], off offset:512 nt
	v_pk_mul_f32 v[62:63], v[62:63], v[68:69] op_sel_hi:[1,0]
	v_pk_mul_f32 v[60:61], v[12:13], v[60:61]
	v_pk_mul_f32 v[58:59], v[58:59], v[68:69] op_sel_hi:[1,0]
	v_pk_mul_f32 v[66:67], v[8:9], v[56:57]
	v_pk_mul_f32 v[62:63], v[14:15], v[62:63]
	v_pk_mul_f32 v[64:65], v[10:11], v[58:59]
	v_cndmask_b32_e32 v59, v60, v66, vcc
	v_cndmask_b32_e32 v56, v63, v65, vcc
	v_cndmask_b32_e32 v57, v62, v64, vcc
	v_cndmask_b32_e32 v58, v61, v67, vcc
	v_mov_b32_dpp v72, v59 row_ror:8 row_mask:0xf bank_mask:0xf bound_ctrl:1
	v_mov_b32_dpp v74, v57 row_ror:8 row_mask:0xf bank_mask:0xf bound_ctrl:1
	v_mov_b32_dpp v73, v58 row_ror:8 row_mask:0xf bank_mask:0xf bound_ctrl:1
	v_mov_b32_dpp v75, v56 row_ror:8 row_mask:0xf bank_mask:0xf bound_ctrl:1
	v_cndmask_b32_e32 v56, v72, v60, vcc
	v_add_co_u32_e64 v60, s[2:3], s89, v130
	v_cndmask_b32_e32 v59, v75, v63, vcc
	v_cndmask_b32_e32 v58, v74, v62, vcc
	v_cndmask_b32_e32 v57, v73, v61, vcc
	v_addc_co_u32_e64 v61, s[2:3], 0, v131, s[2:3]
	global_store_dwordx4 v[60:61], v[56:59], off nt
	v_add_co_u32_e64 v60, s[2:3], s91, v130
	s_nop 0
	v_cndmask_b32_e32 v59, v65, v75, vcc
	v_cndmask_b32_e32 v58, v64, v74, vcc
	v_cndmask_b32_e32 v57, v67, v73, vcc
	v_cndmask_b32_e32 v56, v66, v72, vcc
	v_addc_co_u32_e64 v61, s[2:3], 0, v131, s[2:3]
	v_pk_mul_f32 v[52:53], v[52:53], v[68:69] op_sel_hi:[1,0]
	v_pk_mul_f32 v[54:55], v[54:55], v[68:69] op_sel_hi:[1,0]
	v_pk_mul_f32 v[48:49], v[48:49], v[68:69] op_sel_hi:[1,0]
	v_pk_mul_f32 v[50:51], v[50:51], v[68:69] op_sel_hi:[1,0]
	global_store_dwordx4 v[60:61], v[56:59], off nt
	v_pk_mul_f32 v[54:55], v[6:7], v[54:55]
	v_pk_mul_f32 v[52:53], v[4:5], v[52:53]
	v_pk_mul_f32 v[56:57], v[2:3], v[50:51]
	v_pk_mul_f32 v[58:59], v[0:1], v[48:49]
	v_cndmask_b32_e32 v48, v55, v57, vcc
	v_cndmask_b32_e32 v49, v54, v56, vcc
	v_cndmask_b32_e32 v50, v53, v59, vcc
	v_cndmask_b32_e32 v51, v52, v58, vcc
	v_mov_b32_dpp v64, v49 row_ror:8 row_mask:0xf bank_mask:0xf bound_ctrl:1
	v_mov_b32_dpp v63, v50 row_ror:8 row_mask:0xf bank_mask:0xf bound_ctrl:1
	v_mov_b32_dpp v62, v51 row_ror:8 row_mask:0xf bank_mask:0xf bound_ctrl:1
	v_mov_b32_dpp v65, v48 row_ror:8 row_mask:0xf bank_mask:0xf bound_ctrl:1
	v_cndmask_b32_e32 v51, v65, v55, vcc
	v_cndmask_b32_e32 v50, v64, v54, vcc
	v_cndmask_b32_e32 v49, v63, v53, vcc
	v_cndmask_b32_e32 v48, v62, v52, vcc
	global_store_dwordx4 v[70:71], v[48:51], off offset:512 nt
	v_lshl_add_u64 v[54:55], v[130:131], 0, s[38:39]
	s_nop 0
	v_cndmask_b32_e32 v51, v57, v65, vcc
	v_cndmask_b32_e32 v50, v56, v64, vcc
	v_cndmask_b32_e32 v49, v59, v63, vcc
	v_cndmask_b32_e32 v48, v58, v62, vcc
	global_store_dwordx4 v[60:61], v[48:51], off offset:512 nt
	s_nop 1
	v_mov_b32_e32 v48, v69
	v_pk_mul_f32 v[44:45], v[44:45], v[48:49] op_sel_hi:[1,0]
	v_pk_mul_f32 v[40:41], v[40:41], v[48:49] op_sel_hi:[1,0]
	v_pk_mul_f32 v[46:47], v[46:47], v[48:49] op_sel_hi:[1,0]
	v_pk_mul_f32 v[44:45], v[12:13], v[44:45]
	v_pk_mul_f32 v[42:43], v[42:43], v[48:49] op_sel_hi:[1,0]
	v_pk_mul_f32 v[52:53], v[8:9], v[40:41]
	v_pk_mul_f32 v[46:47], v[14:15], v[46:47]
	v_pk_mul_f32 v[50:51], v[10:11], v[42:43]
	v_cndmask_b32_e32 v43, v44, v52, vcc
	v_cndmask_b32_e32 v40, v47, v51, vcc
	v_cndmask_b32_e32 v41, v46, v50, vcc
	v_cndmask_b32_e32 v42, v45, v53, vcc
	v_mov_b32_dpp v49, v43 row_ror:8 row_mask:0xf bank_mask:0xf bound_ctrl:1
	v_mov_b32_dpp v57, v41 row_ror:8 row_mask:0xf bank_mask:0xf bound_ctrl:1
	v_mov_b32_dpp v56, v42 row_ror:8 row_mask:0xf bank_mask:0xf bound_ctrl:1
	v_mov_b32_dpp v58, v40 row_ror:8 row_mask:0xf bank_mask:0xf bound_ctrl:1
	v_cndmask_b32_e32 v40, v49, v44, vcc
	v_add_co_u32_e64 v44, s[2:3], s92, v130
	v_cndmask_b32_e32 v43, v58, v47, vcc
	v_cndmask_b32_e32 v42, v57, v46, vcc
	v_cndmask_b32_e32 v41, v56, v45, vcc
	v_addc_co_u32_e64 v45, s[2:3], 0, v131, s[2:3]
	global_store_dwordx4 v[44:45], v[40:43], off nt
	v_add_co_u32_e64 v44, s[2:3], s93, v130
	s_nop 0
	v_cndmask_b32_e32 v43, v51, v58, vcc
	v_cndmask_b32_e32 v42, v50, v57, vcc
	v_cndmask_b32_e32 v41, v53, v56, vcc
	v_cndmask_b32_e32 v40, v52, v49, vcc
	v_addc_co_u32_e64 v45, s[2:3], 0, v131, s[2:3]
	v_pk_mul_f32 v[36:37], v[36:37], v[48:49] op_sel_hi:[1,0]
	v_pk_mul_f32 v[32:33], v[32:33], v[48:49] op_sel_hi:[1,0]
	global_store_dwordx4 v[44:45], v[40:43], off nt
	v_pk_mul_f32 v[38:39], v[38:39], v[48:49] op_sel_hi:[1,0]
	v_pk_mul_f32 v[36:37], v[4:5], v[36:37]
	v_pk_mul_f32 v[34:35], v[34:35], v[48:49] op_sel_hi:[1,0]
	v_pk_mul_f32 v[42:43], v[0:1], v[32:33]
	v_pk_mul_f32 v[38:39], v[6:7], v[38:39]
	v_pk_mul_f32 v[40:41], v[2:3], v[34:35]
	v_cndmask_b32_e32 v34, v37, v43, vcc
	v_cndmask_b32_e32 v35, v36, v42, vcc
	v_cndmask_b32_e32 v32, v39, v41, vcc
	v_cndmask_b32_e32 v33, v38, v40, vcc
	v_mov_b32_dpp v46, v35 row_ror:8 row_mask:0xf bank_mask:0xf bound_ctrl:1
	v_mov_b32_dpp v47, v34 row_ror:8 row_mask:0xf bank_mask:0xf bound_ctrl:1
	v_mov_b32_dpp v48, v33 row_ror:8 row_mask:0xf bank_mask:0xf bound_ctrl:1
	v_mov_b32_dpp v49, v32 row_ror:8 row_mask:0xf bank_mask:0xf bound_ctrl:1
	v_cndmask_b32_e32 v33, v47, v37, vcc
	v_cndmask_b32_e32 v32, v46, v36, vcc
	ds_read2_b32 v[36:37], v142 offset0:160 offset1:176
	v_cndmask_b32_e32 v35, v49, v39, vcc
	v_cndmask_b32_e32 v34, v48, v38, vcc
	global_store_dwordx4 v[54:55], v[32:35], off offset:512 nt
	s_waitcnt lgkmcnt(0)
	v_pk_mul_f32 v[30:31], v[30:31], v[36:37] op_sel_hi:[1,0]
	v_cndmask_b32_e32 v35, v41, v49, vcc
	v_cndmask_b32_e32 v34, v40, v48, vcc
	v_cndmask_b32_e32 v33, v43, v47, vcc
	v_cndmask_b32_e32 v32, v42, v46, vcc
	global_store_dwordx4 v[44:45], v[32:35], off offset:512 nt
	v_pk_mul_f32 v[26:27], v[26:27], v[36:37] op_sel_hi:[1,0]
	v_pk_mul_f32 v[30:31], v[14:15], v[30:31]
	v_pk_mul_f32 v[32:33], v[104:105], v[36:37] op_sel_hi:[1,0]
	v_pk_mul_f32 v[26:27], v[10:11], v[26:27]
	v_pk_mul_f32 v[34:35], v[12:13], v[32:33]
	v_pk_mul_f32 v[32:33], v[108:109], v[36:37] op_sel_hi:[1,0]
	v_pk_mul_f32 v[20:21], v[20:21], v[36:37] op_sel_hi:[1,0]
	v_pk_mul_f32 v[38:39], v[8:9], v[32:33]
	v_cndmask_b32_e32 v33, v30, v26, vcc
	v_cndmask_b32_e32 v41, v34, v38, vcc
	v_cndmask_b32_e32 v32, v31, v27, vcc
	v_cndmask_b32_e32 v40, v35, v39, vcc
	v_mov_b32_dpp v42, v41 row_ror:8 row_mask:0xf bank_mask:0xf bound_ctrl:1
	v_mov_b32_dpp v44, v33 row_ror:8 row_mask:0xf bank_mask:0xf bound_ctrl:1
	v_mov_b32_dpp v43, v40 row_ror:8 row_mask:0xf bank_mask:0xf bound_ctrl:1
	v_mov_b32_dpp v45, v32 row_ror:8 row_mask:0xf bank_mask:0xf bound_ctrl:1
	v_cndmask_b32_e32 v32, v44, v30, vcc
	v_cndmask_b32_e32 v30, v42, v34, vcc
	v_add_co_u32_e64 v34, s[2:3], s94, v130
	v_cndmask_b32_e32 v33, v45, v31, vcc
	v_cndmask_b32_e32 v31, v43, v35, vcc
	v_addc_co_u32_e64 v35, s[2:3], 0, v131, s[2:3]
	global_store_dwordx4 v[34:35], v[30:33], off nt
	v_pk_mul_f32 v[22:23], v[22:23], v[36:37] op_sel_hi:[1,0]
	v_pk_mul_f32 v[16:17], v[16:17], v[36:37] op_sel_hi:[1,0]
	v_cndmask_b32_e32 v32, v26, v44, vcc
	v_add_co_u32_e64 v26, s[2:3], s95, v130
	v_cndmask_b32_e32 v33, v27, v45, vcc
	v_cndmask_b32_e32 v31, v39, v43, vcc
	v_cndmask_b32_e32 v30, v38, v42, vcc
	v_addc_co_u32_e64 v27, s[2:3], 0, v131, s[2:3]
	v_pk_mul_f32 v[18:19], v[18:19], v[36:37] op_sel_hi:[1,0]
	global_store_dwordx4 v[26:27], v[30:33], off nt
	v_pk_mul_f32 v[22:23], v[6:7], v[22:23]
	v_pk_mul_f32 v[20:21], v[4:5], v[20:21]
	v_pk_mul_f32 v[30:31], v[2:3], v[18:19]
	v_pk_mul_f32 v[32:33], v[0:1], v[16:17]
	v_cndmask_b32_e32 v16, v23, v31, vcc
	v_cndmask_b32_e32 v17, v22, v30, vcc
	v_cndmask_b32_e32 v18, v21, v33, vcc
	v_cndmask_b32_e32 v19, v20, v32, vcc
	v_mov_b32_dpp v36, v17 row_ror:8 row_mask:0xf bank_mask:0xf bound_ctrl:1
	v_mov_b32_dpp v35, v18 row_ror:8 row_mask:0xf bank_mask:0xf bound_ctrl:1
	v_mov_b32_dpp v34, v19 row_ror:8 row_mask:0xf bank_mask:0xf bound_ctrl:1
	v_mov_b32_dpp v38, v16 row_ror:8 row_mask:0xf bank_mask:0xf bound_ctrl:1
	v_lshl_add_u64 v[40:41], v[130:131], 0, s[40:41]
	v_cndmask_b32_e32 v19, v38, v23, vcc
	v_cndmask_b32_e32 v18, v36, v22, vcc
	v_cndmask_b32_e32 v17, v35, v21, vcc
	v_cndmask_b32_e32 v16, v34, v20, vcc
	global_store_dwordx4 v[40:41], v[16:19], off offset:512 nt
	v_lshl_add_u64 v[22:23], v[130:131], 0, s[42:43]
	s_nop 0
	v_cndmask_b32_e32 v19, v31, v38, vcc
	v_cndmask_b32_e32 v18, v30, v36, vcc
	v_cndmask_b32_e32 v17, v33, v35, vcc
	v_cndmask_b32_e32 v16, v32, v34, vcc
	global_store_dwordx4 v[26:27], v[16:19], off offset:512 nt
	s_nop 1
	v_mov_b32_e32 v16, v37
	v_pk_mul_f32 v[18:19], v[134:135], v[16:17] op_sel_hi:[1,0]
	v_pk_mul_f32 v[20:21], v[110:111], v[16:17] op_sel_hi:[1,0]
	v_pk_mul_f32 v[12:13], v[12:13], v[18:19]
	v_pk_mul_f32 v[18:19], v[136:137], v[16:17] op_sel_hi:[1,0]
	v_pk_mul_f32 v[14:15], v[14:15], v[20:21]
	v_pk_mul_f32 v[20:21], v[132:133], v[16:17] op_sel_hi:[1,0]
	v_pk_mul_f32 v[18:19], v[8:9], v[18:19]
	v_pk_mul_f32 v[20:21], v[10:11], v[20:21]
	v_cndmask_b32_e32 v11, v12, v18, vcc
	v_cndmask_b32_e32 v8, v15, v21, vcc
	v_cndmask_b32_e32 v9, v14, v20, vcc
	v_cndmask_b32_e32 v10, v13, v19, vcc
	v_mov_b32_dpp v17, v11 row_ror:8 row_mask:0xf bank_mask:0xf bound_ctrl:1
	v_mov_b32_dpp v27, v9 row_ror:8 row_mask:0xf bank_mask:0xf bound_ctrl:1
	v_mov_b32_dpp v26, v10 row_ror:8 row_mask:0xf bank_mask:0xf bound_ctrl:1
	v_mov_b32_dpp v30, v8 row_ror:8 row_mask:0xf bank_mask:0xf bound_ctrl:1
	v_cndmask_b32_e32 v8, v17, v12, vcc
	v_add_co_u32_e64 v12, s[2:3], s96, v130
	v_cndmask_b32_e32 v11, v30, v15, vcc
	v_cndmask_b32_e32 v10, v27, v14, vcc
	v_cndmask_b32_e32 v9, v26, v13, vcc
	v_addc_co_u32_e64 v13, s[2:3], 0, v131, s[2:3]
	global_store_dwordx4 v[12:13], v[8:11], off nt
	v_add_co_u32_e64 v12, s[2:3], s97, v130
	s_nop 0
	v_cndmask_b32_e32 v11, v21, v30, vcc
	v_cndmask_b32_e32 v10, v20, v27, vcc
	v_cndmask_b32_e32 v9, v19, v26, vcc
	v_cndmask_b32_e32 v8, v18, v17, vcc
	v_addc_co_u32_e64 v13, s[2:3], 0, v131, s[2:3]
	global_store_dwordx4 v[12:13], v[8:11], off nt
	s_nop 1
	v_pk_mul_f32 v[8:9], v[106:107], v[16:17] op_sel_hi:[1,0]
	v_pk_mul_f32 v[10:11], v[24:25], v[16:17] op_sel_hi:[1,0]
	v_pk_mul_f32 v[4:5], v[4:5], v[8:9]
	v_pk_mul_f32 v[6:7], v[6:7], v[10:11]
	v_pk_mul_f32 v[8:9], v[128:129], v[16:17] op_sel_hi:[1,0]
	v_pk_mul_f32 v[10:11], v[28:29], v[16:17] op_sel_hi:[1,0]
	v_pk_mul_f32 v[8:9], v[0:1], v[8:9]
	v_pk_mul_f32 v[10:11], v[2:3], v[10:11]
	v_cndmask_b32_e32 v2, v5, v9, vcc
	v_cndmask_b32_e32 v0, v7, v11, vcc
	v_cndmask_b32_e32 v1, v6, v10, vcc
	v_cndmask_b32_e32 v3, v4, v8, vcc
	v_mov_b32_dpp v15, v2 row_ror:8 row_mask:0xf bank_mask:0xf bound_ctrl:1
	v_mov_b32_dpp v16, v1 row_ror:8 row_mask:0xf bank_mask:0xf bound_ctrl:1
	v_mov_b32_dpp v14, v3 row_ror:8 row_mask:0xf bank_mask:0xf bound_ctrl:1
	v_mov_b32_dpp v17, v0 row_ror:8 row_mask:0xf bank_mask:0xf bound_ctrl:1
	v_cndmask_b32_e32 v3, v17, v7, vcc
	v_cndmask_b32_e32 v2, v16, v6, vcc
	v_cndmask_b32_e32 v1, v15, v5, vcc
	v_cndmask_b32_e32 v0, v14, v4, vcc
	global_store_dwordx4 v[22:23], v[0:3], off offset:512 nt
	s_nop 1
	v_cndmask_b32_e32 v3, v11, v17, vcc
	v_cndmask_b32_e32 v2, v10, v16, vcc
	v_cndmask_b32_e32 v1, v9, v15, vcc
	v_cndmask_b32_e32 v0, v8, v14, vcc
	global_store_dwordx4 v[12:13], v[0:3], off offset:512 nt
	s_waitcnt lgkmcnt(0)
	s_barrier
	s_andn2_b64 vcc, exec, s[0:1]
	s_mov_b64 s[0:1], -1
	s_cbranch_vccnz .LBB0_1043
	s_andn2_b64 vcc, exec, s[14:15]
	s_cbranch_vccnz .LBB0_1042
	s_barrier
	s_branch .LBB0_1042
